# lean f16 v-row sweep (row offsets and weights fetched per block as vectors, raw-buffer row loads), LN2 gamma/beta preloaded per half, P6 epilogue x loads prefetched 8 steps deep
# speedup vs baseline: 1.0233x; 1.0193x over previous
.LBB0_1012:
	v_cndmask_b32_e64 v103, v97, v93, s[0:1]
	v_cndmask_b32_e64 v104, v87, v85, s[0:1]
	v_cndmask_b32_e64 v105, v99, v95, s[0:1]
	v_cndmask_b32_e64 v106, v92, v86, s[0:1]
	v_cndmask_b32_e64 v107, v98, v94, s[0:1]
	v_cndmask_b32_e64 v108, v91, v89, s[0:1]
	v_cndmask_b32_e64 v109, v100, v96, s[0:1]
	v_cndmask_b32_e64 v110, v88, v90, s[0:1]
	s_xor_b64 s[8:9], s[0:1], -1
	s_lshl_b32 s0, s10, 11
	s_add_i32 s0, s26, s0
	v_mbcnt_lo_u32_b32 v150, -1, 0
	v_mbcnt_hi_u32_b32 v150, -1, v150
	v_lshlrev_b32_e32 v115, 4, v150
	v_lshl_add_u32 v111, v150, 2, s0
	v_lshrrev_b32_e32 v151, 7, v103
	v_lshlrev_b32_e32 v151, 10, v151
	ds_write_b32 v111, v151 offset:8192
	v_lshrrev_b32_e32 v152, 7, v107
	v_lshlrev_b32_e32 v152, 10, v152
	ds_write_b32 v111, v152 offset:8448
	v_lshrrev_b32_e32 v151, 7, v104
	v_lshlrev_b32_e32 v151, 10, v151
	ds_write_b32 v111, v151 offset:8704
	v_lshrrev_b32_e32 v152, 7, v108
	v_lshlrev_b32_e32 v152, 10, v152
	ds_write_b32 v111, v152 offset:8960
	v_lshrrev_b32_e32 v151, 7, v105
	v_lshlrev_b32_e32 v151, 10, v151
	ds_write_b32 v111, v151 offset:9216
	v_lshrrev_b32_e32 v152, 7, v109
	v_lshlrev_b32_e32 v152, 10, v152
	ds_write_b32 v111, v152 offset:9472
	v_lshrrev_b32_e32 v151, 7, v106
	v_lshlrev_b32_e32 v151, 10, v151
	ds_write_b32 v111, v151 offset:9728
	v_lshrrev_b32_e32 v152, 7, v110
	v_lshlrev_b32_e32 v152, 10, v152
	ds_write_b32 v111, v152 offset:9984
	s_add_u32 s12, s72, 0x4300000
	s_addc_u32 s13, s73, 0
	s_and_b32 s13, s13, 0xffff
	s_mov_b32 s14, 0x1000000
	s_mov_b32 s15, 0x20000
	v_mov_b32_e32 v139, 0
	v_mov_b32_e32 v138, 0
	v_mov_b32_e32 v136, 0
	v_mov_b32_e32 v135, 0
	v_mov_b32_e32 v134, 0
	v_mov_b32_e32 v133, 0
	v_mov_b32_e32 v132, 0
	v_mov_b32_e32 v131, 0
	v_mov_b32_e32 v130, 0
	v_mov_b32_e32 v129, 0
	v_mov_b32_e32 v128, 0
	v_mov_b32_e32 v127, 0
	v_mov_b32_e32 v126, 0
	v_mov_b32_e32 v114, 0
	v_mov_b32_e32 v140, 0
	v_mov_b32_e32 v137, 0
	v_mov_b32_e32 v124, 0
	v_mov_b32_e32 v123, 0
	v_mov_b32_e32 v121, 0
	v_mov_b32_e32 v120, 0
	v_mov_b32_e32 v119, 0
	v_mov_b32_e32 v118, 0
	v_mov_b32_e32 v117, 0
	v_mov_b32_e32 v116, 0
	v_mov_b32_e32 v113, 0
	v_mov_b32_e32 v112, 0
	v_mov_b32_e32 v67, 0
	v_mov_b32_e32 v66, 0
	v_mov_b32_e32 v65, 0
	v_mov_b32_e32 v64, 0
	v_mov_b32_e32 v125, 0
	v_mov_b32_e32 v122, 0
	v_mov_b32_e32 v74, 0
	v_mov_b32_e32 v73, 0
	v_mov_b32_e32 v71, 0
	v_mov_b32_e32 v70, 0
	v_mov_b32_e32 v69, 0
	v_mov_b32_e32 v68, 0
	v_mov_b32_e32 v63, 0
	v_mov_b32_e32 v62, 0
	v_mov_b32_e32 v61, 0
	v_mov_b32_e32 v60, 0
	v_mov_b32_e32 v59, 0
	v_mov_b32_e32 v58, 0
	v_mov_b32_e32 v57, 0
	v_mov_b32_e32 v56, 0
	v_mov_b32_e32 v75, 0
	v_mov_b32_e32 v72, 0
	v_mov_b32_e32 v162, 0
	v_mov_b32_e32 v161, 0
	v_mov_b32_e32 v160, 0
	v_mov_b32_e32 v159, 0
	v_mov_b32_e32 v158, 0
	v_mov_b32_e32 v157, 0
	v_mov_b32_e32 v156, 0
	v_mov_b32_e32 v147, 0
	v_mov_b32_e32 v146, 0
	v_mov_b32_e32 v145, 0
	v_mov_b32_e32 v144, 0
	v_mov_b32_e32 v143, 0
	v_mov_b32_e32 v142, 0
	v_mov_b32_e32 v141, 0
	v_mov_b32_e32 v149, 0
	v_mov_b32_e32 v148, 0
	s_waitcnt lgkmcnt(0)
	ds_read_b32 v48, v111 offset:8192
	ds_read_b32 v49, v111 offset:8704
	ds_read_b32 v50, v111 offset:9216
	ds_read_b32 v51, v111 offset:9728
	ds_read_b32 v52, v111 offset:0
	ds_read_b32 v53, v111 offset:512
	ds_read_b32 v54, v111 offset:1024
	ds_read_b32 v55, v111 offset:1536
	s_waitcnt lgkmcnt(0)
	v_readlane_b32 s4, v48, 0
	s_nop 4
	buffer_load_dwordx4 v[0:3], v115, s[12:15], s4 offen
	v_readlane_b32 s4, v49, 0
	s_nop 4
	buffer_load_dwordx4 v[4:7], v115, s[12:15], s4 offen
	v_readlane_b32 s4, v50, 0
	s_nop 4
	buffer_load_dwordx4 v[8:11], v115, s[12:15], s4 offen
	v_readlane_b32 s4, v51, 0
	s_nop 4
	buffer_load_dwordx4 v[12:15], v115, s[12:15], s4 offen
	v_readlane_b32 s4, v48, 1
	s_nop 4
	buffer_load_dwordx4 v[16:19], v115, s[12:15], s4 offen
	v_readlane_b32 s4, v49, 1
	s_nop 4
	buffer_load_dwordx4 v[20:23], v115, s[12:15], s4 offen
	v_readlane_b32 s4, v50, 1
	s_nop 4
	buffer_load_dwordx4 v[24:27], v115, s[12:15], s4 offen
	s_mov_b32 s11, 0
	s_branch .Lmy_lrow0
.Lmy_lblk:
	ds_read_b32 v48, v111 offset:8192
	ds_read_b32 v49, v111 offset:8704
	ds_read_b32 v50, v111 offset:9216
	ds_read_b32 v51, v111 offset:9728
	ds_read_b32 v52, v111 offset:0
	ds_read_b32 v53, v111 offset:512
	ds_read_b32 v54, v111 offset:1024
	ds_read_b32 v55, v111 offset:1536
	s_waitcnt lgkmcnt(0)
.Lmy_lrow0:
	s_waitcnt vmcnt(6)
	v_readlane_b32 s4, v51, 1
	v_readlane_b32 s0, v52, 0
	v_cvt_scalef32_pk_f16_fp4 v32, v0, 1.0
	v_cvt_scalef32_pk_f16_fp4 v33, v0, 1.0 op_sel:[1,0,0]
	v_cvt_scalef32_pk_f16_fp4 v34, v0, 1.0 op_sel:[0,1,0]
	v_cvt_scalef32_pk_f16_fp4 v35, v0, 1.0 op_sel:[1,1,0]
	v_cvt_scalef32_pk_f16_fp4 v36, v1, 1.0
	v_cvt_scalef32_pk_f16_fp4 v37, v1, 1.0 op_sel:[1,0,0]
	v_cvt_scalef32_pk_f16_fp4 v38, v1, 1.0 op_sel:[0,1,0]
	v_cvt_scalef32_pk_f16_fp4 v39, v1, 1.0 op_sel:[1,1,0]
	v_cvt_scalef32_pk_f16_fp4 v40, v2, 1.0
	v_cvt_scalef32_pk_f16_fp4 v41, v2, 1.0 op_sel:[1,0,0]
	v_cvt_scalef32_pk_f16_fp4 v42, v2, 1.0 op_sel:[0,1,0]
	v_cvt_scalef32_pk_f16_fp4 v43, v2, 1.0 op_sel:[1,1,0]
	v_cvt_scalef32_pk_f16_fp4 v44, v3, 1.0
	v_cvt_scalef32_pk_f16_fp4 v45, v3, 1.0 op_sel:[1,0,0]
	v_cvt_scalef32_pk_f16_fp4 v46, v3, 1.0 op_sel:[0,1,0]
	v_cvt_scalef32_pk_f16_fp4 v47, v3, 1.0 op_sel:[1,1,0]
	buffer_load_dwordx4 v[28:31], v115, s[12:15], s4 offen
	v_pk_fma_f16 v139, v32, s0, v139
	v_pk_fma_f16 v138, v33, s0, v138
	v_pk_fma_f16 v136, v34, s0, v136
	v_pk_fma_f16 v135, v35, s0, v135
	v_pk_fma_f16 v134, v36, s0, v134
	v_pk_fma_f16 v133, v37, s0, v133
	v_pk_fma_f16 v132, v38, s0, v132
	v_pk_fma_f16 v131, v39, s0, v131
	v_pk_fma_f16 v130, v40, s0, v130
	v_pk_fma_f16 v129, v41, s0, v129
	v_pk_fma_f16 v128, v42, s0, v128
	v_pk_fma_f16 v127, v43, s0, v127
	v_pk_fma_f16 v126, v44, s0, v126
	v_pk_fma_f16 v114, v45, s0, v114
	v_pk_fma_f16 v140, v46, s0, v140
	v_pk_fma_f16 v137, v47, s0, v137
	s_waitcnt vmcnt(6)
	v_readlane_b32 s4, v48, 2
	v_readlane_b32 s0, v53, 0
	v_cvt_scalef32_pk_f16_fp4 v32, v4, 1.0
	v_cvt_scalef32_pk_f16_fp4 v33, v4, 1.0 op_sel:[1,0,0]
	v_cvt_scalef32_pk_f16_fp4 v34, v4, 1.0 op_sel:[0,1,0]
	v_cvt_scalef32_pk_f16_fp4 v35, v4, 1.0 op_sel:[1,1,0]
	v_cvt_scalef32_pk_f16_fp4 v36, v5, 1.0
	v_cvt_scalef32_pk_f16_fp4 v37, v5, 1.0 op_sel:[1,0,0]
	v_cvt_scalef32_pk_f16_fp4 v38, v5, 1.0 op_sel:[0,1,0]
	v_cvt_scalef32_pk_f16_fp4 v39, v5, 1.0 op_sel:[1,1,0]
	v_cvt_scalef32_pk_f16_fp4 v40, v6, 1.0
	v_cvt_scalef32_pk_f16_fp4 v41, v6, 1.0 op_sel:[1,0,0]
	v_cvt_scalef32_pk_f16_fp4 v42, v6, 1.0 op_sel:[0,1,0]
	v_cvt_scalef32_pk_f16_fp4 v43, v6, 1.0 op_sel:[1,1,0]
	v_cvt_scalef32_pk_f16_fp4 v44, v7, 1.0
	v_cvt_scalef32_pk_f16_fp4 v45, v7, 1.0 op_sel:[1,0,0]
	v_cvt_scalef32_pk_f16_fp4 v46, v7, 1.0 op_sel:[0,1,0]
	v_cvt_scalef32_pk_f16_fp4 v47, v7, 1.0 op_sel:[1,1,0]
	buffer_load_dwordx4 v[0:3], v115, s[12:15], s4 offen
	v_pk_fma_f16 v124, v32, s0, v124
	v_pk_fma_f16 v123, v33, s0, v123
	v_pk_fma_f16 v121, v34, s0, v121
	v_pk_fma_f16 v120, v35, s0, v120
	v_pk_fma_f16 v119, v36, s0, v119
	v_pk_fma_f16 v118, v37, s0, v118
	v_pk_fma_f16 v117, v38, s0, v117
	v_pk_fma_f16 v116, v39, s0, v116
	v_pk_fma_f16 v113, v40, s0, v113
	v_pk_fma_f16 v112, v41, s0, v112
	v_pk_fma_f16 v67, v42, s0, v67
	v_pk_fma_f16 v66, v43, s0, v66
	v_pk_fma_f16 v65, v44, s0, v65
	v_pk_fma_f16 v64, v45, s0, v64
	v_pk_fma_f16 v125, v46, s0, v125
	v_pk_fma_f16 v122, v47, s0, v122
	s_waitcnt vmcnt(6)
	v_readlane_b32 s4, v49, 2
	v_readlane_b32 s0, v54, 0
	v_cvt_scalef32_pk_f16_fp4 v32, v8, 1.0
	v_cvt_scalef32_pk_f16_fp4 v33, v8, 1.0 op_sel:[1,0,0]
	v_cvt_scalef32_pk_f16_fp4 v34, v8, 1.0 op_sel:[0,1,0]
	v_cvt_scalef32_pk_f16_fp4 v35, v8, 1.0 op_sel:[1,1,0]
	v_cvt_scalef32_pk_f16_fp4 v36, v9, 1.0
	v_cvt_scalef32_pk_f16_fp4 v37, v9, 1.0 op_sel:[1,0,0]
	v_cvt_scalef32_pk_f16_fp4 v38, v9, 1.0 op_sel:[0,1,0]
	v_cvt_scalef32_pk_f16_fp4 v39, v9, 1.0 op_sel:[1,1,0]
	v_cvt_scalef32_pk_f16_fp4 v40, v10, 1.0
	v_cvt_scalef32_pk_f16_fp4 v41, v10, 1.0 op_sel:[1,0,0]
	v_cvt_scalef32_pk_f16_fp4 v42, v10, 1.0 op_sel:[0,1,0]
	v_cvt_scalef32_pk_f16_fp4 v43, v10, 1.0 op_sel:[1,1,0]
	v_cvt_scalef32_pk_f16_fp4 v44, v11, 1.0
	v_cvt_scalef32_pk_f16_fp4 v45, v11, 1.0 op_sel:[1,0,0]
	v_cvt_scalef32_pk_f16_fp4 v46, v11, 1.0 op_sel:[0,1,0]
	v_cvt_scalef32_pk_f16_fp4 v47, v11, 1.0 op_sel:[1,1,0]
	buffer_load_dwordx4 v[4:7], v115, s[12:15], s4 offen
	v_pk_fma_f16 v74, v32, s0, v74
	v_pk_fma_f16 v73, v33, s0, v73
	v_pk_fma_f16 v71, v34, s0, v71
	v_pk_fma_f16 v70, v35, s0, v70
	v_pk_fma_f16 v69, v36, s0, v69
	v_pk_fma_f16 v68, v37, s0, v68
	v_pk_fma_f16 v63, v38, s0, v63
	v_pk_fma_f16 v62, v39, s0, v62
	v_pk_fma_f16 v61, v40, s0, v61
	v_pk_fma_f16 v60, v41, s0, v60
	v_pk_fma_f16 v59, v42, s0, v59
	v_pk_fma_f16 v58, v43, s0, v58
	v_pk_fma_f16 v57, v44, s0, v57
	v_pk_fma_f16 v56, v45, s0, v56
	v_pk_fma_f16 v75, v46, s0, v75
	v_pk_fma_f16 v72, v47, s0, v72
	s_waitcnt vmcnt(6)
	v_readlane_b32 s4, v50, 2
	v_readlane_b32 s0, v55, 0
	v_cvt_scalef32_pk_f16_fp4 v32, v12, 1.0
	v_cvt_scalef32_pk_f16_fp4 v33, v12, 1.0 op_sel:[1,0,0]
	v_cvt_scalef32_pk_f16_fp4 v34, v12, 1.0 op_sel:[0,1,0]
	v_cvt_scalef32_pk_f16_fp4 v35, v12, 1.0 op_sel:[1,1,0]
	v_cvt_scalef32_pk_f16_fp4 v36, v13, 1.0
	v_cvt_scalef32_pk_f16_fp4 v37, v13, 1.0 op_sel:[1,0,0]
	v_cvt_scalef32_pk_f16_fp4 v38, v13, 1.0 op_sel:[0,1,0]
	v_cvt_scalef32_pk_f16_fp4 v39, v13, 1.0 op_sel:[1,1,0]
	v_cvt_scalef32_pk_f16_fp4 v40, v14, 1.0
	v_cvt_scalef32_pk_f16_fp4 v41, v14, 1.0 op_sel:[1,0,0]
	v_cvt_scalef32_pk_f16_fp4 v42, v14, 1.0 op_sel:[0,1,0]
	v_cvt_scalef32_pk_f16_fp4 v43, v14, 1.0 op_sel:[1,1,0]
	v_cvt_scalef32_pk_f16_fp4 v44, v15, 1.0
	v_cvt_scalef32_pk_f16_fp4 v45, v15, 1.0 op_sel:[1,0,0]
	v_cvt_scalef32_pk_f16_fp4 v46, v15, 1.0 op_sel:[0,1,0]
	v_cvt_scalef32_pk_f16_fp4 v47, v15, 1.0 op_sel:[1,1,0]
	buffer_load_dwordx4 v[8:11], v115, s[12:15], s4 offen
	v_pk_fma_f16 v162, v32, s0, v162
	v_pk_fma_f16 v161, v33, s0, v161
	v_pk_fma_f16 v160, v34, s0, v160
	v_pk_fma_f16 v159, v35, s0, v159
	v_pk_fma_f16 v158, v36, s0, v158
	v_pk_fma_f16 v157, v37, s0, v157
	v_pk_fma_f16 v156, v38, s0, v156
	v_pk_fma_f16 v147, v39, s0, v147
	v_pk_fma_f16 v146, v40, s0, v146
	v_pk_fma_f16 v145, v41, s0, v145
	v_pk_fma_f16 v144, v42, s0, v144
	v_pk_fma_f16 v143, v43, s0, v143
	v_pk_fma_f16 v142, v44, s0, v142
	v_pk_fma_f16 v141, v45, s0, v141
	v_pk_fma_f16 v149, v46, s0, v149
	v_pk_fma_f16 v148, v47, s0, v148
	s_waitcnt vmcnt(6)
	v_readlane_b32 s4, v51, 2
	v_readlane_b32 s0, v52, 1
	v_cvt_scalef32_pk_f16_fp4 v32, v16, 1.0
	v_cvt_scalef32_pk_f16_fp4 v33, v16, 1.0 op_sel:[1,0,0]
	v_cvt_scalef32_pk_f16_fp4 v34, v16, 1.0 op_sel:[0,1,0]
	v_cvt_scalef32_pk_f16_fp4 v35, v16, 1.0 op_sel:[1,1,0]
	v_cvt_scalef32_pk_f16_fp4 v36, v17, 1.0
	v_cvt_scalef32_pk_f16_fp4 v37, v17, 1.0 op_sel:[1,0,0]
	v_cvt_scalef32_pk_f16_fp4 v38, v17, 1.0 op_sel:[0,1,0]
	v_cvt_scalef32_pk_f16_fp4 v39, v17, 1.0 op_sel:[1,1,0]
	v_cvt_scalef32_pk_f16_fp4 v40, v18, 1.0
	v_cvt_scalef32_pk_f16_fp4 v41, v18, 1.0 op_sel:[1,0,0]
	v_cvt_scalef32_pk_f16_fp4 v42, v18, 1.0 op_sel:[0,1,0]
	v_cvt_scalef32_pk_f16_fp4 v43, v18, 1.0 op_sel:[1,1,0]
	v_cvt_scalef32_pk_f16_fp4 v44, v19, 1.0
	v_cvt_scalef32_pk_f16_fp4 v45, v19, 1.0 op_sel:[1,0,0]
	v_cvt_scalef32_pk_f16_fp4 v46, v19, 1.0 op_sel:[0,1,0]
	v_cvt_scalef32_pk_f16_fp4 v47, v19, 1.0 op_sel:[1,1,0]
	buffer_load_dwordx4 v[12:15], v115, s[12:15], s4 offen
	v_pk_fma_f16 v139, v32, s0, v139
	v_pk_fma_f16 v138, v33, s0, v138
	v_pk_fma_f16 v136, v34, s0, v136
	v_pk_fma_f16 v135, v35, s0, v135
	v_pk_fma_f16 v134, v36, s0, v134
	v_pk_fma_f16 v133, v37, s0, v133
	v_pk_fma_f16 v132, v38, s0, v132
	v_pk_fma_f16 v131, v39, s0, v131
	v_pk_fma_f16 v130, v40, s0, v130
	v_pk_fma_f16 v129, v41, s0, v129
	v_pk_fma_f16 v128, v42, s0, v128
	v_pk_fma_f16 v127, v43, s0, v127
	v_pk_fma_f16 v126, v44, s0, v126
	v_pk_fma_f16 v114, v45, s0, v114
	v_pk_fma_f16 v140, v46, s0, v140
	v_pk_fma_f16 v137, v47, s0, v137
	s_waitcnt vmcnt(6)
	v_readlane_b32 s4, v48, 3
	v_readlane_b32 s0, v53, 1
	v_cvt_scalef32_pk_f16_fp4 v32, v20, 1.0
	v_cvt_scalef32_pk_f16_fp4 v33, v20, 1.0 op_sel:[1,0,0]
	v_cvt_scalef32_pk_f16_fp4 v34, v20, 1.0 op_sel:[0,1,0]
	v_cvt_scalef32_pk_f16_fp4 v35, v20, 1.0 op_sel:[1,1,0]
	v_cvt_scalef32_pk_f16_fp4 v36, v21, 1.0
	v_cvt_scalef32_pk_f16_fp4 v37, v21, 1.0 op_sel:[1,0,0]
	v_cvt_scalef32_pk_f16_fp4 v38, v21, 1.0 op_sel:[0,1,0]
	v_cvt_scalef32_pk_f16_fp4 v39, v21, 1.0 op_sel:[1,1,0]
	v_cvt_scalef32_pk_f16_fp4 v40, v22, 1.0
	v_cvt_scalef32_pk_f16_fp4 v41, v22, 1.0 op_sel:[1,0,0]
	v_cvt_scalef32_pk_f16_fp4 v42, v22, 1.0 op_sel:[0,1,0]
	v_cvt_scalef32_pk_f16_fp4 v43, v22, 1.0 op_sel:[1,1,0]
	v_cvt_scalef32_pk_f16_fp4 v44, v23, 1.0
	v_cvt_scalef32_pk_f16_fp4 v45, v23, 1.0 op_sel:[1,0,0]
	v_cvt_scalef32_pk_f16_fp4 v46, v23, 1.0 op_sel:[0,1,0]
	v_cvt_scalef32_pk_f16_fp4 v47, v23, 1.0 op_sel:[1,1,0]
	buffer_load_dwordx4 v[16:19], v115, s[12:15], s4 offen
	v_pk_fma_f16 v124, v32, s0, v124
	v_pk_fma_f16 v123, v33, s0, v123
	v_pk_fma_f16 v121, v34, s0, v121
	v_pk_fma_f16 v120, v35, s0, v120
	v_pk_fma_f16 v119, v36, s0, v119
	v_pk_fma_f16 v118, v37, s0, v118
	v_pk_fma_f16 v117, v38, s0, v117
	v_pk_fma_f16 v116, v39, s0, v116
	v_pk_fma_f16 v113, v40, s0, v113
	v_pk_fma_f16 v112, v41, s0, v112
	v_pk_fma_f16 v67, v42, s0, v67
	v_pk_fma_f16 v66, v43, s0, v66
	v_pk_fma_f16 v65, v44, s0, v65
	v_pk_fma_f16 v64, v45, s0, v64
	v_pk_fma_f16 v125, v46, s0, v125
	v_pk_fma_f16 v122, v47, s0, v122
	s_waitcnt vmcnt(6)
	v_readlane_b32 s4, v49, 3
	v_readlane_b32 s0, v54, 1
	v_cvt_scalef32_pk_f16_fp4 v32, v24, 1.0
	v_cvt_scalef32_pk_f16_fp4 v33, v24, 1.0 op_sel:[1,0,0]
	v_cvt_scalef32_pk_f16_fp4 v34, v24, 1.0 op_sel:[0,1,0]
	v_cvt_scalef32_pk_f16_fp4 v35, v24, 1.0 op_sel:[1,1,0]
	v_cvt_scalef32_pk_f16_fp4 v36, v25, 1.0
	v_cvt_scalef32_pk_f16_fp4 v37, v25, 1.0 op_sel:[1,0,0]
	v_cvt_scalef32_pk_f16_fp4 v38, v25, 1.0 op_sel:[0,1,0]
	v_cvt_scalef32_pk_f16_fp4 v39, v25, 1.0 op_sel:[1,1,0]
	v_cvt_scalef32_pk_f16_fp4 v40, v26, 1.0
	v_cvt_scalef32_pk_f16_fp4 v41, v26, 1.0 op_sel:[1,0,0]
	v_cvt_scalef32_pk_f16_fp4 v42, v26, 1.0 op_sel:[0,1,0]
	v_cvt_scalef32_pk_f16_fp4 v43, v26, 1.0 op_sel:[1,1,0]
	v_cvt_scalef32_pk_f16_fp4 v44, v27, 1.0
	v_cvt_scalef32_pk_f16_fp4 v45, v27, 1.0 op_sel:[1,0,0]
	v_cvt_scalef32_pk_f16_fp4 v46, v27, 1.0 op_sel:[0,1,0]
	v_cvt_scalef32_pk_f16_fp4 v47, v27, 1.0 op_sel:[1,1,0]
	buffer_load_dwordx4 v[20:23], v115, s[12:15], s4 offen
	v_pk_fma_f16 v74, v32, s0, v74
	v_pk_fma_f16 v73, v33, s0, v73
	v_pk_fma_f16 v71, v34, s0, v71
	v_pk_fma_f16 v70, v35, s0, v70
	v_pk_fma_f16 v69, v36, s0, v69
	v_pk_fma_f16 v68, v37, s0, v68
	v_pk_fma_f16 v63, v38, s0, v63
	v_pk_fma_f16 v62, v39, s0, v62
	v_pk_fma_f16 v61, v40, s0, v61
	v_pk_fma_f16 v60, v41, s0, v60
	v_pk_fma_f16 v59, v42, s0, v59
	v_pk_fma_f16 v58, v43, s0, v58
	v_pk_fma_f16 v57, v44, s0, v57
	v_pk_fma_f16 v56, v45, s0, v56
	v_pk_fma_f16 v75, v46, s0, v75
	v_pk_fma_f16 v72, v47, s0, v72
	s_waitcnt vmcnt(6)
	v_readlane_b32 s4, v50, 3
	v_readlane_b32 s0, v55, 1
	v_cvt_scalef32_pk_f16_fp4 v32, v28, 1.0
	v_cvt_scalef32_pk_f16_fp4 v33, v28, 1.0 op_sel:[1,0,0]
	v_cvt_scalef32_pk_f16_fp4 v34, v28, 1.0 op_sel:[0,1,0]
	v_cvt_scalef32_pk_f16_fp4 v35, v28, 1.0 op_sel:[1,1,0]
	v_cvt_scalef32_pk_f16_fp4 v36, v29, 1.0
	v_cvt_scalef32_pk_f16_fp4 v37, v29, 1.0 op_sel:[1,0,0]
	v_cvt_scalef32_pk_f16_fp4 v38, v29, 1.0 op_sel:[0,1,0]
	v_cvt_scalef32_pk_f16_fp4 v39, v29, 1.0 op_sel:[1,1,0]
	v_cvt_scalef32_pk_f16_fp4 v40, v30, 1.0
	v_cvt_scalef32_pk_f16_fp4 v41, v30, 1.0 op_sel:[1,0,0]
	v_cvt_scalef32_pk_f16_fp4 v42, v30, 1.0 op_sel:[0,1,0]
	v_cvt_scalef32_pk_f16_fp4 v43, v30, 1.0 op_sel:[1,1,0]
	v_cvt_scalef32_pk_f16_fp4 v44, v31, 1.0
	v_cvt_scalef32_pk_f16_fp4 v45, v31, 1.0 op_sel:[1,0,0]
	v_cvt_scalef32_pk_f16_fp4 v46, v31, 1.0 op_sel:[0,1,0]
	v_cvt_scalef32_pk_f16_fp4 v47, v31, 1.0 op_sel:[1,1,0]
	buffer_load_dwordx4 v[24:27], v115, s[12:15], s4 offen
	v_pk_fma_f16 v162, v32, s0, v162
	v_pk_fma_f16 v161, v33, s0, v161
	v_pk_fma_f16 v160, v34, s0, v160
	v_pk_fma_f16 v159, v35, s0, v159
	v_pk_fma_f16 v158, v36, s0, v158
	v_pk_fma_f16 v157, v37, s0, v157
	v_pk_fma_f16 v156, v38, s0, v156
	v_pk_fma_f16 v147, v39, s0, v147
	v_pk_fma_f16 v146, v40, s0, v146
	v_pk_fma_f16 v145, v41, s0, v145
	v_pk_fma_f16 v144, v42, s0, v144
	v_pk_fma_f16 v143, v43, s0, v143
	v_pk_fma_f16 v142, v44, s0, v142
	v_pk_fma_f16 v141, v45, s0, v141
	v_pk_fma_f16 v149, v46, s0, v149
	v_pk_fma_f16 v148, v47, s0, v148
	s_waitcnt vmcnt(6)
	v_readlane_b32 s4, v51, 3
	v_readlane_b32 s0, v52, 2
	v_cvt_scalef32_pk_f16_fp4 v32, v0, 1.0
	v_cvt_scalef32_pk_f16_fp4 v33, v0, 1.0 op_sel:[1,0,0]
	v_cvt_scalef32_pk_f16_fp4 v34, v0, 1.0 op_sel:[0,1,0]
	v_cvt_scalef32_pk_f16_fp4 v35, v0, 1.0 op_sel:[1,1,0]
	v_cvt_scalef32_pk_f16_fp4 v36, v1, 1.0
	v_cvt_scalef32_pk_f16_fp4 v37, v1, 1.0 op_sel:[1,0,0]
	v_cvt_scalef32_pk_f16_fp4 v38, v1, 1.0 op_sel:[0,1,0]
	v_cvt_scalef32_pk_f16_fp4 v39, v1, 1.0 op_sel:[1,1,0]
	v_cvt_scalef32_pk_f16_fp4 v40, v2, 1.0
	v_cvt_scalef32_pk_f16_fp4 v41, v2, 1.0 op_sel:[1,0,0]
	v_cvt_scalef32_pk_f16_fp4 v42, v2, 1.0 op_sel:[0,1,0]
	v_cvt_scalef32_pk_f16_fp4 v43, v2, 1.0 op_sel:[1,1,0]
	v_cvt_scalef32_pk_f16_fp4 v44, v3, 1.0
	v_cvt_scalef32_pk_f16_fp4 v45, v3, 1.0 op_sel:[1,0,0]
	v_cvt_scalef32_pk_f16_fp4 v46, v3, 1.0 op_sel:[0,1,0]
	v_cvt_scalef32_pk_f16_fp4 v47, v3, 1.0 op_sel:[1,1,0]
	buffer_load_dwordx4 v[28:31], v115, s[12:15], s4 offen
	v_pk_fma_f16 v139, v32, s0, v139
	v_pk_fma_f16 v138, v33, s0, v138
	v_pk_fma_f16 v136, v34, s0, v136
	v_pk_fma_f16 v135, v35, s0, v135
	v_pk_fma_f16 v134, v36, s0, v134
	v_pk_fma_f16 v133, v37, s0, v133
	v_pk_fma_f16 v132, v38, s0, v132
	v_pk_fma_f16 v131, v39, s0, v131
	v_pk_fma_f16 v130, v40, s0, v130
	v_pk_fma_f16 v129, v41, s0, v129
	v_pk_fma_f16 v128, v42, s0, v128
	v_pk_fma_f16 v127, v43, s0, v127
	v_pk_fma_f16 v126, v44, s0, v126
	v_pk_fma_f16 v114, v45, s0, v114
	v_pk_fma_f16 v140, v46, s0, v140
	v_pk_fma_f16 v137, v47, s0, v137
	s_waitcnt vmcnt(6)
	v_readlane_b32 s4, v48, 4
	v_readlane_b32 s0, v53, 2
	v_cvt_scalef32_pk_f16_fp4 v32, v4, 1.0
	v_cvt_scalef32_pk_f16_fp4 v33, v4, 1.0 op_sel:[1,0,0]
	v_cvt_scalef32_pk_f16_fp4 v34, v4, 1.0 op_sel:[0,1,0]
	v_cvt_scalef32_pk_f16_fp4 v35, v4, 1.0 op_sel:[1,1,0]
	v_cvt_scalef32_pk_f16_fp4 v36, v5, 1.0
	v_cvt_scalef32_pk_f16_fp4 v37, v5, 1.0 op_sel:[1,0,0]
	v_cvt_scalef32_pk_f16_fp4 v38, v5, 1.0 op_sel:[0,1,0]
	v_cvt_scalef32_pk_f16_fp4 v39, v5, 1.0 op_sel:[1,1,0]
	v_cvt_scalef32_pk_f16_fp4 v40, v6, 1.0
	v_cvt_scalef32_pk_f16_fp4 v41, v6, 1.0 op_sel:[1,0,0]
	v_cvt_scalef32_pk_f16_fp4 v42, v6, 1.0 op_sel:[0,1,0]
	v_cvt_scalef32_pk_f16_fp4 v43, v6, 1.0 op_sel:[1,1,0]
	v_cvt_scalef32_pk_f16_fp4 v44, v7, 1.0
	v_cvt_scalef32_pk_f16_fp4 v45, v7, 1.0 op_sel:[1,0,0]
	v_cvt_scalef32_pk_f16_fp4 v46, v7, 1.0 op_sel:[0,1,0]
	v_cvt_scalef32_pk_f16_fp4 v47, v7, 1.0 op_sel:[1,1,0]
	buffer_load_dwordx4 v[0:3], v115, s[12:15], s4 offen
	v_pk_fma_f16 v124, v32, s0, v124
	v_pk_fma_f16 v123, v33, s0, v123
	v_pk_fma_f16 v121, v34, s0, v121
	v_pk_fma_f16 v120, v35, s0, v120
	v_pk_fma_f16 v119, v36, s0, v119
	v_pk_fma_f16 v118, v37, s0, v118
	v_pk_fma_f16 v117, v38, s0, v117
	v_pk_fma_f16 v116, v39, s0, v116
	v_pk_fma_f16 v113, v40, s0, v113
	v_pk_fma_f16 v112, v41, s0, v112
	v_pk_fma_f16 v67, v42, s0, v67
	v_pk_fma_f16 v66, v43, s0, v66
	v_pk_fma_f16 v65, v44, s0, v65
	v_pk_fma_f16 v64, v45, s0, v64
	v_pk_fma_f16 v125, v46, s0, v125
	v_pk_fma_f16 v122, v47, s0, v122
	s_waitcnt vmcnt(6)
	v_readlane_b32 s4, v49, 4
	v_readlane_b32 s0, v54, 2
	v_cvt_scalef32_pk_f16_fp4 v32, v8, 1.0
	v_cvt_scalef32_pk_f16_fp4 v33, v8, 1.0 op_sel:[1,0,0]
	v_cvt_scalef32_pk_f16_fp4 v34, v8, 1.0 op_sel:[0,1,0]
	v_cvt_scalef32_pk_f16_fp4 v35, v8, 1.0 op_sel:[1,1,0]
	v_cvt_scalef32_pk_f16_fp4 v36, v9, 1.0
	v_cvt_scalef32_pk_f16_fp4 v37, v9, 1.0 op_sel:[1,0,0]
	v_cvt_scalef32_pk_f16_fp4 v38, v9, 1.0 op_sel:[0,1,0]
	v_cvt_scalef32_pk_f16_fp4 v39, v9, 1.0 op_sel:[1,1,0]
	v_cvt_scalef32_pk_f16_fp4 v40, v10, 1.0
	v_cvt_scalef32_pk_f16_fp4 v41, v10, 1.0 op_sel:[1,0,0]
	v_cvt_scalef32_pk_f16_fp4 v42, v10, 1.0 op_sel:[0,1,0]
	v_cvt_scalef32_pk_f16_fp4 v43, v10, 1.0 op_sel:[1,1,0]
	v_cvt_scalef32_pk_f16_fp4 v44, v11, 1.0
	v_cvt_scalef32_pk_f16_fp4 v45, v11, 1.0 op_sel:[1,0,0]
	v_cvt_scalef32_pk_f16_fp4 v46, v11, 1.0 op_sel:[0,1,0]
	v_cvt_scalef32_pk_f16_fp4 v47, v11, 1.0 op_sel:[1,1,0]
	buffer_load_dwordx4 v[4:7], v115, s[12:15], s4 offen
	v_pk_fma_f16 v74, v32, s0, v74
	v_pk_fma_f16 v73, v33, s0, v73
	v_pk_fma_f16 v71, v34, s0, v71
	v_pk_fma_f16 v70, v35, s0, v70
	v_pk_fma_f16 v69, v36, s0, v69
	v_pk_fma_f16 v68, v37, s0, v68
	v_pk_fma_f16 v63, v38, s0, v63
	v_pk_fma_f16 v62, v39, s0, v62
	v_pk_fma_f16 v61, v40, s0, v61
	v_pk_fma_f16 v60, v41, s0, v60
	v_pk_fma_f16 v59, v42, s0, v59
	v_pk_fma_f16 v58, v43, s0, v58
	v_pk_fma_f16 v57, v44, s0, v57
	v_pk_fma_f16 v56, v45, s0, v56
	v_pk_fma_f16 v75, v46, s0, v75
	v_pk_fma_f16 v72, v47, s0, v72
	s_waitcnt vmcnt(6)
	v_readlane_b32 s4, v50, 4
	v_readlane_b32 s0, v55, 2
	v_cvt_scalef32_pk_f16_fp4 v32, v12, 1.0
	v_cvt_scalef32_pk_f16_fp4 v33, v12, 1.0 op_sel:[1,0,0]
	v_cvt_scalef32_pk_f16_fp4 v34, v12, 1.0 op_sel:[0,1,0]
	v_cvt_scalef32_pk_f16_fp4 v35, v12, 1.0 op_sel:[1,1,0]
	v_cvt_scalef32_pk_f16_fp4 v36, v13, 1.0
	v_cvt_scalef32_pk_f16_fp4 v37, v13, 1.0 op_sel:[1,0,0]
	v_cvt_scalef32_pk_f16_fp4 v38, v13, 1.0 op_sel:[0,1,0]
	v_cvt_scalef32_pk_f16_fp4 v39, v13, 1.0 op_sel:[1,1,0]
	v_cvt_scalef32_pk_f16_fp4 v40, v14, 1.0
	v_cvt_scalef32_pk_f16_fp4 v41, v14, 1.0 op_sel:[1,0,0]
	v_cvt_scalef32_pk_f16_fp4 v42, v14, 1.0 op_sel:[0,1,0]
	v_cvt_scalef32_pk_f16_fp4 v43, v14, 1.0 op_sel:[1,1,0]
	v_cvt_scalef32_pk_f16_fp4 v44, v15, 1.0
	v_cvt_scalef32_pk_f16_fp4 v45, v15, 1.0 op_sel:[1,0,0]
	v_cvt_scalef32_pk_f16_fp4 v46, v15, 1.0 op_sel:[0,1,0]
	v_cvt_scalef32_pk_f16_fp4 v47, v15, 1.0 op_sel:[1,1,0]
	buffer_load_dwordx4 v[8:11], v115, s[12:15], s4 offen
	v_pk_fma_f16 v162, v32, s0, v162
	v_pk_fma_f16 v161, v33, s0, v161
	v_pk_fma_f16 v160, v34, s0, v160
	v_pk_fma_f16 v159, v35, s0, v159
	v_pk_fma_f16 v158, v36, s0, v158
	v_pk_fma_f16 v157, v37, s0, v157
	v_pk_fma_f16 v156, v38, s0, v156
	v_pk_fma_f16 v147, v39, s0, v147
	v_pk_fma_f16 v146, v40, s0, v146
	v_pk_fma_f16 v145, v41, s0, v145
	v_pk_fma_f16 v144, v42, s0, v144
	v_pk_fma_f16 v143, v43, s0, v143
	v_pk_fma_f16 v142, v44, s0, v142
	v_pk_fma_f16 v141, v45, s0, v141
	v_pk_fma_f16 v149, v46, s0, v149
	v_pk_fma_f16 v148, v47, s0, v148
	s_waitcnt vmcnt(6)
	v_readlane_b32 s4, v51, 4
	v_readlane_b32 s0, v52, 3
	v_cvt_scalef32_pk_f16_fp4 v32, v16, 1.0
	v_cvt_scalef32_pk_f16_fp4 v33, v16, 1.0 op_sel:[1,0,0]
	v_cvt_scalef32_pk_f16_fp4 v34, v16, 1.0 op_sel:[0,1,0]
	v_cvt_scalef32_pk_f16_fp4 v35, v16, 1.0 op_sel:[1,1,0]
	v_cvt_scalef32_pk_f16_fp4 v36, v17, 1.0
	v_cvt_scalef32_pk_f16_fp4 v37, v17, 1.0 op_sel:[1,0,0]
	v_cvt_scalef32_pk_f16_fp4 v38, v17, 1.0 op_sel:[0,1,0]
	v_cvt_scalef32_pk_f16_fp4 v39, v17, 1.0 op_sel:[1,1,0]
	v_cvt_scalef32_pk_f16_fp4 v40, v18, 1.0
	v_cvt_scalef32_pk_f16_fp4 v41, v18, 1.0 op_sel:[1,0,0]
	v_cvt_scalef32_pk_f16_fp4 v42, v18, 1.0 op_sel:[0,1,0]
	v_cvt_scalef32_pk_f16_fp4 v43, v18, 1.0 op_sel:[1,1,0]
	v_cvt_scalef32_pk_f16_fp4 v44, v19, 1.0
	v_cvt_scalef32_pk_f16_fp4 v45, v19, 1.0 op_sel:[1,0,0]
	v_cvt_scalef32_pk_f16_fp4 v46, v19, 1.0 op_sel:[0,1,0]
	v_cvt_scalef32_pk_f16_fp4 v47, v19, 1.0 op_sel:[1,1,0]
	buffer_load_dwordx4 v[12:15], v115, s[12:15], s4 offen
	v_pk_fma_f16 v139, v32, s0, v139
	v_pk_fma_f16 v138, v33, s0, v138
	v_pk_fma_f16 v136, v34, s0, v136
	v_pk_fma_f16 v135, v35, s0, v135
	v_pk_fma_f16 v134, v36, s0, v134
	v_pk_fma_f16 v133, v37, s0, v133
	v_pk_fma_f16 v132, v38, s0, v132
	v_pk_fma_f16 v131, v39, s0, v131
	v_pk_fma_f16 v130, v40, s0, v130
	v_pk_fma_f16 v129, v41, s0, v129
	v_pk_fma_f16 v128, v42, s0, v128
	v_pk_fma_f16 v127, v43, s0, v127
	v_pk_fma_f16 v126, v44, s0, v126
	v_pk_fma_f16 v114, v45, s0, v114
	v_pk_fma_f16 v140, v46, s0, v140
	v_pk_fma_f16 v137, v47, s0, v137
	s_waitcnt vmcnt(6)
	v_readlane_b32 s4, v48, 5
	v_readlane_b32 s0, v53, 3
	v_cvt_scalef32_pk_f16_fp4 v32, v20, 1.0
	v_cvt_scalef32_pk_f16_fp4 v33, v20, 1.0 op_sel:[1,0,0]
	v_cvt_scalef32_pk_f16_fp4 v34, v20, 1.0 op_sel:[0,1,0]
	v_cvt_scalef32_pk_f16_fp4 v35, v20, 1.0 op_sel:[1,1,0]
	v_cvt_scalef32_pk_f16_fp4 v36, v21, 1.0
	v_cvt_scalef32_pk_f16_fp4 v37, v21, 1.0 op_sel:[1,0,0]
	v_cvt_scalef32_pk_f16_fp4 v38, v21, 1.0 op_sel:[0,1,0]
	v_cvt_scalef32_pk_f16_fp4 v39, v21, 1.0 op_sel:[1,1,0]
	v_cvt_scalef32_pk_f16_fp4 v40, v22, 1.0
	v_cvt_scalef32_pk_f16_fp4 v41, v22, 1.0 op_sel:[1,0,0]
	v_cvt_scalef32_pk_f16_fp4 v42, v22, 1.0 op_sel:[0,1,0]
	v_cvt_scalef32_pk_f16_fp4 v43, v22, 1.0 op_sel:[1,1,0]
	v_cvt_scalef32_pk_f16_fp4 v44, v23, 1.0
	v_cvt_scalef32_pk_f16_fp4 v45, v23, 1.0 op_sel:[1,0,0]
	v_cvt_scalef32_pk_f16_fp4 v46, v23, 1.0 op_sel:[0,1,0]
	v_cvt_scalef32_pk_f16_fp4 v47, v23, 1.0 op_sel:[1,1,0]
	buffer_load_dwordx4 v[16:19], v115, s[12:15], s4 offen
	v_pk_fma_f16 v124, v32, s0, v124
	v_pk_fma_f16 v123, v33, s0, v123
	v_pk_fma_f16 v121, v34, s0, v121
	v_pk_fma_f16 v120, v35, s0, v120
	v_pk_fma_f16 v119, v36, s0, v119
	v_pk_fma_f16 v118, v37, s0, v118
	v_pk_fma_f16 v117, v38, s0, v117
	v_pk_fma_f16 v116, v39, s0, v116
	v_pk_fma_f16 v113, v40, s0, v113
	v_pk_fma_f16 v112, v41, s0, v112
	v_pk_fma_f16 v67, v42, s0, v67
	v_pk_fma_f16 v66, v43, s0, v66
	v_pk_fma_f16 v65, v44, s0, v65
	v_pk_fma_f16 v64, v45, s0, v64
	v_pk_fma_f16 v125, v46, s0, v125
	v_pk_fma_f16 v122, v47, s0, v122
	s_waitcnt vmcnt(6)
	v_readlane_b32 s4, v49, 5
	v_readlane_b32 s0, v54, 3
	v_cvt_scalef32_pk_f16_fp4 v32, v24, 1.0
	v_cvt_scalef32_pk_f16_fp4 v33, v24, 1.0 op_sel:[1,0,0]
	v_cvt_scalef32_pk_f16_fp4 v34, v24, 1.0 op_sel:[0,1,0]
	v_cvt_scalef32_pk_f16_fp4 v35, v24, 1.0 op_sel:[1,1,0]
	v_cvt_scalef32_pk_f16_fp4 v36, v25, 1.0
	v_cvt_scalef32_pk_f16_fp4 v37, v25, 1.0 op_sel:[1,0,0]
	v_cvt_scalef32_pk_f16_fp4 v38, v25, 1.0 op_sel:[0,1,0]
	v_cvt_scalef32_pk_f16_fp4 v39, v25, 1.0 op_sel:[1,1,0]
	v_cvt_scalef32_pk_f16_fp4 v40, v26, 1.0
	v_cvt_scalef32_pk_f16_fp4 v41, v26, 1.0 op_sel:[1,0,0]
	v_cvt_scalef32_pk_f16_fp4 v42, v26, 1.0 op_sel:[0,1,0]
	v_cvt_scalef32_pk_f16_fp4 v43, v26, 1.0 op_sel:[1,1,0]
	v_cvt_scalef32_pk_f16_fp4 v44, v27, 1.0
	v_cvt_scalef32_pk_f16_fp4 v45, v27, 1.0 op_sel:[1,0,0]
	v_cvt_scalef32_pk_f16_fp4 v46, v27, 1.0 op_sel:[0,1,0]
	v_cvt_scalef32_pk_f16_fp4 v47, v27, 1.0 op_sel:[1,1,0]
	buffer_load_dwordx4 v[20:23], v115, s[12:15], s4 offen
	v_pk_fma_f16 v74, v32, s0, v74
	v_pk_fma_f16 v73, v33, s0, v73
	v_pk_fma_f16 v71, v34, s0, v71
	v_pk_fma_f16 v70, v35, s0, v70
	v_pk_fma_f16 v69, v36, s0, v69
	v_pk_fma_f16 v68, v37, s0, v68
	v_pk_fma_f16 v63, v38, s0, v63
	v_pk_fma_f16 v62, v39, s0, v62
	v_pk_fma_f16 v61, v40, s0, v61
	v_pk_fma_f16 v60, v41, s0, v60
	v_pk_fma_f16 v59, v42, s0, v59
	v_pk_fma_f16 v58, v43, s0, v58
	v_pk_fma_f16 v57, v44, s0, v57
	v_pk_fma_f16 v56, v45, s0, v56
	v_pk_fma_f16 v75, v46, s0, v75
	v_pk_fma_f16 v72, v47, s0, v72
	s_waitcnt vmcnt(6)
	v_readlane_b32 s4, v50, 5
	v_readlane_b32 s0, v55, 3
	v_cvt_scalef32_pk_f16_fp4 v32, v28, 1.0
	v_cvt_scalef32_pk_f16_fp4 v33, v28, 1.0 op_sel:[1,0,0]
	v_cvt_scalef32_pk_f16_fp4 v34, v28, 1.0 op_sel:[0,1,0]
	v_cvt_scalef32_pk_f16_fp4 v35, v28, 1.0 op_sel:[1,1,0]
	v_cvt_scalef32_pk_f16_fp4 v36, v29, 1.0
	v_cvt_scalef32_pk_f16_fp4 v37, v29, 1.0 op_sel:[1,0,0]
	v_cvt_scalef32_pk_f16_fp4 v38, v29, 1.0 op_sel:[0,1,0]
	v_cvt_scalef32_pk_f16_fp4 v39, v29, 1.0 op_sel:[1,1,0]
	v_cvt_scalef32_pk_f16_fp4 v40, v30, 1.0
	v_cvt_scalef32_pk_f16_fp4 v41, v30, 1.0 op_sel:[1,0,0]
	v_cvt_scalef32_pk_f16_fp4 v42, v30, 1.0 op_sel:[0,1,0]
	v_cvt_scalef32_pk_f16_fp4 v43, v30, 1.0 op_sel:[1,1,0]
	v_cvt_scalef32_pk_f16_fp4 v44, v31, 1.0
	v_cvt_scalef32_pk_f16_fp4 v45, v31, 1.0 op_sel:[1,0,0]
	v_cvt_scalef32_pk_f16_fp4 v46, v31, 1.0 op_sel:[0,1,0]
	v_cvt_scalef32_pk_f16_fp4 v47, v31, 1.0 op_sel:[1,1,0]
	buffer_load_dwordx4 v[24:27], v115, s[12:15], s4 offen
	v_pk_fma_f16 v162, v32, s0, v162
	v_pk_fma_f16 v161, v33, s0, v161
	v_pk_fma_f16 v160, v34, s0, v160
	v_pk_fma_f16 v159, v35, s0, v159
	v_pk_fma_f16 v158, v36, s0, v158
	v_pk_fma_f16 v157, v37, s0, v157
	v_pk_fma_f16 v156, v38, s0, v156
	v_pk_fma_f16 v147, v39, s0, v147
	v_pk_fma_f16 v146, v40, s0, v146
	v_pk_fma_f16 v145, v41, s0, v145
	v_pk_fma_f16 v144, v42, s0, v144
	v_pk_fma_f16 v143, v43, s0, v143
	v_pk_fma_f16 v142, v44, s0, v142
	v_pk_fma_f16 v141, v45, s0, v141
	v_pk_fma_f16 v149, v46, s0, v149
	v_pk_fma_f16 v148, v47, s0, v148
	s_waitcnt vmcnt(6)
	v_readlane_b32 s4, v51, 5
	v_readlane_b32 s0, v52, 4
	v_cvt_scalef32_pk_f16_fp4 v32, v0, 1.0
	v_cvt_scalef32_pk_f16_fp4 v33, v0, 1.0 op_sel:[1,0,0]
	v_cvt_scalef32_pk_f16_fp4 v34, v0, 1.0 op_sel:[0,1,0]
	v_cvt_scalef32_pk_f16_fp4 v35, v0, 1.0 op_sel:[1,1,0]
	v_cvt_scalef32_pk_f16_fp4 v36, v1, 1.0
	v_cvt_scalef32_pk_f16_fp4 v37, v1, 1.0 op_sel:[1,0,0]
	v_cvt_scalef32_pk_f16_fp4 v38, v1, 1.0 op_sel:[0,1,0]
	v_cvt_scalef32_pk_f16_fp4 v39, v1, 1.0 op_sel:[1,1,0]
	v_cvt_scalef32_pk_f16_fp4 v40, v2, 1.0
	v_cvt_scalef32_pk_f16_fp4 v41, v2, 1.0 op_sel:[1,0,0]
	v_cvt_scalef32_pk_f16_fp4 v42, v2, 1.0 op_sel:[0,1,0]
	v_cvt_scalef32_pk_f16_fp4 v43, v2, 1.0 op_sel:[1,1,0]
	v_cvt_scalef32_pk_f16_fp4 v44, v3, 1.0
	v_cvt_scalef32_pk_f16_fp4 v45, v3, 1.0 op_sel:[1,0,0]
	v_cvt_scalef32_pk_f16_fp4 v46, v3, 1.0 op_sel:[0,1,0]
	v_cvt_scalef32_pk_f16_fp4 v47, v3, 1.0 op_sel:[1,1,0]
	buffer_load_dwordx4 v[28:31], v115, s[12:15], s4 offen
	v_pk_fma_f16 v139, v32, s0, v139
	v_pk_fma_f16 v138, v33, s0, v138
	v_pk_fma_f16 v136, v34, s0, v136
	v_pk_fma_f16 v135, v35, s0, v135
	v_pk_fma_f16 v134, v36, s0, v134
	v_pk_fma_f16 v133, v37, s0, v133
	v_pk_fma_f16 v132, v38, s0, v132
	v_pk_fma_f16 v131, v39, s0, v131
	v_pk_fma_f16 v130, v40, s0, v130
	v_pk_fma_f16 v129, v41, s0, v129
	v_pk_fma_f16 v128, v42, s0, v128
	v_pk_fma_f16 v127, v43, s0, v127
	v_pk_fma_f16 v126, v44, s0, v126
	v_pk_fma_f16 v114, v45, s0, v114
	v_pk_fma_f16 v140, v46, s0, v140
	v_pk_fma_f16 v137, v47, s0, v137
	s_waitcnt vmcnt(6)
	v_readlane_b32 s4, v48, 6
	v_readlane_b32 s0, v53, 4
	v_cvt_scalef32_pk_f16_fp4 v32, v4, 1.0
	v_cvt_scalef32_pk_f16_fp4 v33, v4, 1.0 op_sel:[1,0,0]
	v_cvt_scalef32_pk_f16_fp4 v34, v4, 1.0 op_sel:[0,1,0]
	v_cvt_scalef32_pk_f16_fp4 v35, v4, 1.0 op_sel:[1,1,0]
	v_cvt_scalef32_pk_f16_fp4 v36, v5, 1.0
	v_cvt_scalef32_pk_f16_fp4 v37, v5, 1.0 op_sel:[1,0,0]
	v_cvt_scalef32_pk_f16_fp4 v38, v5, 1.0 op_sel:[0,1,0]
	v_cvt_scalef32_pk_f16_fp4 v39, v5, 1.0 op_sel:[1,1,0]
	v_cvt_scalef32_pk_f16_fp4 v40, v6, 1.0
	v_cvt_scalef32_pk_f16_fp4 v41, v6, 1.0 op_sel:[1,0,0]
	v_cvt_scalef32_pk_f16_fp4 v42, v6, 1.0 op_sel:[0,1,0]
	v_cvt_scalef32_pk_f16_fp4 v43, v6, 1.0 op_sel:[1,1,0]
	v_cvt_scalef32_pk_f16_fp4 v44, v7, 1.0
	v_cvt_scalef32_pk_f16_fp4 v45, v7, 1.0 op_sel:[1,0,0]
	v_cvt_scalef32_pk_f16_fp4 v46, v7, 1.0 op_sel:[0,1,0]
	v_cvt_scalef32_pk_f16_fp4 v47, v7, 1.0 op_sel:[1,1,0]
	buffer_load_dwordx4 v[0:3], v115, s[12:15], s4 offen
	v_pk_fma_f16 v124, v32, s0, v124
	v_pk_fma_f16 v123, v33, s0, v123
	v_pk_fma_f16 v121, v34, s0, v121
	v_pk_fma_f16 v120, v35, s0, v120
	v_pk_fma_f16 v119, v36, s0, v119
	v_pk_fma_f16 v118, v37, s0, v118
	v_pk_fma_f16 v117, v38, s0, v117
	v_pk_fma_f16 v116, v39, s0, v116
	v_pk_fma_f16 v113, v40, s0, v113
	v_pk_fma_f16 v112, v41, s0, v112
	v_pk_fma_f16 v67, v42, s0, v67
	v_pk_fma_f16 v66, v43, s0, v66
	v_pk_fma_f16 v65, v44, s0, v65
	v_pk_fma_f16 v64, v45, s0, v64
	v_pk_fma_f16 v125, v46, s0, v125
	v_pk_fma_f16 v122, v47, s0, v122
	s_waitcnt vmcnt(6)
	v_readlane_b32 s4, v49, 6
	v_readlane_b32 s0, v54, 4
	v_cvt_scalef32_pk_f16_fp4 v32, v8, 1.0
	v_cvt_scalef32_pk_f16_fp4 v33, v8, 1.0 op_sel:[1,0,0]
	v_cvt_scalef32_pk_f16_fp4 v34, v8, 1.0 op_sel:[0,1,0]
	v_cvt_scalef32_pk_f16_fp4 v35, v8, 1.0 op_sel:[1,1,0]
	v_cvt_scalef32_pk_f16_fp4 v36, v9, 1.0
	v_cvt_scalef32_pk_f16_fp4 v37, v9, 1.0 op_sel:[1,0,0]
	v_cvt_scalef32_pk_f16_fp4 v38, v9, 1.0 op_sel:[0,1,0]
	v_cvt_scalef32_pk_f16_fp4 v39, v9, 1.0 op_sel:[1,1,0]
	v_cvt_scalef32_pk_f16_fp4 v40, v10, 1.0
	v_cvt_scalef32_pk_f16_fp4 v41, v10, 1.0 op_sel:[1,0,0]
	v_cvt_scalef32_pk_f16_fp4 v42, v10, 1.0 op_sel:[0,1,0]
	v_cvt_scalef32_pk_f16_fp4 v43, v10, 1.0 op_sel:[1,1,0]
	v_cvt_scalef32_pk_f16_fp4 v44, v11, 1.0
	v_cvt_scalef32_pk_f16_fp4 v45, v11, 1.0 op_sel:[1,0,0]
	v_cvt_scalef32_pk_f16_fp4 v46, v11, 1.0 op_sel:[0,1,0]
	v_cvt_scalef32_pk_f16_fp4 v47, v11, 1.0 op_sel:[1,1,0]
	buffer_load_dwordx4 v[4:7], v115, s[12:15], s4 offen
	v_pk_fma_f16 v74, v32, s0, v74
	v_pk_fma_f16 v73, v33, s0, v73
	v_pk_fma_f16 v71, v34, s0, v71
	v_pk_fma_f16 v70, v35, s0, v70
	v_pk_fma_f16 v69, v36, s0, v69
	v_pk_fma_f16 v68, v37, s0, v68
	v_pk_fma_f16 v63, v38, s0, v63
	v_pk_fma_f16 v62, v39, s0, v62
	v_pk_fma_f16 v61, v40, s0, v61
	v_pk_fma_f16 v60, v41, s0, v60
	v_pk_fma_f16 v59, v42, s0, v59
	v_pk_fma_f16 v58, v43, s0, v58
	v_pk_fma_f16 v57, v44, s0, v57
	v_pk_fma_f16 v56, v45, s0, v56
	v_pk_fma_f16 v75, v46, s0, v75
	v_pk_fma_f16 v72, v47, s0, v72
	s_waitcnt vmcnt(6)
	v_readlane_b32 s4, v50, 6
	v_readlane_b32 s0, v55, 4
	v_cvt_scalef32_pk_f16_fp4 v32, v12, 1.0
	v_cvt_scalef32_pk_f16_fp4 v33, v12, 1.0 op_sel:[1,0,0]
	v_cvt_scalef32_pk_f16_fp4 v34, v12, 1.0 op_sel:[0,1,0]
	v_cvt_scalef32_pk_f16_fp4 v35, v12, 1.0 op_sel:[1,1,0]
	v_cvt_scalef32_pk_f16_fp4 v36, v13, 1.0
	v_cvt_scalef32_pk_f16_fp4 v37, v13, 1.0 op_sel:[1,0,0]
	v_cvt_scalef32_pk_f16_fp4 v38, v13, 1.0 op_sel:[0,1,0]
	v_cvt_scalef32_pk_f16_fp4 v39, v13, 1.0 op_sel:[1,1,0]
	v_cvt_scalef32_pk_f16_fp4 v40, v14, 1.0
	v_cvt_scalef32_pk_f16_fp4 v41, v14, 1.0 op_sel:[1,0,0]
	v_cvt_scalef32_pk_f16_fp4 v42, v14, 1.0 op_sel:[0,1,0]
	v_cvt_scalef32_pk_f16_fp4 v43, v14, 1.0 op_sel:[1,1,0]
	v_cvt_scalef32_pk_f16_fp4 v44, v15, 1.0
	v_cvt_scalef32_pk_f16_fp4 v45, v15, 1.0 op_sel:[1,0,0]
	v_cvt_scalef32_pk_f16_fp4 v46, v15, 1.0 op_sel:[0,1,0]
	v_cvt_scalef32_pk_f16_fp4 v47, v15, 1.0 op_sel:[1,1,0]
	buffer_load_dwordx4 v[8:11], v115, s[12:15], s4 offen
	v_pk_fma_f16 v162, v32, s0, v162
	v_pk_fma_f16 v161, v33, s0, v161
	v_pk_fma_f16 v160, v34, s0, v160
	v_pk_fma_f16 v159, v35, s0, v159
	v_pk_fma_f16 v158, v36, s0, v158
	v_pk_fma_f16 v157, v37, s0, v157
	v_pk_fma_f16 v156, v38, s0, v156
	v_pk_fma_f16 v147, v39, s0, v147
	v_pk_fma_f16 v146, v40, s0, v146
	v_pk_fma_f16 v145, v41, s0, v145
	v_pk_fma_f16 v144, v42, s0, v144
	v_pk_fma_f16 v143, v43, s0, v143
	v_pk_fma_f16 v142, v44, s0, v142
	v_pk_fma_f16 v141, v45, s0, v141
	v_pk_fma_f16 v149, v46, s0, v149
	v_pk_fma_f16 v148, v47, s0, v148
	s_waitcnt vmcnt(6)
	v_readlane_b32 s4, v51, 6
	v_readlane_b32 s0, v52, 5
	v_cvt_scalef32_pk_f16_fp4 v32, v16, 1.0
	v_cvt_scalef32_pk_f16_fp4 v33, v16, 1.0 op_sel:[1,0,0]
	v_cvt_scalef32_pk_f16_fp4 v34, v16, 1.0 op_sel:[0,1,0]
	v_cvt_scalef32_pk_f16_fp4 v35, v16, 1.0 op_sel:[1,1,0]
	v_cvt_scalef32_pk_f16_fp4 v36, v17, 1.0
	v_cvt_scalef32_pk_f16_fp4 v37, v17, 1.0 op_sel:[1,0,0]
	v_cvt_scalef32_pk_f16_fp4 v38, v17, 1.0 op_sel:[0,1,0]
	v_cvt_scalef32_pk_f16_fp4 v39, v17, 1.0 op_sel:[1,1,0]
	v_cvt_scalef32_pk_f16_fp4 v40, v18, 1.0
	v_cvt_scalef32_pk_f16_fp4 v41, v18, 1.0 op_sel:[1,0,0]
	v_cvt_scalef32_pk_f16_fp4 v42, v18, 1.0 op_sel:[0,1,0]
	v_cvt_scalef32_pk_f16_fp4 v43, v18, 1.0 op_sel:[1,1,0]
	v_cvt_scalef32_pk_f16_fp4 v44, v19, 1.0
	v_cvt_scalef32_pk_f16_fp4 v45, v19, 1.0 op_sel:[1,0,0]
	v_cvt_scalef32_pk_f16_fp4 v46, v19, 1.0 op_sel:[0,1,0]
	v_cvt_scalef32_pk_f16_fp4 v47, v19, 1.0 op_sel:[1,1,0]
	buffer_load_dwordx4 v[12:15], v115, s[12:15], s4 offen
	v_pk_fma_f16 v139, v32, s0, v139
	v_pk_fma_f16 v138, v33, s0, v138
	v_pk_fma_f16 v136, v34, s0, v136
	v_pk_fma_f16 v135, v35, s0, v135
	v_pk_fma_f16 v134, v36, s0, v134
	v_pk_fma_f16 v133, v37, s0, v133
	v_pk_fma_f16 v132, v38, s0, v132
	v_pk_fma_f16 v131, v39, s0, v131
	v_pk_fma_f16 v130, v40, s0, v130
	v_pk_fma_f16 v129, v41, s0, v129
	v_pk_fma_f16 v128, v42, s0, v128
	v_pk_fma_f16 v127, v43, s0, v127
	v_pk_fma_f16 v126, v44, s0, v126
	v_pk_fma_f16 v114, v45, s0, v114
	v_pk_fma_f16 v140, v46, s0, v140
	v_pk_fma_f16 v137, v47, s0, v137
	s_waitcnt vmcnt(6)
	v_readlane_b32 s4, v48, 7
	v_readlane_b32 s0, v53, 5
	v_cvt_scalef32_pk_f16_fp4 v32, v20, 1.0
	v_cvt_scalef32_pk_f16_fp4 v33, v20, 1.0 op_sel:[1,0,0]
	v_cvt_scalef32_pk_f16_fp4 v34, v20, 1.0 op_sel:[0,1,0]
	v_cvt_scalef32_pk_f16_fp4 v35, v20, 1.0 op_sel:[1,1,0]
	v_cvt_scalef32_pk_f16_fp4 v36, v21, 1.0
	v_cvt_scalef32_pk_f16_fp4 v37, v21, 1.0 op_sel:[1,0,0]
	v_cvt_scalef32_pk_f16_fp4 v38, v21, 1.0 op_sel:[0,1,0]
	v_cvt_scalef32_pk_f16_fp4 v39, v21, 1.0 op_sel:[1,1,0]
	v_cvt_scalef32_pk_f16_fp4 v40, v22, 1.0
	v_cvt_scalef32_pk_f16_fp4 v41, v22, 1.0 op_sel:[1,0,0]
	v_cvt_scalef32_pk_f16_fp4 v42, v22, 1.0 op_sel:[0,1,0]
	v_cvt_scalef32_pk_f16_fp4 v43, v22, 1.0 op_sel:[1,1,0]
	v_cvt_scalef32_pk_f16_fp4 v44, v23, 1.0
	v_cvt_scalef32_pk_f16_fp4 v45, v23, 1.0 op_sel:[1,0,0]
	v_cvt_scalef32_pk_f16_fp4 v46, v23, 1.0 op_sel:[0,1,0]
	v_cvt_scalef32_pk_f16_fp4 v47, v23, 1.0 op_sel:[1,1,0]
	buffer_load_dwordx4 v[16:19], v115, s[12:15], s4 offen
	v_pk_fma_f16 v124, v32, s0, v124
	v_pk_fma_f16 v123, v33, s0, v123
	v_pk_fma_f16 v121, v34, s0, v121
	v_pk_fma_f16 v120, v35, s0, v120
	v_pk_fma_f16 v119, v36, s0, v119
	v_pk_fma_f16 v118, v37, s0, v118
	v_pk_fma_f16 v117, v38, s0, v117
	v_pk_fma_f16 v116, v39, s0, v116
	v_pk_fma_f16 v113, v40, s0, v113
	v_pk_fma_f16 v112, v41, s0, v112
	v_pk_fma_f16 v67, v42, s0, v67
	v_pk_fma_f16 v66, v43, s0, v66
	v_pk_fma_f16 v65, v44, s0, v65
	v_pk_fma_f16 v64, v45, s0, v64
	v_pk_fma_f16 v125, v46, s0, v125
	v_pk_fma_f16 v122, v47, s0, v122
	s_waitcnt vmcnt(6)
	v_readlane_b32 s4, v49, 7
	v_readlane_b32 s0, v54, 5
	v_cvt_scalef32_pk_f16_fp4 v32, v24, 1.0
	v_cvt_scalef32_pk_f16_fp4 v33, v24, 1.0 op_sel:[1,0,0]
	v_cvt_scalef32_pk_f16_fp4 v34, v24, 1.0 op_sel:[0,1,0]
	v_cvt_scalef32_pk_f16_fp4 v35, v24, 1.0 op_sel:[1,1,0]
	v_cvt_scalef32_pk_f16_fp4 v36, v25, 1.0
	v_cvt_scalef32_pk_f16_fp4 v37, v25, 1.0 op_sel:[1,0,0]
	v_cvt_scalef32_pk_f16_fp4 v38, v25, 1.0 op_sel:[0,1,0]
	v_cvt_scalef32_pk_f16_fp4 v39, v25, 1.0 op_sel:[1,1,0]
	v_cvt_scalef32_pk_f16_fp4 v40, v26, 1.0
	v_cvt_scalef32_pk_f16_fp4 v41, v26, 1.0 op_sel:[1,0,0]
	v_cvt_scalef32_pk_f16_fp4 v42, v26, 1.0 op_sel:[0,1,0]
	v_cvt_scalef32_pk_f16_fp4 v43, v26, 1.0 op_sel:[1,1,0]
	v_cvt_scalef32_pk_f16_fp4 v44, v27, 1.0
	v_cvt_scalef32_pk_f16_fp4 v45, v27, 1.0 op_sel:[1,0,0]
	v_cvt_scalef32_pk_f16_fp4 v46, v27, 1.0 op_sel:[0,1,0]
	v_cvt_scalef32_pk_f16_fp4 v47, v27, 1.0 op_sel:[1,1,0]
	buffer_load_dwordx4 v[20:23], v115, s[12:15], s4 offen
	v_pk_fma_f16 v74, v32, s0, v74
	v_pk_fma_f16 v73, v33, s0, v73
	v_pk_fma_f16 v71, v34, s0, v71
	v_pk_fma_f16 v70, v35, s0, v70
	v_pk_fma_f16 v69, v36, s0, v69
	v_pk_fma_f16 v68, v37, s0, v68
	v_pk_fma_f16 v63, v38, s0, v63
	v_pk_fma_f16 v62, v39, s0, v62
	v_pk_fma_f16 v61, v40, s0, v61
	v_pk_fma_f16 v60, v41, s0, v60
	v_pk_fma_f16 v59, v42, s0, v59
	v_pk_fma_f16 v58, v43, s0, v58
	v_pk_fma_f16 v57, v44, s0, v57
	v_pk_fma_f16 v56, v45, s0, v56
	v_pk_fma_f16 v75, v46, s0, v75
	v_pk_fma_f16 v72, v47, s0, v72
	s_waitcnt vmcnt(6)
	v_readlane_b32 s4, v50, 7
	v_readlane_b32 s0, v55, 5
	v_cvt_scalef32_pk_f16_fp4 v32, v28, 1.0
	v_cvt_scalef32_pk_f16_fp4 v33, v28, 1.0 op_sel:[1,0,0]
	v_cvt_scalef32_pk_f16_fp4 v34, v28, 1.0 op_sel:[0,1,0]
	v_cvt_scalef32_pk_f16_fp4 v35, v28, 1.0 op_sel:[1,1,0]
	v_cvt_scalef32_pk_f16_fp4 v36, v29, 1.0
	v_cvt_scalef32_pk_f16_fp4 v37, v29, 1.0 op_sel:[1,0,0]
	v_cvt_scalef32_pk_f16_fp4 v38, v29, 1.0 op_sel:[0,1,0]
	v_cvt_scalef32_pk_f16_fp4 v39, v29, 1.0 op_sel:[1,1,0]
	v_cvt_scalef32_pk_f16_fp4 v40, v30, 1.0
	v_cvt_scalef32_pk_f16_fp4 v41, v30, 1.0 op_sel:[1,0,0]
	v_cvt_scalef32_pk_f16_fp4 v42, v30, 1.0 op_sel:[0,1,0]
	v_cvt_scalef32_pk_f16_fp4 v43, v30, 1.0 op_sel:[1,1,0]
	v_cvt_scalef32_pk_f16_fp4 v44, v31, 1.0
	v_cvt_scalef32_pk_f16_fp4 v45, v31, 1.0 op_sel:[1,0,0]
	v_cvt_scalef32_pk_f16_fp4 v46, v31, 1.0 op_sel:[0,1,0]
	v_cvt_scalef32_pk_f16_fp4 v47, v31, 1.0 op_sel:[1,1,0]
	buffer_load_dwordx4 v[24:27], v115, s[12:15], s4 offen
	v_pk_fma_f16 v162, v32, s0, v162
	v_pk_fma_f16 v161, v33, s0, v161
	v_pk_fma_f16 v160, v34, s0, v160
	v_pk_fma_f16 v159, v35, s0, v159
	v_pk_fma_f16 v158, v36, s0, v158
	v_pk_fma_f16 v157, v37, s0, v157
	v_pk_fma_f16 v156, v38, s0, v156
	v_pk_fma_f16 v147, v39, s0, v147
	v_pk_fma_f16 v146, v40, s0, v146
	v_pk_fma_f16 v145, v41, s0, v145
	v_pk_fma_f16 v144, v42, s0, v144
	v_pk_fma_f16 v143, v43, s0, v143
	v_pk_fma_f16 v142, v44, s0, v142
	v_pk_fma_f16 v141, v45, s0, v141
	v_pk_fma_f16 v149, v46, s0, v149
	v_pk_fma_f16 v148, v47, s0, v148
	s_waitcnt vmcnt(6)
	v_readlane_b32 s4, v51, 7
	v_readlane_b32 s0, v52, 6
	v_cvt_scalef32_pk_f16_fp4 v32, v0, 1.0
	v_cvt_scalef32_pk_f16_fp4 v33, v0, 1.0 op_sel:[1,0,0]
	v_cvt_scalef32_pk_f16_fp4 v34, v0, 1.0 op_sel:[0,1,0]
	v_cvt_scalef32_pk_f16_fp4 v35, v0, 1.0 op_sel:[1,1,0]
	v_cvt_scalef32_pk_f16_fp4 v36, v1, 1.0
	v_cvt_scalef32_pk_f16_fp4 v37, v1, 1.0 op_sel:[1,0,0]
	v_cvt_scalef32_pk_f16_fp4 v38, v1, 1.0 op_sel:[0,1,0]
	v_cvt_scalef32_pk_f16_fp4 v39, v1, 1.0 op_sel:[1,1,0]
	v_cvt_scalef32_pk_f16_fp4 v40, v2, 1.0
	v_cvt_scalef32_pk_f16_fp4 v41, v2, 1.0 op_sel:[1,0,0]
	v_cvt_scalef32_pk_f16_fp4 v42, v2, 1.0 op_sel:[0,1,0]
	v_cvt_scalef32_pk_f16_fp4 v43, v2, 1.0 op_sel:[1,1,0]
	v_cvt_scalef32_pk_f16_fp4 v44, v3, 1.0
	v_cvt_scalef32_pk_f16_fp4 v45, v3, 1.0 op_sel:[1,0,0]
	v_cvt_scalef32_pk_f16_fp4 v46, v3, 1.0 op_sel:[0,1,0]
	v_cvt_scalef32_pk_f16_fp4 v47, v3, 1.0 op_sel:[1,1,0]
	buffer_load_dwordx4 v[28:31], v115, s[12:15], s4 offen
	v_pk_fma_f16 v139, v32, s0, v139
	v_pk_fma_f16 v138, v33, s0, v138
	v_pk_fma_f16 v136, v34, s0, v136
	v_pk_fma_f16 v135, v35, s0, v135
	v_pk_fma_f16 v134, v36, s0, v134
	v_pk_fma_f16 v133, v37, s0, v133
	v_pk_fma_f16 v132, v38, s0, v132
	v_pk_fma_f16 v131, v39, s0, v131
	v_pk_fma_f16 v130, v40, s0, v130
	v_pk_fma_f16 v129, v41, s0, v129
	v_pk_fma_f16 v128, v42, s0, v128
	v_pk_fma_f16 v127, v43, s0, v127
	v_pk_fma_f16 v126, v44, s0, v126
	v_pk_fma_f16 v114, v45, s0, v114
	v_pk_fma_f16 v140, v46, s0, v140
	v_pk_fma_f16 v137, v47, s0, v137
	s_waitcnt vmcnt(6)
	v_readlane_b32 s4, v48, 8
	v_readlane_b32 s0, v53, 6
	v_cvt_scalef32_pk_f16_fp4 v32, v4, 1.0
	v_cvt_scalef32_pk_f16_fp4 v33, v4, 1.0 op_sel:[1,0,0]
	v_cvt_scalef32_pk_f16_fp4 v34, v4, 1.0 op_sel:[0,1,0]
	v_cvt_scalef32_pk_f16_fp4 v35, v4, 1.0 op_sel:[1,1,0]
	v_cvt_scalef32_pk_f16_fp4 v36, v5, 1.0
	v_cvt_scalef32_pk_f16_fp4 v37, v5, 1.0 op_sel:[1,0,0]
	v_cvt_scalef32_pk_f16_fp4 v38, v5, 1.0 op_sel:[0,1,0]
	v_cvt_scalef32_pk_f16_fp4 v39, v5, 1.0 op_sel:[1,1,0]
	v_cvt_scalef32_pk_f16_fp4 v40, v6, 1.0
	v_cvt_scalef32_pk_f16_fp4 v41, v6, 1.0 op_sel:[1,0,0]
	v_cvt_scalef32_pk_f16_fp4 v42, v6, 1.0 op_sel:[0,1,0]
	v_cvt_scalef32_pk_f16_fp4 v43, v6, 1.0 op_sel:[1,1,0]
	v_cvt_scalef32_pk_f16_fp4 v44, v7, 1.0
	v_cvt_scalef32_pk_f16_fp4 v45, v7, 1.0 op_sel:[1,0,0]
	v_cvt_scalef32_pk_f16_fp4 v46, v7, 1.0 op_sel:[0,1,0]
	v_cvt_scalef32_pk_f16_fp4 v47, v7, 1.0 op_sel:[1,1,0]
	buffer_load_dwordx4 v[0:3], v115, s[12:15], s4 offen
	v_pk_fma_f16 v124, v32, s0, v124
	v_pk_fma_f16 v123, v33, s0, v123
	v_pk_fma_f16 v121, v34, s0, v121
	v_pk_fma_f16 v120, v35, s0, v120
	v_pk_fma_f16 v119, v36, s0, v119
	v_pk_fma_f16 v118, v37, s0, v118
	v_pk_fma_f16 v117, v38, s0, v117
	v_pk_fma_f16 v116, v39, s0, v116
	v_pk_fma_f16 v113, v40, s0, v113
	v_pk_fma_f16 v112, v41, s0, v112
	v_pk_fma_f16 v67, v42, s0, v67
	v_pk_fma_f16 v66, v43, s0, v66
	v_pk_fma_f16 v65, v44, s0, v65
	v_pk_fma_f16 v64, v45, s0, v64
	v_pk_fma_f16 v125, v46, s0, v125
	v_pk_fma_f16 v122, v47, s0, v122
	s_waitcnt vmcnt(6)
	v_readlane_b32 s4, v49, 8
	v_readlane_b32 s0, v54, 6
	v_cvt_scalef32_pk_f16_fp4 v32, v8, 1.0
	v_cvt_scalef32_pk_f16_fp4 v33, v8, 1.0 op_sel:[1,0,0]
	v_cvt_scalef32_pk_f16_fp4 v34, v8, 1.0 op_sel:[0,1,0]
	v_cvt_scalef32_pk_f16_fp4 v35, v8, 1.0 op_sel:[1,1,0]
	v_cvt_scalef32_pk_f16_fp4 v36, v9, 1.0
	v_cvt_scalef32_pk_f16_fp4 v37, v9, 1.0 op_sel:[1,0,0]
	v_cvt_scalef32_pk_f16_fp4 v38, v9, 1.0 op_sel:[0,1,0]
	v_cvt_scalef32_pk_f16_fp4 v39, v9, 1.0 op_sel:[1,1,0]
	v_cvt_scalef32_pk_f16_fp4 v40, v10, 1.0
	v_cvt_scalef32_pk_f16_fp4 v41, v10, 1.0 op_sel:[1,0,0]
	v_cvt_scalef32_pk_f16_fp4 v42, v10, 1.0 op_sel:[0,1,0]
	v_cvt_scalef32_pk_f16_fp4 v43, v10, 1.0 op_sel:[1,1,0]
	v_cvt_scalef32_pk_f16_fp4 v44, v11, 1.0
	v_cvt_scalef32_pk_f16_fp4 v45, v11, 1.0 op_sel:[1,0,0]
	v_cvt_scalef32_pk_f16_fp4 v46, v11, 1.0 op_sel:[0,1,0]
	v_cvt_scalef32_pk_f16_fp4 v47, v11, 1.0 op_sel:[1,1,0]
	buffer_load_dwordx4 v[4:7], v115, s[12:15], s4 offen
	v_pk_fma_f16 v74, v32, s0, v74
	v_pk_fma_f16 v73, v33, s0, v73
	v_pk_fma_f16 v71, v34, s0, v71
	v_pk_fma_f16 v70, v35, s0, v70
	v_pk_fma_f16 v69, v36, s0, v69
	v_pk_fma_f16 v68, v37, s0, v68
	v_pk_fma_f16 v63, v38, s0, v63
	v_pk_fma_f16 v62, v39, s0, v62
	v_pk_fma_f16 v61, v40, s0, v61
	v_pk_fma_f16 v60, v41, s0, v60
	v_pk_fma_f16 v59, v42, s0, v59
	v_pk_fma_f16 v58, v43, s0, v58
	v_pk_fma_f16 v57, v44, s0, v57
	v_pk_fma_f16 v56, v45, s0, v56
	v_pk_fma_f16 v75, v46, s0, v75
	v_pk_fma_f16 v72, v47, s0, v72
	s_waitcnt vmcnt(6)
	v_readlane_b32 s4, v50, 8
	v_readlane_b32 s0, v55, 6
	v_cvt_scalef32_pk_f16_fp4 v32, v12, 1.0
	v_cvt_scalef32_pk_f16_fp4 v33, v12, 1.0 op_sel:[1,0,0]
	v_cvt_scalef32_pk_f16_fp4 v34, v12, 1.0 op_sel:[0,1,0]
	v_cvt_scalef32_pk_f16_fp4 v35, v12, 1.0 op_sel:[1,1,0]
	v_cvt_scalef32_pk_f16_fp4 v36, v13, 1.0
	v_cvt_scalef32_pk_f16_fp4 v37, v13, 1.0 op_sel:[1,0,0]
	v_cvt_scalef32_pk_f16_fp4 v38, v13, 1.0 op_sel:[0,1,0]
	v_cvt_scalef32_pk_f16_fp4 v39, v13, 1.0 op_sel:[1,1,0]
	v_cvt_scalef32_pk_f16_fp4 v40, v14, 1.0
	v_cvt_scalef32_pk_f16_fp4 v41, v14, 1.0 op_sel:[1,0,0]
	v_cvt_scalef32_pk_f16_fp4 v42, v14, 1.0 op_sel:[0,1,0]
	v_cvt_scalef32_pk_f16_fp4 v43, v14, 1.0 op_sel:[1,1,0]
	v_cvt_scalef32_pk_f16_fp4 v44, v15, 1.0
	v_cvt_scalef32_pk_f16_fp4 v45, v15, 1.0 op_sel:[1,0,0]
	v_cvt_scalef32_pk_f16_fp4 v46, v15, 1.0 op_sel:[0,1,0]
	v_cvt_scalef32_pk_f16_fp4 v47, v15, 1.0 op_sel:[1,1,0]
	buffer_load_dwordx4 v[8:11], v115, s[12:15], s4 offen
	v_pk_fma_f16 v162, v32, s0, v162
	v_pk_fma_f16 v161, v33, s0, v161
	v_pk_fma_f16 v160, v34, s0, v160
	v_pk_fma_f16 v159, v35, s0, v159
	v_pk_fma_f16 v158, v36, s0, v158
	v_pk_fma_f16 v157, v37, s0, v157
	v_pk_fma_f16 v156, v38, s0, v156
	v_pk_fma_f16 v147, v39, s0, v147
	v_pk_fma_f16 v146, v40, s0, v146
	v_pk_fma_f16 v145, v41, s0, v145
	v_pk_fma_f16 v144, v42, s0, v144
	v_pk_fma_f16 v143, v43, s0, v143
	v_pk_fma_f16 v142, v44, s0, v142
	v_pk_fma_f16 v141, v45, s0, v141
	v_pk_fma_f16 v149, v46, s0, v149
	v_pk_fma_f16 v148, v47, s0, v148
	s_waitcnt vmcnt(6)
	v_readlane_b32 s4, v51, 8
	v_readlane_b32 s0, v52, 7
	v_cvt_scalef32_pk_f16_fp4 v32, v16, 1.0
	v_cvt_scalef32_pk_f16_fp4 v33, v16, 1.0 op_sel:[1,0,0]
	v_cvt_scalef32_pk_f16_fp4 v34, v16, 1.0 op_sel:[0,1,0]
	v_cvt_scalef32_pk_f16_fp4 v35, v16, 1.0 op_sel:[1,1,0]
	v_cvt_scalef32_pk_f16_fp4 v36, v17, 1.0
	v_cvt_scalef32_pk_f16_fp4 v37, v17, 1.0 op_sel:[1,0,0]
	v_cvt_scalef32_pk_f16_fp4 v38, v17, 1.0 op_sel:[0,1,0]
	v_cvt_scalef32_pk_f16_fp4 v39, v17, 1.0 op_sel:[1,1,0]
	v_cvt_scalef32_pk_f16_fp4 v40, v18, 1.0
	v_cvt_scalef32_pk_f16_fp4 v41, v18, 1.0 op_sel:[1,0,0]
	v_cvt_scalef32_pk_f16_fp4 v42, v18, 1.0 op_sel:[0,1,0]
	v_cvt_scalef32_pk_f16_fp4 v43, v18, 1.0 op_sel:[1,1,0]
	v_cvt_scalef32_pk_f16_fp4 v44, v19, 1.0
	v_cvt_scalef32_pk_f16_fp4 v45, v19, 1.0 op_sel:[1,0,0]
	v_cvt_scalef32_pk_f16_fp4 v46, v19, 1.0 op_sel:[0,1,0]
	v_cvt_scalef32_pk_f16_fp4 v47, v19, 1.0 op_sel:[1,1,0]
	buffer_load_dwordx4 v[12:15], v115, s[12:15], s4 offen
	v_pk_fma_f16 v139, v32, s0, v139
	v_pk_fma_f16 v138, v33, s0, v138
	v_pk_fma_f16 v136, v34, s0, v136
	v_pk_fma_f16 v135, v35, s0, v135
	v_pk_fma_f16 v134, v36, s0, v134
	v_pk_fma_f16 v133, v37, s0, v133
	v_pk_fma_f16 v132, v38, s0, v132
	v_pk_fma_f16 v131, v39, s0, v131
	v_pk_fma_f16 v130, v40, s0, v130
	v_pk_fma_f16 v129, v41, s0, v129
	v_pk_fma_f16 v128, v42, s0, v128
	v_pk_fma_f16 v127, v43, s0, v127
	v_pk_fma_f16 v126, v44, s0, v126
	v_pk_fma_f16 v114, v45, s0, v114
	v_pk_fma_f16 v140, v46, s0, v140
	v_pk_fma_f16 v137, v47, s0, v137
	s_waitcnt vmcnt(6)
	v_readlane_b32 s4, v48, 9
	v_readlane_b32 s0, v53, 7
	v_cvt_scalef32_pk_f16_fp4 v32, v20, 1.0
	v_cvt_scalef32_pk_f16_fp4 v33, v20, 1.0 op_sel:[1,0,0]
	v_cvt_scalef32_pk_f16_fp4 v34, v20, 1.0 op_sel:[0,1,0]
	v_cvt_scalef32_pk_f16_fp4 v35, v20, 1.0 op_sel:[1,1,0]
	v_cvt_scalef32_pk_f16_fp4 v36, v21, 1.0
	v_cvt_scalef32_pk_f16_fp4 v37, v21, 1.0 op_sel:[1,0,0]
	v_cvt_scalef32_pk_f16_fp4 v38, v21, 1.0 op_sel:[0,1,0]
	v_cvt_scalef32_pk_f16_fp4 v39, v21, 1.0 op_sel:[1,1,0]
	v_cvt_scalef32_pk_f16_fp4 v40, v22, 1.0
	v_cvt_scalef32_pk_f16_fp4 v41, v22, 1.0 op_sel:[1,0,0]
	v_cvt_scalef32_pk_f16_fp4 v42, v22, 1.0 op_sel:[0,1,0]
	v_cvt_scalef32_pk_f16_fp4 v43, v22, 1.0 op_sel:[1,1,0]
	v_cvt_scalef32_pk_f16_fp4 v44, v23, 1.0
	v_cvt_scalef32_pk_f16_fp4 v45, v23, 1.0 op_sel:[1,0,0]
	v_cvt_scalef32_pk_f16_fp4 v46, v23, 1.0 op_sel:[0,1,0]
	v_cvt_scalef32_pk_f16_fp4 v47, v23, 1.0 op_sel:[1,1,0]
	buffer_load_dwordx4 v[16:19], v115, s[12:15], s4 offen
	v_pk_fma_f16 v124, v32, s0, v124
	v_pk_fma_f16 v123, v33, s0, v123
	v_pk_fma_f16 v121, v34, s0, v121
	v_pk_fma_f16 v120, v35, s0, v120
	v_pk_fma_f16 v119, v36, s0, v119
	v_pk_fma_f16 v118, v37, s0, v118
	v_pk_fma_f16 v117, v38, s0, v117
	v_pk_fma_f16 v116, v39, s0, v116
	v_pk_fma_f16 v113, v40, s0, v113
	v_pk_fma_f16 v112, v41, s0, v112
	v_pk_fma_f16 v67, v42, s0, v67
	v_pk_fma_f16 v66, v43, s0, v66
	v_pk_fma_f16 v65, v44, s0, v65
	v_pk_fma_f16 v64, v45, s0, v64
	v_pk_fma_f16 v125, v46, s0, v125
	v_pk_fma_f16 v122, v47, s0, v122
	s_waitcnt vmcnt(6)
	v_readlane_b32 s4, v49, 9
	v_readlane_b32 s0, v54, 7
	v_cvt_scalef32_pk_f16_fp4 v32, v24, 1.0
	v_cvt_scalef32_pk_f16_fp4 v33, v24, 1.0 op_sel:[1,0,0]
	v_cvt_scalef32_pk_f16_fp4 v34, v24, 1.0 op_sel:[0,1,0]
	v_cvt_scalef32_pk_f16_fp4 v35, v24, 1.0 op_sel:[1,1,0]
	v_cvt_scalef32_pk_f16_fp4 v36, v25, 1.0
	v_cvt_scalef32_pk_f16_fp4 v37, v25, 1.0 op_sel:[1,0,0]
	v_cvt_scalef32_pk_f16_fp4 v38, v25, 1.0 op_sel:[0,1,0]
	v_cvt_scalef32_pk_f16_fp4 v39, v25, 1.0 op_sel:[1,1,0]
	v_cvt_scalef32_pk_f16_fp4 v40, v26, 1.0
	v_cvt_scalef32_pk_f16_fp4 v41, v26, 1.0 op_sel:[1,0,0]
	v_cvt_scalef32_pk_f16_fp4 v42, v26, 1.0 op_sel:[0,1,0]
	v_cvt_scalef32_pk_f16_fp4 v43, v26, 1.0 op_sel:[1,1,0]
	v_cvt_scalef32_pk_f16_fp4 v44, v27, 1.0
	v_cvt_scalef32_pk_f16_fp4 v45, v27, 1.0 op_sel:[1,0,0]
	v_cvt_scalef32_pk_f16_fp4 v46, v27, 1.0 op_sel:[0,1,0]
	v_cvt_scalef32_pk_f16_fp4 v47, v27, 1.0 op_sel:[1,1,0]
	buffer_load_dwordx4 v[20:23], v115, s[12:15], s4 offen
	v_pk_fma_f16 v74, v32, s0, v74
	v_pk_fma_f16 v73, v33, s0, v73
	v_pk_fma_f16 v71, v34, s0, v71
	v_pk_fma_f16 v70, v35, s0, v70
	v_pk_fma_f16 v69, v36, s0, v69
	v_pk_fma_f16 v68, v37, s0, v68
	v_pk_fma_f16 v63, v38, s0, v63
	v_pk_fma_f16 v62, v39, s0, v62
	v_pk_fma_f16 v61, v40, s0, v61
	v_pk_fma_f16 v60, v41, s0, v60
	v_pk_fma_f16 v59, v42, s0, v59
	v_pk_fma_f16 v58, v43, s0, v58
	v_pk_fma_f16 v57, v44, s0, v57
	v_pk_fma_f16 v56, v45, s0, v56
	v_pk_fma_f16 v75, v46, s0, v75
	v_pk_fma_f16 v72, v47, s0, v72
	s_waitcnt vmcnt(6)
	v_readlane_b32 s4, v50, 9
	v_readlane_b32 s0, v55, 7
	v_cvt_scalef32_pk_f16_fp4 v32, v28, 1.0
	v_cvt_scalef32_pk_f16_fp4 v33, v28, 1.0 op_sel:[1,0,0]
	v_cvt_scalef32_pk_f16_fp4 v34, v28, 1.0 op_sel:[0,1,0]
	v_cvt_scalef32_pk_f16_fp4 v35, v28, 1.0 op_sel:[1,1,0]
	v_cvt_scalef32_pk_f16_fp4 v36, v29, 1.0
	v_cvt_scalef32_pk_f16_fp4 v37, v29, 1.0 op_sel:[1,0,0]
	v_cvt_scalef32_pk_f16_fp4 v38, v29, 1.0 op_sel:[0,1,0]
	v_cvt_scalef32_pk_f16_fp4 v39, v29, 1.0 op_sel:[1,1,0]
	v_cvt_scalef32_pk_f16_fp4 v40, v30, 1.0
	v_cvt_scalef32_pk_f16_fp4 v41, v30, 1.0 op_sel:[1,0,0]
	v_cvt_scalef32_pk_f16_fp4 v42, v30, 1.0 op_sel:[0,1,0]
	v_cvt_scalef32_pk_f16_fp4 v43, v30, 1.0 op_sel:[1,1,0]
	v_cvt_scalef32_pk_f16_fp4 v44, v31, 1.0
	v_cvt_scalef32_pk_f16_fp4 v45, v31, 1.0 op_sel:[1,0,0]
	v_cvt_scalef32_pk_f16_fp4 v46, v31, 1.0 op_sel:[0,1,0]
	v_cvt_scalef32_pk_f16_fp4 v47, v31, 1.0 op_sel:[1,1,0]
	buffer_load_dwordx4 v[24:27], v115, s[12:15], s4 offen
	v_pk_fma_f16 v162, v32, s0, v162
	v_pk_fma_f16 v161, v33, s0, v161
	v_pk_fma_f16 v160, v34, s0, v160
	v_pk_fma_f16 v159, v35, s0, v159
	v_pk_fma_f16 v158, v36, s0, v158
	v_pk_fma_f16 v157, v37, s0, v157
	v_pk_fma_f16 v156, v38, s0, v156
	v_pk_fma_f16 v147, v39, s0, v147
	v_pk_fma_f16 v146, v40, s0, v146
	v_pk_fma_f16 v145, v41, s0, v145
	v_pk_fma_f16 v144, v42, s0, v144
	v_pk_fma_f16 v143, v43, s0, v143
	v_pk_fma_f16 v142, v44, s0, v142
	v_pk_fma_f16 v141, v45, s0, v141
	v_pk_fma_f16 v149, v46, s0, v149
	v_pk_fma_f16 v148, v47, s0, v148
	s_waitcnt vmcnt(6)
	v_readlane_b32 s4, v51, 9
	v_readlane_b32 s0, v52, 8
	v_cvt_scalef32_pk_f16_fp4 v32, v0, 1.0
	v_cvt_scalef32_pk_f16_fp4 v33, v0, 1.0 op_sel:[1,0,0]
	v_cvt_scalef32_pk_f16_fp4 v34, v0, 1.0 op_sel:[0,1,0]
	v_cvt_scalef32_pk_f16_fp4 v35, v0, 1.0 op_sel:[1,1,0]
	v_cvt_scalef32_pk_f16_fp4 v36, v1, 1.0
	v_cvt_scalef32_pk_f16_fp4 v37, v1, 1.0 op_sel:[1,0,0]
	v_cvt_scalef32_pk_f16_fp4 v38, v1, 1.0 op_sel:[0,1,0]
	v_cvt_scalef32_pk_f16_fp4 v39, v1, 1.0 op_sel:[1,1,0]
	v_cvt_scalef32_pk_f16_fp4 v40, v2, 1.0
	v_cvt_scalef32_pk_f16_fp4 v41, v2, 1.0 op_sel:[1,0,0]
	v_cvt_scalef32_pk_f16_fp4 v42, v2, 1.0 op_sel:[0,1,0]
	v_cvt_scalef32_pk_f16_fp4 v43, v2, 1.0 op_sel:[1,1,0]
	v_cvt_scalef32_pk_f16_fp4 v44, v3, 1.0
	v_cvt_scalef32_pk_f16_fp4 v45, v3, 1.0 op_sel:[1,0,0]
	v_cvt_scalef32_pk_f16_fp4 v46, v3, 1.0 op_sel:[0,1,0]
	v_cvt_scalef32_pk_f16_fp4 v47, v3, 1.0 op_sel:[1,1,0]
	buffer_load_dwordx4 v[28:31], v115, s[12:15], s4 offen
	v_pk_fma_f16 v139, v32, s0, v139
	v_pk_fma_f16 v138, v33, s0, v138
	v_pk_fma_f16 v136, v34, s0, v136
	v_pk_fma_f16 v135, v35, s0, v135
	v_pk_fma_f16 v134, v36, s0, v134
	v_pk_fma_f16 v133, v37, s0, v133
	v_pk_fma_f16 v132, v38, s0, v132
	v_pk_fma_f16 v131, v39, s0, v131
	v_pk_fma_f16 v130, v40, s0, v130
	v_pk_fma_f16 v129, v41, s0, v129
	v_pk_fma_f16 v128, v42, s0, v128
	v_pk_fma_f16 v127, v43, s0, v127
	v_pk_fma_f16 v126, v44, s0, v126
	v_pk_fma_f16 v114, v45, s0, v114
	v_pk_fma_f16 v140, v46, s0, v140
	v_pk_fma_f16 v137, v47, s0, v137
	s_waitcnt vmcnt(6)
	v_readlane_b32 s4, v48, 10
	v_readlane_b32 s0, v53, 8
	v_cvt_scalef32_pk_f16_fp4 v32, v4, 1.0
	v_cvt_scalef32_pk_f16_fp4 v33, v4, 1.0 op_sel:[1,0,0]
	v_cvt_scalef32_pk_f16_fp4 v34, v4, 1.0 op_sel:[0,1,0]
	v_cvt_scalef32_pk_f16_fp4 v35, v4, 1.0 op_sel:[1,1,0]
	v_cvt_scalef32_pk_f16_fp4 v36, v5, 1.0
	v_cvt_scalef32_pk_f16_fp4 v37, v5, 1.0 op_sel:[1,0,0]
	v_cvt_scalef32_pk_f16_fp4 v38, v5, 1.0 op_sel:[0,1,0]
	v_cvt_scalef32_pk_f16_fp4 v39, v5, 1.0 op_sel:[1,1,0]
	v_cvt_scalef32_pk_f16_fp4 v40, v6, 1.0
	v_cvt_scalef32_pk_f16_fp4 v41, v6, 1.0 op_sel:[1,0,0]
	v_cvt_scalef32_pk_f16_fp4 v42, v6, 1.0 op_sel:[0,1,0]
	v_cvt_scalef32_pk_f16_fp4 v43, v6, 1.0 op_sel:[1,1,0]
	v_cvt_scalef32_pk_f16_fp4 v44, v7, 1.0
	v_cvt_scalef32_pk_f16_fp4 v45, v7, 1.0 op_sel:[1,0,0]
	v_cvt_scalef32_pk_f16_fp4 v46, v7, 1.0 op_sel:[0,1,0]
	v_cvt_scalef32_pk_f16_fp4 v47, v7, 1.0 op_sel:[1,1,0]
	buffer_load_dwordx4 v[0:3], v115, s[12:15], s4 offen
	v_pk_fma_f16 v124, v32, s0, v124
	v_pk_fma_f16 v123, v33, s0, v123
	v_pk_fma_f16 v121, v34, s0, v121
	v_pk_fma_f16 v120, v35, s0, v120
	v_pk_fma_f16 v119, v36, s0, v119
	v_pk_fma_f16 v118, v37, s0, v118
	v_pk_fma_f16 v117, v38, s0, v117
	v_pk_fma_f16 v116, v39, s0, v116
	v_pk_fma_f16 v113, v40, s0, v113
	v_pk_fma_f16 v112, v41, s0, v112
	v_pk_fma_f16 v67, v42, s0, v67
	v_pk_fma_f16 v66, v43, s0, v66
	v_pk_fma_f16 v65, v44, s0, v65
	v_pk_fma_f16 v64, v45, s0, v64
	v_pk_fma_f16 v125, v46, s0, v125
	v_pk_fma_f16 v122, v47, s0, v122
	s_waitcnt vmcnt(6)
	v_readlane_b32 s4, v49, 10
	v_readlane_b32 s0, v54, 8
	v_cvt_scalef32_pk_f16_fp4 v32, v8, 1.0
	v_cvt_scalef32_pk_f16_fp4 v33, v8, 1.0 op_sel:[1,0,0]
	v_cvt_scalef32_pk_f16_fp4 v34, v8, 1.0 op_sel:[0,1,0]
	v_cvt_scalef32_pk_f16_fp4 v35, v8, 1.0 op_sel:[1,1,0]
	v_cvt_scalef32_pk_f16_fp4 v36, v9, 1.0
	v_cvt_scalef32_pk_f16_fp4 v37, v9, 1.0 op_sel:[1,0,0]
	v_cvt_scalef32_pk_f16_fp4 v38, v9, 1.0 op_sel:[0,1,0]
	v_cvt_scalef32_pk_f16_fp4 v39, v9, 1.0 op_sel:[1,1,0]
	v_cvt_scalef32_pk_f16_fp4 v40, v10, 1.0
	v_cvt_scalef32_pk_f16_fp4 v41, v10, 1.0 op_sel:[1,0,0]
	v_cvt_scalef32_pk_f16_fp4 v42, v10, 1.0 op_sel:[0,1,0]
	v_cvt_scalef32_pk_f16_fp4 v43, v10, 1.0 op_sel:[1,1,0]
	v_cvt_scalef32_pk_f16_fp4 v44, v11, 1.0
	v_cvt_scalef32_pk_f16_fp4 v45, v11, 1.0 op_sel:[1,0,0]
	v_cvt_scalef32_pk_f16_fp4 v46, v11, 1.0 op_sel:[0,1,0]
	v_cvt_scalef32_pk_f16_fp4 v47, v11, 1.0 op_sel:[1,1,0]
	buffer_load_dwordx4 v[4:7], v115, s[12:15], s4 offen
	v_pk_fma_f16 v74, v32, s0, v74
	v_pk_fma_f16 v73, v33, s0, v73
	v_pk_fma_f16 v71, v34, s0, v71
	v_pk_fma_f16 v70, v35, s0, v70
	v_pk_fma_f16 v69, v36, s0, v69
	v_pk_fma_f16 v68, v37, s0, v68
	v_pk_fma_f16 v63, v38, s0, v63
	v_pk_fma_f16 v62, v39, s0, v62
	v_pk_fma_f16 v61, v40, s0, v61
	v_pk_fma_f16 v60, v41, s0, v60
	v_pk_fma_f16 v59, v42, s0, v59
	v_pk_fma_f16 v58, v43, s0, v58
	v_pk_fma_f16 v57, v44, s0, v57
	v_pk_fma_f16 v56, v45, s0, v56
	v_pk_fma_f16 v75, v46, s0, v75
	v_pk_fma_f16 v72, v47, s0, v72
	s_waitcnt vmcnt(6)
	v_readlane_b32 s4, v50, 10
	v_readlane_b32 s0, v55, 8
	v_cvt_scalef32_pk_f16_fp4 v32, v12, 1.0
	v_cvt_scalef32_pk_f16_fp4 v33, v12, 1.0 op_sel:[1,0,0]
	v_cvt_scalef32_pk_f16_fp4 v34, v12, 1.0 op_sel:[0,1,0]
	v_cvt_scalef32_pk_f16_fp4 v35, v12, 1.0 op_sel:[1,1,0]
	v_cvt_scalef32_pk_f16_fp4 v36, v13, 1.0
	v_cvt_scalef32_pk_f16_fp4 v37, v13, 1.0 op_sel:[1,0,0]
	v_cvt_scalef32_pk_f16_fp4 v38, v13, 1.0 op_sel:[0,1,0]
	v_cvt_scalef32_pk_f16_fp4 v39, v13, 1.0 op_sel:[1,1,0]
	v_cvt_scalef32_pk_f16_fp4 v40, v14, 1.0
	v_cvt_scalef32_pk_f16_fp4 v41, v14, 1.0 op_sel:[1,0,0]
	v_cvt_scalef32_pk_f16_fp4 v42, v14, 1.0 op_sel:[0,1,0]
	v_cvt_scalef32_pk_f16_fp4 v43, v14, 1.0 op_sel:[1,1,0]
	v_cvt_scalef32_pk_f16_fp4 v44, v15, 1.0
	v_cvt_scalef32_pk_f16_fp4 v45, v15, 1.0 op_sel:[1,0,0]
	v_cvt_scalef32_pk_f16_fp4 v46, v15, 1.0 op_sel:[0,1,0]
	v_cvt_scalef32_pk_f16_fp4 v47, v15, 1.0 op_sel:[1,1,0]
	buffer_load_dwordx4 v[8:11], v115, s[12:15], s4 offen
	v_pk_fma_f16 v162, v32, s0, v162
	v_pk_fma_f16 v161, v33, s0, v161
	v_pk_fma_f16 v160, v34, s0, v160
	v_pk_fma_f16 v159, v35, s0, v159
	v_pk_fma_f16 v158, v36, s0, v158
	v_pk_fma_f16 v157, v37, s0, v157
	v_pk_fma_f16 v156, v38, s0, v156
	v_pk_fma_f16 v147, v39, s0, v147
	v_pk_fma_f16 v146, v40, s0, v146
	v_pk_fma_f16 v145, v41, s0, v145
	v_pk_fma_f16 v144, v42, s0, v144
	v_pk_fma_f16 v143, v43, s0, v143
	v_pk_fma_f16 v142, v44, s0, v142
	v_pk_fma_f16 v141, v45, s0, v141
	v_pk_fma_f16 v149, v46, s0, v149
	v_pk_fma_f16 v148, v47, s0, v148
	s_waitcnt vmcnt(6)
	v_readlane_b32 s4, v51, 10
	v_readlane_b32 s0, v52, 9
	v_cvt_scalef32_pk_f16_fp4 v32, v16, 1.0
	v_cvt_scalef32_pk_f16_fp4 v33, v16, 1.0 op_sel:[1,0,0]
	v_cvt_scalef32_pk_f16_fp4 v34, v16, 1.0 op_sel:[0,1,0]
	v_cvt_scalef32_pk_f16_fp4 v35, v16, 1.0 op_sel:[1,1,0]
	v_cvt_scalef32_pk_f16_fp4 v36, v17, 1.0
	v_cvt_scalef32_pk_f16_fp4 v37, v17, 1.0 op_sel:[1,0,0]
	v_cvt_scalef32_pk_f16_fp4 v38, v17, 1.0 op_sel:[0,1,0]
	v_cvt_scalef32_pk_f16_fp4 v39, v17, 1.0 op_sel:[1,1,0]
	v_cvt_scalef32_pk_f16_fp4 v40, v18, 1.0
	v_cvt_scalef32_pk_f16_fp4 v41, v18, 1.0 op_sel:[1,0,0]
	v_cvt_scalef32_pk_f16_fp4 v42, v18, 1.0 op_sel:[0,1,0]
	v_cvt_scalef32_pk_f16_fp4 v43, v18, 1.0 op_sel:[1,1,0]
	v_cvt_scalef32_pk_f16_fp4 v44, v19, 1.0
	v_cvt_scalef32_pk_f16_fp4 v45, v19, 1.0 op_sel:[1,0,0]
	v_cvt_scalef32_pk_f16_fp4 v46, v19, 1.0 op_sel:[0,1,0]
	v_cvt_scalef32_pk_f16_fp4 v47, v19, 1.0 op_sel:[1,1,0]
	buffer_load_dwordx4 v[12:15], v115, s[12:15], s4 offen
	v_pk_fma_f16 v139, v32, s0, v139
	v_pk_fma_f16 v138, v33, s0, v138
	v_pk_fma_f16 v136, v34, s0, v136
	v_pk_fma_f16 v135, v35, s0, v135
	v_pk_fma_f16 v134, v36, s0, v134
	v_pk_fma_f16 v133, v37, s0, v133
	v_pk_fma_f16 v132, v38, s0, v132
	v_pk_fma_f16 v131, v39, s0, v131
	v_pk_fma_f16 v130, v40, s0, v130
	v_pk_fma_f16 v129, v41, s0, v129
	v_pk_fma_f16 v128, v42, s0, v128
	v_pk_fma_f16 v127, v43, s0, v127
	v_pk_fma_f16 v126, v44, s0, v126
	v_pk_fma_f16 v114, v45, s0, v114
	v_pk_fma_f16 v140, v46, s0, v140
	v_pk_fma_f16 v137, v47, s0, v137
	s_waitcnt vmcnt(6)
	v_readlane_b32 s4, v48, 11
	v_readlane_b32 s0, v53, 9
	v_cvt_scalef32_pk_f16_fp4 v32, v20, 1.0
	v_cvt_scalef32_pk_f16_fp4 v33, v20, 1.0 op_sel:[1,0,0]
	v_cvt_scalef32_pk_f16_fp4 v34, v20, 1.0 op_sel:[0,1,0]
	v_cvt_scalef32_pk_f16_fp4 v35, v20, 1.0 op_sel:[1,1,0]
	v_cvt_scalef32_pk_f16_fp4 v36, v21, 1.0
	v_cvt_scalef32_pk_f16_fp4 v37, v21, 1.0 op_sel:[1,0,0]
	v_cvt_scalef32_pk_f16_fp4 v38, v21, 1.0 op_sel:[0,1,0]
	v_cvt_scalef32_pk_f16_fp4 v39, v21, 1.0 op_sel:[1,1,0]
	v_cvt_scalef32_pk_f16_fp4 v40, v22, 1.0
	v_cvt_scalef32_pk_f16_fp4 v41, v22, 1.0 op_sel:[1,0,0]
	v_cvt_scalef32_pk_f16_fp4 v42, v22, 1.0 op_sel:[0,1,0]
	v_cvt_scalef32_pk_f16_fp4 v43, v22, 1.0 op_sel:[1,1,0]
	v_cvt_scalef32_pk_f16_fp4 v44, v23, 1.0
	v_cvt_scalef32_pk_f16_fp4 v45, v23, 1.0 op_sel:[1,0,0]
	v_cvt_scalef32_pk_f16_fp4 v46, v23, 1.0 op_sel:[0,1,0]
	v_cvt_scalef32_pk_f16_fp4 v47, v23, 1.0 op_sel:[1,1,0]
	buffer_load_dwordx4 v[16:19], v115, s[12:15], s4 offen
	v_pk_fma_f16 v124, v32, s0, v124
	v_pk_fma_f16 v123, v33, s0, v123
	v_pk_fma_f16 v121, v34, s0, v121
	v_pk_fma_f16 v120, v35, s0, v120
	v_pk_fma_f16 v119, v36, s0, v119
	v_pk_fma_f16 v118, v37, s0, v118
	v_pk_fma_f16 v117, v38, s0, v117
	v_pk_fma_f16 v116, v39, s0, v116
	v_pk_fma_f16 v113, v40, s0, v113
	v_pk_fma_f16 v112, v41, s0, v112
	v_pk_fma_f16 v67, v42, s0, v67
	v_pk_fma_f16 v66, v43, s0, v66
	v_pk_fma_f16 v65, v44, s0, v65
	v_pk_fma_f16 v64, v45, s0, v64
	v_pk_fma_f16 v125, v46, s0, v125
	v_pk_fma_f16 v122, v47, s0, v122
	s_waitcnt vmcnt(6)
	v_readlane_b32 s4, v49, 11
	v_readlane_b32 s0, v54, 9
	v_cvt_scalef32_pk_f16_fp4 v32, v24, 1.0
	v_cvt_scalef32_pk_f16_fp4 v33, v24, 1.0 op_sel:[1,0,0]
	v_cvt_scalef32_pk_f16_fp4 v34, v24, 1.0 op_sel:[0,1,0]
	v_cvt_scalef32_pk_f16_fp4 v35, v24, 1.0 op_sel:[1,1,0]
	v_cvt_scalef32_pk_f16_fp4 v36, v25, 1.0
	v_cvt_scalef32_pk_f16_fp4 v37, v25, 1.0 op_sel:[1,0,0]
	v_cvt_scalef32_pk_f16_fp4 v38, v25, 1.0 op_sel:[0,1,0]
	v_cvt_scalef32_pk_f16_fp4 v39, v25, 1.0 op_sel:[1,1,0]
	v_cvt_scalef32_pk_f16_fp4 v40, v26, 1.0
	v_cvt_scalef32_pk_f16_fp4 v41, v26, 1.0 op_sel:[1,0,0]
	v_cvt_scalef32_pk_f16_fp4 v42, v26, 1.0 op_sel:[0,1,0]
	v_cvt_scalef32_pk_f16_fp4 v43, v26, 1.0 op_sel:[1,1,0]
	v_cvt_scalef32_pk_f16_fp4 v44, v27, 1.0
	v_cvt_scalef32_pk_f16_fp4 v45, v27, 1.0 op_sel:[1,0,0]
	v_cvt_scalef32_pk_f16_fp4 v46, v27, 1.0 op_sel:[0,1,0]
	v_cvt_scalef32_pk_f16_fp4 v47, v27, 1.0 op_sel:[1,1,0]
	buffer_load_dwordx4 v[20:23], v115, s[12:15], s4 offen
	v_pk_fma_f16 v74, v32, s0, v74
	v_pk_fma_f16 v73, v33, s0, v73
	v_pk_fma_f16 v71, v34, s0, v71
	v_pk_fma_f16 v70, v35, s0, v70
	v_pk_fma_f16 v69, v36, s0, v69
	v_pk_fma_f16 v68, v37, s0, v68
	v_pk_fma_f16 v63, v38, s0, v63
	v_pk_fma_f16 v62, v39, s0, v62
	v_pk_fma_f16 v61, v40, s0, v61
	v_pk_fma_f16 v60, v41, s0, v60
	v_pk_fma_f16 v59, v42, s0, v59
	v_pk_fma_f16 v58, v43, s0, v58
	v_pk_fma_f16 v57, v44, s0, v57
	v_pk_fma_f16 v56, v45, s0, v56
	v_pk_fma_f16 v75, v46, s0, v75
	v_pk_fma_f16 v72, v47, s0, v72
	s_waitcnt vmcnt(6)
	v_readlane_b32 s4, v50, 11
	v_readlane_b32 s0, v55, 9
	v_cvt_scalef32_pk_f16_fp4 v32, v28, 1.0
	v_cvt_scalef32_pk_f16_fp4 v33, v28, 1.0 op_sel:[1,0,0]
	v_cvt_scalef32_pk_f16_fp4 v34, v28, 1.0 op_sel:[0,1,0]
	v_cvt_scalef32_pk_f16_fp4 v35, v28, 1.0 op_sel:[1,1,0]
	v_cvt_scalef32_pk_f16_fp4 v36, v29, 1.0
	v_cvt_scalef32_pk_f16_fp4 v37, v29, 1.0 op_sel:[1,0,0]
	v_cvt_scalef32_pk_f16_fp4 v38, v29, 1.0 op_sel:[0,1,0]
	v_cvt_scalef32_pk_f16_fp4 v39, v29, 1.0 op_sel:[1,1,0]
	v_cvt_scalef32_pk_f16_fp4 v40, v30, 1.0
	v_cvt_scalef32_pk_f16_fp4 v41, v30, 1.0 op_sel:[1,0,0]
	v_cvt_scalef32_pk_f16_fp4 v42, v30, 1.0 op_sel:[0,1,0]
	v_cvt_scalef32_pk_f16_fp4 v43, v30, 1.0 op_sel:[1,1,0]
	v_cvt_scalef32_pk_f16_fp4 v44, v31, 1.0
	v_cvt_scalef32_pk_f16_fp4 v45, v31, 1.0 op_sel:[1,0,0]
	v_cvt_scalef32_pk_f16_fp4 v46, v31, 1.0 op_sel:[0,1,0]
	v_cvt_scalef32_pk_f16_fp4 v47, v31, 1.0 op_sel:[1,1,0]
	buffer_load_dwordx4 v[24:27], v115, s[12:15], s4 offen
	v_pk_fma_f16 v162, v32, s0, v162
	v_pk_fma_f16 v161, v33, s0, v161
	v_pk_fma_f16 v160, v34, s0, v160
	v_pk_fma_f16 v159, v35, s0, v159
	v_pk_fma_f16 v158, v36, s0, v158
	v_pk_fma_f16 v157, v37, s0, v157
	v_pk_fma_f16 v156, v38, s0, v156
	v_pk_fma_f16 v147, v39, s0, v147
	v_pk_fma_f16 v146, v40, s0, v146
	v_pk_fma_f16 v145, v41, s0, v145
	v_pk_fma_f16 v144, v42, s0, v144
	v_pk_fma_f16 v143, v43, s0, v143
	v_pk_fma_f16 v142, v44, s0, v142
	v_pk_fma_f16 v141, v45, s0, v141
	v_pk_fma_f16 v149, v46, s0, v149
	v_pk_fma_f16 v148, v47, s0, v148
	s_waitcnt vmcnt(6)
	v_readlane_b32 s4, v51, 11
	v_readlane_b32 s0, v52, 10
	v_cvt_scalef32_pk_f16_fp4 v32, v0, 1.0
	v_cvt_scalef32_pk_f16_fp4 v33, v0, 1.0 op_sel:[1,0,0]
	v_cvt_scalef32_pk_f16_fp4 v34, v0, 1.0 op_sel:[0,1,0]
	v_cvt_scalef32_pk_f16_fp4 v35, v0, 1.0 op_sel:[1,1,0]
	v_cvt_scalef32_pk_f16_fp4 v36, v1, 1.0
	v_cvt_scalef32_pk_f16_fp4 v37, v1, 1.0 op_sel:[1,0,0]
	v_cvt_scalef32_pk_f16_fp4 v38, v1, 1.0 op_sel:[0,1,0]
	v_cvt_scalef32_pk_f16_fp4 v39, v1, 1.0 op_sel:[1,1,0]
	v_cvt_scalef32_pk_f16_fp4 v40, v2, 1.0
	v_cvt_scalef32_pk_f16_fp4 v41, v2, 1.0 op_sel:[1,0,0]
	v_cvt_scalef32_pk_f16_fp4 v42, v2, 1.0 op_sel:[0,1,0]
	v_cvt_scalef32_pk_f16_fp4 v43, v2, 1.0 op_sel:[1,1,0]
	v_cvt_scalef32_pk_f16_fp4 v44, v3, 1.0
	v_cvt_scalef32_pk_f16_fp4 v45, v3, 1.0 op_sel:[1,0,0]
	v_cvt_scalef32_pk_f16_fp4 v46, v3, 1.0 op_sel:[0,1,0]
	v_cvt_scalef32_pk_f16_fp4 v47, v3, 1.0 op_sel:[1,1,0]
	buffer_load_dwordx4 v[28:31], v115, s[12:15], s4 offen
	v_pk_fma_f16 v139, v32, s0, v139
	v_pk_fma_f16 v138, v33, s0, v138
	v_pk_fma_f16 v136, v34, s0, v136
	v_pk_fma_f16 v135, v35, s0, v135
	v_pk_fma_f16 v134, v36, s0, v134
	v_pk_fma_f16 v133, v37, s0, v133
	v_pk_fma_f16 v132, v38, s0, v132
	v_pk_fma_f16 v131, v39, s0, v131
	v_pk_fma_f16 v130, v40, s0, v130
	v_pk_fma_f16 v129, v41, s0, v129
	v_pk_fma_f16 v128, v42, s0, v128
	v_pk_fma_f16 v127, v43, s0, v127
	v_pk_fma_f16 v126, v44, s0, v126
	v_pk_fma_f16 v114, v45, s0, v114
	v_pk_fma_f16 v140, v46, s0, v140
	v_pk_fma_f16 v137, v47, s0, v137
	s_waitcnt vmcnt(6)
	v_readlane_b32 s4, v48, 12
	v_readlane_b32 s0, v53, 10
	v_cvt_scalef32_pk_f16_fp4 v32, v4, 1.0
	v_cvt_scalef32_pk_f16_fp4 v33, v4, 1.0 op_sel:[1,0,0]
	v_cvt_scalef32_pk_f16_fp4 v34, v4, 1.0 op_sel:[0,1,0]
	v_cvt_scalef32_pk_f16_fp4 v35, v4, 1.0 op_sel:[1,1,0]
	v_cvt_scalef32_pk_f16_fp4 v36, v5, 1.0
	v_cvt_scalef32_pk_f16_fp4 v37, v5, 1.0 op_sel:[1,0,0]
	v_cvt_scalef32_pk_f16_fp4 v38, v5, 1.0 op_sel:[0,1,0]
	v_cvt_scalef32_pk_f16_fp4 v39, v5, 1.0 op_sel:[1,1,0]
	v_cvt_scalef32_pk_f16_fp4 v40, v6, 1.0
	v_cvt_scalef32_pk_f16_fp4 v41, v6, 1.0 op_sel:[1,0,0]
	v_cvt_scalef32_pk_f16_fp4 v42, v6, 1.0 op_sel:[0,1,0]
	v_cvt_scalef32_pk_f16_fp4 v43, v6, 1.0 op_sel:[1,1,0]
	v_cvt_scalef32_pk_f16_fp4 v44, v7, 1.0
	v_cvt_scalef32_pk_f16_fp4 v45, v7, 1.0 op_sel:[1,0,0]
	v_cvt_scalef32_pk_f16_fp4 v46, v7, 1.0 op_sel:[0,1,0]
	v_cvt_scalef32_pk_f16_fp4 v47, v7, 1.0 op_sel:[1,1,0]
	buffer_load_dwordx4 v[0:3], v115, s[12:15], s4 offen
	v_pk_fma_f16 v124, v32, s0, v124
	v_pk_fma_f16 v123, v33, s0, v123
	v_pk_fma_f16 v121, v34, s0, v121
	v_pk_fma_f16 v120, v35, s0, v120
	v_pk_fma_f16 v119, v36, s0, v119
	v_pk_fma_f16 v118, v37, s0, v118
	v_pk_fma_f16 v117, v38, s0, v117
	v_pk_fma_f16 v116, v39, s0, v116
	v_pk_fma_f16 v113, v40, s0, v113
	v_pk_fma_f16 v112, v41, s0, v112
	v_pk_fma_f16 v67, v42, s0, v67
	v_pk_fma_f16 v66, v43, s0, v66
	v_pk_fma_f16 v65, v44, s0, v65
	v_pk_fma_f16 v64, v45, s0, v64
	v_pk_fma_f16 v125, v46, s0, v125
	v_pk_fma_f16 v122, v47, s0, v122
	s_waitcnt vmcnt(6)
	v_readlane_b32 s4, v49, 12
	v_readlane_b32 s0, v54, 10
	v_cvt_scalef32_pk_f16_fp4 v32, v8, 1.0
	v_cvt_scalef32_pk_f16_fp4 v33, v8, 1.0 op_sel:[1,0,0]
	v_cvt_scalef32_pk_f16_fp4 v34, v8, 1.0 op_sel:[0,1,0]
	v_cvt_scalef32_pk_f16_fp4 v35, v8, 1.0 op_sel:[1,1,0]
	v_cvt_scalef32_pk_f16_fp4 v36, v9, 1.0
	v_cvt_scalef32_pk_f16_fp4 v37, v9, 1.0 op_sel:[1,0,0]
	v_cvt_scalef32_pk_f16_fp4 v38, v9, 1.0 op_sel:[0,1,0]
	v_cvt_scalef32_pk_f16_fp4 v39, v9, 1.0 op_sel:[1,1,0]
	v_cvt_scalef32_pk_f16_fp4 v40, v10, 1.0
	v_cvt_scalef32_pk_f16_fp4 v41, v10, 1.0 op_sel:[1,0,0]
	v_cvt_scalef32_pk_f16_fp4 v42, v10, 1.0 op_sel:[0,1,0]
	v_cvt_scalef32_pk_f16_fp4 v43, v10, 1.0 op_sel:[1,1,0]
	v_cvt_scalef32_pk_f16_fp4 v44, v11, 1.0
	v_cvt_scalef32_pk_f16_fp4 v45, v11, 1.0 op_sel:[1,0,0]
	v_cvt_scalef32_pk_f16_fp4 v46, v11, 1.0 op_sel:[0,1,0]
	v_cvt_scalef32_pk_f16_fp4 v47, v11, 1.0 op_sel:[1,1,0]
	buffer_load_dwordx4 v[4:7], v115, s[12:15], s4 offen
	v_pk_fma_f16 v74, v32, s0, v74
	v_pk_fma_f16 v73, v33, s0, v73
	v_pk_fma_f16 v71, v34, s0, v71
	v_pk_fma_f16 v70, v35, s0, v70
	v_pk_fma_f16 v69, v36, s0, v69
	v_pk_fma_f16 v68, v37, s0, v68
	v_pk_fma_f16 v63, v38, s0, v63
	v_pk_fma_f16 v62, v39, s0, v62
	v_pk_fma_f16 v61, v40, s0, v61
	v_pk_fma_f16 v60, v41, s0, v60
	v_pk_fma_f16 v59, v42, s0, v59
	v_pk_fma_f16 v58, v43, s0, v58
	v_pk_fma_f16 v57, v44, s0, v57
	v_pk_fma_f16 v56, v45, s0, v56
	v_pk_fma_f16 v75, v46, s0, v75
	v_pk_fma_f16 v72, v47, s0, v72
	s_waitcnt vmcnt(6)
	v_readlane_b32 s4, v50, 12
	v_readlane_b32 s0, v55, 10
	v_cvt_scalef32_pk_f16_fp4 v32, v12, 1.0
	v_cvt_scalef32_pk_f16_fp4 v33, v12, 1.0 op_sel:[1,0,0]
	v_cvt_scalef32_pk_f16_fp4 v34, v12, 1.0 op_sel:[0,1,0]
	v_cvt_scalef32_pk_f16_fp4 v35, v12, 1.0 op_sel:[1,1,0]
	v_cvt_scalef32_pk_f16_fp4 v36, v13, 1.0
	v_cvt_scalef32_pk_f16_fp4 v37, v13, 1.0 op_sel:[1,0,0]
	v_cvt_scalef32_pk_f16_fp4 v38, v13, 1.0 op_sel:[0,1,0]
	v_cvt_scalef32_pk_f16_fp4 v39, v13, 1.0 op_sel:[1,1,0]
	v_cvt_scalef32_pk_f16_fp4 v40, v14, 1.0
	v_cvt_scalef32_pk_f16_fp4 v41, v14, 1.0 op_sel:[1,0,0]
	v_cvt_scalef32_pk_f16_fp4 v42, v14, 1.0 op_sel:[0,1,0]
	v_cvt_scalef32_pk_f16_fp4 v43, v14, 1.0 op_sel:[1,1,0]
	v_cvt_scalef32_pk_f16_fp4 v44, v15, 1.0
	v_cvt_scalef32_pk_f16_fp4 v45, v15, 1.0 op_sel:[1,0,0]
	v_cvt_scalef32_pk_f16_fp4 v46, v15, 1.0 op_sel:[0,1,0]
	v_cvt_scalef32_pk_f16_fp4 v47, v15, 1.0 op_sel:[1,1,0]
	buffer_load_dwordx4 v[8:11], v115, s[12:15], s4 offen
	v_pk_fma_f16 v162, v32, s0, v162
	v_pk_fma_f16 v161, v33, s0, v161
	v_pk_fma_f16 v160, v34, s0, v160
	v_pk_fma_f16 v159, v35, s0, v159
	v_pk_fma_f16 v158, v36, s0, v158
	v_pk_fma_f16 v157, v37, s0, v157
	v_pk_fma_f16 v156, v38, s0, v156
	v_pk_fma_f16 v147, v39, s0, v147
	v_pk_fma_f16 v146, v40, s0, v146
	v_pk_fma_f16 v145, v41, s0, v145
	v_pk_fma_f16 v144, v42, s0, v144
	v_pk_fma_f16 v143, v43, s0, v143
	v_pk_fma_f16 v142, v44, s0, v142
	v_pk_fma_f16 v141, v45, s0, v141
	v_pk_fma_f16 v149, v46, s0, v149
	v_pk_fma_f16 v148, v47, s0, v148
	s_waitcnt vmcnt(6)
	v_readlane_b32 s4, v51, 12
	v_readlane_b32 s0, v52, 11
	v_cvt_scalef32_pk_f16_fp4 v32, v16, 1.0
	v_cvt_scalef32_pk_f16_fp4 v33, v16, 1.0 op_sel:[1,0,0]
	v_cvt_scalef32_pk_f16_fp4 v34, v16, 1.0 op_sel:[0,1,0]
	v_cvt_scalef32_pk_f16_fp4 v35, v16, 1.0 op_sel:[1,1,0]
	v_cvt_scalef32_pk_f16_fp4 v36, v17, 1.0
	v_cvt_scalef32_pk_f16_fp4 v37, v17, 1.0 op_sel:[1,0,0]
	v_cvt_scalef32_pk_f16_fp4 v38, v17, 1.0 op_sel:[0,1,0]
	v_cvt_scalef32_pk_f16_fp4 v39, v17, 1.0 op_sel:[1,1,0]
	v_cvt_scalef32_pk_f16_fp4 v40, v18, 1.0
	v_cvt_scalef32_pk_f16_fp4 v41, v18, 1.0 op_sel:[1,0,0]
	v_cvt_scalef32_pk_f16_fp4 v42, v18, 1.0 op_sel:[0,1,0]
	v_cvt_scalef32_pk_f16_fp4 v43, v18, 1.0 op_sel:[1,1,0]
	v_cvt_scalef32_pk_f16_fp4 v44, v19, 1.0
	v_cvt_scalef32_pk_f16_fp4 v45, v19, 1.0 op_sel:[1,0,0]
	v_cvt_scalef32_pk_f16_fp4 v46, v19, 1.0 op_sel:[0,1,0]
	v_cvt_scalef32_pk_f16_fp4 v47, v19, 1.0 op_sel:[1,1,0]
	buffer_load_dwordx4 v[12:15], v115, s[12:15], s4 offen
	v_pk_fma_f16 v139, v32, s0, v139
	v_pk_fma_f16 v138, v33, s0, v138
	v_pk_fma_f16 v136, v34, s0, v136
	v_pk_fma_f16 v135, v35, s0, v135
	v_pk_fma_f16 v134, v36, s0, v134
	v_pk_fma_f16 v133, v37, s0, v133
	v_pk_fma_f16 v132, v38, s0, v132
	v_pk_fma_f16 v131, v39, s0, v131
	v_pk_fma_f16 v130, v40, s0, v130
	v_pk_fma_f16 v129, v41, s0, v129
	v_pk_fma_f16 v128, v42, s0, v128
	v_pk_fma_f16 v127, v43, s0, v127
	v_pk_fma_f16 v126, v44, s0, v126
	v_pk_fma_f16 v114, v45, s0, v114
	v_pk_fma_f16 v140, v46, s0, v140
	v_pk_fma_f16 v137, v47, s0, v137
	s_waitcnt vmcnt(6)
	v_readlane_b32 s4, v48, 13
	v_readlane_b32 s0, v53, 11
	v_cvt_scalef32_pk_f16_fp4 v32, v20, 1.0
	v_cvt_scalef32_pk_f16_fp4 v33, v20, 1.0 op_sel:[1,0,0]
	v_cvt_scalef32_pk_f16_fp4 v34, v20, 1.0 op_sel:[0,1,0]
	v_cvt_scalef32_pk_f16_fp4 v35, v20, 1.0 op_sel:[1,1,0]
	v_cvt_scalef32_pk_f16_fp4 v36, v21, 1.0
	v_cvt_scalef32_pk_f16_fp4 v37, v21, 1.0 op_sel:[1,0,0]
	v_cvt_scalef32_pk_f16_fp4 v38, v21, 1.0 op_sel:[0,1,0]
	v_cvt_scalef32_pk_f16_fp4 v39, v21, 1.0 op_sel:[1,1,0]
	v_cvt_scalef32_pk_f16_fp4 v40, v22, 1.0
	v_cvt_scalef32_pk_f16_fp4 v41, v22, 1.0 op_sel:[1,0,0]
	v_cvt_scalef32_pk_f16_fp4 v42, v22, 1.0 op_sel:[0,1,0]
	v_cvt_scalef32_pk_f16_fp4 v43, v22, 1.0 op_sel:[1,1,0]
	v_cvt_scalef32_pk_f16_fp4 v44, v23, 1.0
	v_cvt_scalef32_pk_f16_fp4 v45, v23, 1.0 op_sel:[1,0,0]
	v_cvt_scalef32_pk_f16_fp4 v46, v23, 1.0 op_sel:[0,1,0]
	v_cvt_scalef32_pk_f16_fp4 v47, v23, 1.0 op_sel:[1,1,0]
	buffer_load_dwordx4 v[16:19], v115, s[12:15], s4 offen
	v_pk_fma_f16 v124, v32, s0, v124
	v_pk_fma_f16 v123, v33, s0, v123
	v_pk_fma_f16 v121, v34, s0, v121
	v_pk_fma_f16 v120, v35, s0, v120
	v_pk_fma_f16 v119, v36, s0, v119
	v_pk_fma_f16 v118, v37, s0, v118
	v_pk_fma_f16 v117, v38, s0, v117
	v_pk_fma_f16 v116, v39, s0, v116
	v_pk_fma_f16 v113, v40, s0, v113
	v_pk_fma_f16 v112, v41, s0, v112
	v_pk_fma_f16 v67, v42, s0, v67
	v_pk_fma_f16 v66, v43, s0, v66
	v_pk_fma_f16 v65, v44, s0, v65
	v_pk_fma_f16 v64, v45, s0, v64
	v_pk_fma_f16 v125, v46, s0, v125
	v_pk_fma_f16 v122, v47, s0, v122
	s_waitcnt vmcnt(6)
	v_readlane_b32 s4, v49, 13
	v_readlane_b32 s0, v54, 11
	v_cvt_scalef32_pk_f16_fp4 v32, v24, 1.0
	v_cvt_scalef32_pk_f16_fp4 v33, v24, 1.0 op_sel:[1,0,0]
	v_cvt_scalef32_pk_f16_fp4 v34, v24, 1.0 op_sel:[0,1,0]
	v_cvt_scalef32_pk_f16_fp4 v35, v24, 1.0 op_sel:[1,1,0]
	v_cvt_scalef32_pk_f16_fp4 v36, v25, 1.0
	v_cvt_scalef32_pk_f16_fp4 v37, v25, 1.0 op_sel:[1,0,0]
	v_cvt_scalef32_pk_f16_fp4 v38, v25, 1.0 op_sel:[0,1,0]
	v_cvt_scalef32_pk_f16_fp4 v39, v25, 1.0 op_sel:[1,1,0]
	v_cvt_scalef32_pk_f16_fp4 v40, v26, 1.0
	v_cvt_scalef32_pk_f16_fp4 v41, v26, 1.0 op_sel:[1,0,0]
	v_cvt_scalef32_pk_f16_fp4 v42, v26, 1.0 op_sel:[0,1,0]
	v_cvt_scalef32_pk_f16_fp4 v43, v26, 1.0 op_sel:[1,1,0]
	v_cvt_scalef32_pk_f16_fp4 v44, v27, 1.0
	v_cvt_scalef32_pk_f16_fp4 v45, v27, 1.0 op_sel:[1,0,0]
	v_cvt_scalef32_pk_f16_fp4 v46, v27, 1.0 op_sel:[0,1,0]
	v_cvt_scalef32_pk_f16_fp4 v47, v27, 1.0 op_sel:[1,1,0]
	buffer_load_dwordx4 v[20:23], v115, s[12:15], s4 offen
	v_pk_fma_f16 v74, v32, s0, v74
	v_pk_fma_f16 v73, v33, s0, v73
	v_pk_fma_f16 v71, v34, s0, v71
	v_pk_fma_f16 v70, v35, s0, v70
	v_pk_fma_f16 v69, v36, s0, v69
	v_pk_fma_f16 v68, v37, s0, v68
	v_pk_fma_f16 v63, v38, s0, v63
	v_pk_fma_f16 v62, v39, s0, v62
	v_pk_fma_f16 v61, v40, s0, v61
	v_pk_fma_f16 v60, v41, s0, v60
	v_pk_fma_f16 v59, v42, s0, v59
	v_pk_fma_f16 v58, v43, s0, v58
	v_pk_fma_f16 v57, v44, s0, v57
	v_pk_fma_f16 v56, v45, s0, v56
	v_pk_fma_f16 v75, v46, s0, v75
	v_pk_fma_f16 v72, v47, s0, v72
	s_waitcnt vmcnt(6)
	v_readlane_b32 s4, v50, 13
	v_readlane_b32 s0, v55, 11
	v_cvt_scalef32_pk_f16_fp4 v32, v28, 1.0
	v_cvt_scalef32_pk_f16_fp4 v33, v28, 1.0 op_sel:[1,0,0]
	v_cvt_scalef32_pk_f16_fp4 v34, v28, 1.0 op_sel:[0,1,0]
	v_cvt_scalef32_pk_f16_fp4 v35, v28, 1.0 op_sel:[1,1,0]
	v_cvt_scalef32_pk_f16_fp4 v36, v29, 1.0
	v_cvt_scalef32_pk_f16_fp4 v37, v29, 1.0 op_sel:[1,0,0]
	v_cvt_scalef32_pk_f16_fp4 v38, v29, 1.0 op_sel:[0,1,0]
	v_cvt_scalef32_pk_f16_fp4 v39, v29, 1.0 op_sel:[1,1,0]
	v_cvt_scalef32_pk_f16_fp4 v40, v30, 1.0
	v_cvt_scalef32_pk_f16_fp4 v41, v30, 1.0 op_sel:[1,0,0]
	v_cvt_scalef32_pk_f16_fp4 v42, v30, 1.0 op_sel:[0,1,0]
	v_cvt_scalef32_pk_f16_fp4 v43, v30, 1.0 op_sel:[1,1,0]
	v_cvt_scalef32_pk_f16_fp4 v44, v31, 1.0
	v_cvt_scalef32_pk_f16_fp4 v45, v31, 1.0 op_sel:[1,0,0]
	v_cvt_scalef32_pk_f16_fp4 v46, v31, 1.0 op_sel:[0,1,0]
	v_cvt_scalef32_pk_f16_fp4 v47, v31, 1.0 op_sel:[1,1,0]
	buffer_load_dwordx4 v[24:27], v115, s[12:15], s4 offen
	v_pk_fma_f16 v162, v32, s0, v162
	v_pk_fma_f16 v161, v33, s0, v161
	v_pk_fma_f16 v160, v34, s0, v160
	v_pk_fma_f16 v159, v35, s0, v159
	v_pk_fma_f16 v158, v36, s0, v158
	v_pk_fma_f16 v157, v37, s0, v157
	v_pk_fma_f16 v156, v38, s0, v156
	v_pk_fma_f16 v147, v39, s0, v147
	v_pk_fma_f16 v146, v40, s0, v146
	v_pk_fma_f16 v145, v41, s0, v145
	v_pk_fma_f16 v144, v42, s0, v144
	v_pk_fma_f16 v143, v43, s0, v143
	v_pk_fma_f16 v142, v44, s0, v142
	v_pk_fma_f16 v141, v45, s0, v141
	v_pk_fma_f16 v149, v46, s0, v149
	v_pk_fma_f16 v148, v47, s0, v148
	s_waitcnt vmcnt(6)
	v_readlane_b32 s4, v51, 13
	v_readlane_b32 s0, v52, 12
	v_cvt_scalef32_pk_f16_fp4 v32, v0, 1.0
	v_cvt_scalef32_pk_f16_fp4 v33, v0, 1.0 op_sel:[1,0,0]
	v_cvt_scalef32_pk_f16_fp4 v34, v0, 1.0 op_sel:[0,1,0]
	v_cvt_scalef32_pk_f16_fp4 v35, v0, 1.0 op_sel:[1,1,0]
	v_cvt_scalef32_pk_f16_fp4 v36, v1, 1.0
	v_cvt_scalef32_pk_f16_fp4 v37, v1, 1.0 op_sel:[1,0,0]
	v_cvt_scalef32_pk_f16_fp4 v38, v1, 1.0 op_sel:[0,1,0]
	v_cvt_scalef32_pk_f16_fp4 v39, v1, 1.0 op_sel:[1,1,0]
	v_cvt_scalef32_pk_f16_fp4 v40, v2, 1.0
	v_cvt_scalef32_pk_f16_fp4 v41, v2, 1.0 op_sel:[1,0,0]
	v_cvt_scalef32_pk_f16_fp4 v42, v2, 1.0 op_sel:[0,1,0]
	v_cvt_scalef32_pk_f16_fp4 v43, v2, 1.0 op_sel:[1,1,0]
	v_cvt_scalef32_pk_f16_fp4 v44, v3, 1.0
	v_cvt_scalef32_pk_f16_fp4 v45, v3, 1.0 op_sel:[1,0,0]
	v_cvt_scalef32_pk_f16_fp4 v46, v3, 1.0 op_sel:[0,1,0]
	v_cvt_scalef32_pk_f16_fp4 v47, v3, 1.0 op_sel:[1,1,0]
	buffer_load_dwordx4 v[28:31], v115, s[12:15], s4 offen
	v_pk_fma_f16 v139, v32, s0, v139
	v_pk_fma_f16 v138, v33, s0, v138
	v_pk_fma_f16 v136, v34, s0, v136
	v_pk_fma_f16 v135, v35, s0, v135
	v_pk_fma_f16 v134, v36, s0, v134
	v_pk_fma_f16 v133, v37, s0, v133
	v_pk_fma_f16 v132, v38, s0, v132
	v_pk_fma_f16 v131, v39, s0, v131
	v_pk_fma_f16 v130, v40, s0, v130
	v_pk_fma_f16 v129, v41, s0, v129
	v_pk_fma_f16 v128, v42, s0, v128
	v_pk_fma_f16 v127, v43, s0, v127
	v_pk_fma_f16 v126, v44, s0, v126
	v_pk_fma_f16 v114, v45, s0, v114
	v_pk_fma_f16 v140, v46, s0, v140
	v_pk_fma_f16 v137, v47, s0, v137
	s_waitcnt vmcnt(6)
	v_readlane_b32 s4, v48, 14
	v_readlane_b32 s0, v53, 12
	v_cvt_scalef32_pk_f16_fp4 v32, v4, 1.0
	v_cvt_scalef32_pk_f16_fp4 v33, v4, 1.0 op_sel:[1,0,0]
	v_cvt_scalef32_pk_f16_fp4 v34, v4, 1.0 op_sel:[0,1,0]
	v_cvt_scalef32_pk_f16_fp4 v35, v4, 1.0 op_sel:[1,1,0]
	v_cvt_scalef32_pk_f16_fp4 v36, v5, 1.0
	v_cvt_scalef32_pk_f16_fp4 v37, v5, 1.0 op_sel:[1,0,0]
	v_cvt_scalef32_pk_f16_fp4 v38, v5, 1.0 op_sel:[0,1,0]
	v_cvt_scalef32_pk_f16_fp4 v39, v5, 1.0 op_sel:[1,1,0]
	v_cvt_scalef32_pk_f16_fp4 v40, v6, 1.0
	v_cvt_scalef32_pk_f16_fp4 v41, v6, 1.0 op_sel:[1,0,0]
	v_cvt_scalef32_pk_f16_fp4 v42, v6, 1.0 op_sel:[0,1,0]
	v_cvt_scalef32_pk_f16_fp4 v43, v6, 1.0 op_sel:[1,1,0]
	v_cvt_scalef32_pk_f16_fp4 v44, v7, 1.0
	v_cvt_scalef32_pk_f16_fp4 v45, v7, 1.0 op_sel:[1,0,0]
	v_cvt_scalef32_pk_f16_fp4 v46, v7, 1.0 op_sel:[0,1,0]
	v_cvt_scalef32_pk_f16_fp4 v47, v7, 1.0 op_sel:[1,1,0]
	buffer_load_dwordx4 v[0:3], v115, s[12:15], s4 offen
	v_pk_fma_f16 v124, v32, s0, v124
	v_pk_fma_f16 v123, v33, s0, v123
	v_pk_fma_f16 v121, v34, s0, v121
	v_pk_fma_f16 v120, v35, s0, v120
	v_pk_fma_f16 v119, v36, s0, v119
	v_pk_fma_f16 v118, v37, s0, v118
	v_pk_fma_f16 v117, v38, s0, v117
	v_pk_fma_f16 v116, v39, s0, v116
	v_pk_fma_f16 v113, v40, s0, v113
	v_pk_fma_f16 v112, v41, s0, v112
	v_pk_fma_f16 v67, v42, s0, v67
	v_pk_fma_f16 v66, v43, s0, v66
	v_pk_fma_f16 v65, v44, s0, v65
	v_pk_fma_f16 v64, v45, s0, v64
	v_pk_fma_f16 v125, v46, s0, v125
	v_pk_fma_f16 v122, v47, s0, v122
	s_waitcnt vmcnt(6)
	v_readlane_b32 s4, v49, 14
	v_readlane_b32 s0, v54, 12
	v_cvt_scalef32_pk_f16_fp4 v32, v8, 1.0
	v_cvt_scalef32_pk_f16_fp4 v33, v8, 1.0 op_sel:[1,0,0]
	v_cvt_scalef32_pk_f16_fp4 v34, v8, 1.0 op_sel:[0,1,0]
	v_cvt_scalef32_pk_f16_fp4 v35, v8, 1.0 op_sel:[1,1,0]
	v_cvt_scalef32_pk_f16_fp4 v36, v9, 1.0
	v_cvt_scalef32_pk_f16_fp4 v37, v9, 1.0 op_sel:[1,0,0]
	v_cvt_scalef32_pk_f16_fp4 v38, v9, 1.0 op_sel:[0,1,0]
	v_cvt_scalef32_pk_f16_fp4 v39, v9, 1.0 op_sel:[1,1,0]
	v_cvt_scalef32_pk_f16_fp4 v40, v10, 1.0
	v_cvt_scalef32_pk_f16_fp4 v41, v10, 1.0 op_sel:[1,0,0]
	v_cvt_scalef32_pk_f16_fp4 v42, v10, 1.0 op_sel:[0,1,0]
	v_cvt_scalef32_pk_f16_fp4 v43, v10, 1.0 op_sel:[1,1,0]
	v_cvt_scalef32_pk_f16_fp4 v44, v11, 1.0
	v_cvt_scalef32_pk_f16_fp4 v45, v11, 1.0 op_sel:[1,0,0]
	v_cvt_scalef32_pk_f16_fp4 v46, v11, 1.0 op_sel:[0,1,0]
	v_cvt_scalef32_pk_f16_fp4 v47, v11, 1.0 op_sel:[1,1,0]
	buffer_load_dwordx4 v[4:7], v115, s[12:15], s4 offen
	v_pk_fma_f16 v74, v32, s0, v74
	v_pk_fma_f16 v73, v33, s0, v73
	v_pk_fma_f16 v71, v34, s0, v71
	v_pk_fma_f16 v70, v35, s0, v70
	v_pk_fma_f16 v69, v36, s0, v69
	v_pk_fma_f16 v68, v37, s0, v68
	v_pk_fma_f16 v63, v38, s0, v63
	v_pk_fma_f16 v62, v39, s0, v62
	v_pk_fma_f16 v61, v40, s0, v61
	v_pk_fma_f16 v60, v41, s0, v60
	v_pk_fma_f16 v59, v42, s0, v59
	v_pk_fma_f16 v58, v43, s0, v58
	v_pk_fma_f16 v57, v44, s0, v57
	v_pk_fma_f16 v56, v45, s0, v56
	v_pk_fma_f16 v75, v46, s0, v75
	v_pk_fma_f16 v72, v47, s0, v72
	s_waitcnt vmcnt(6)
	v_readlane_b32 s4, v50, 14
	v_readlane_b32 s0, v55, 12
	v_cvt_scalef32_pk_f16_fp4 v32, v12, 1.0
	v_cvt_scalef32_pk_f16_fp4 v33, v12, 1.0 op_sel:[1,0,0]
	v_cvt_scalef32_pk_f16_fp4 v34, v12, 1.0 op_sel:[0,1,0]
	v_cvt_scalef32_pk_f16_fp4 v35, v12, 1.0 op_sel:[1,1,0]
	v_cvt_scalef32_pk_f16_fp4 v36, v13, 1.0
	v_cvt_scalef32_pk_f16_fp4 v37, v13, 1.0 op_sel:[1,0,0]
	v_cvt_scalef32_pk_f16_fp4 v38, v13, 1.0 op_sel:[0,1,0]
	v_cvt_scalef32_pk_f16_fp4 v39, v13, 1.0 op_sel:[1,1,0]
	v_cvt_scalef32_pk_f16_fp4 v40, v14, 1.0
	v_cvt_scalef32_pk_f16_fp4 v41, v14, 1.0 op_sel:[1,0,0]
	v_cvt_scalef32_pk_f16_fp4 v42, v14, 1.0 op_sel:[0,1,0]
	v_cvt_scalef32_pk_f16_fp4 v43, v14, 1.0 op_sel:[1,1,0]
	v_cvt_scalef32_pk_f16_fp4 v44, v15, 1.0
	v_cvt_scalef32_pk_f16_fp4 v45, v15, 1.0 op_sel:[1,0,0]
	v_cvt_scalef32_pk_f16_fp4 v46, v15, 1.0 op_sel:[0,1,0]
	v_cvt_scalef32_pk_f16_fp4 v47, v15, 1.0 op_sel:[1,1,0]
	buffer_load_dwordx4 v[8:11], v115, s[12:15], s4 offen
	v_pk_fma_f16 v162, v32, s0, v162
	v_pk_fma_f16 v161, v33, s0, v161
	v_pk_fma_f16 v160, v34, s0, v160
	v_pk_fma_f16 v159, v35, s0, v159
	v_pk_fma_f16 v158, v36, s0, v158
	v_pk_fma_f16 v157, v37, s0, v157
	v_pk_fma_f16 v156, v38, s0, v156
	v_pk_fma_f16 v147, v39, s0, v147
	v_pk_fma_f16 v146, v40, s0, v146
	v_pk_fma_f16 v145, v41, s0, v145
	v_pk_fma_f16 v144, v42, s0, v144
	v_pk_fma_f16 v143, v43, s0, v143
	v_pk_fma_f16 v142, v44, s0, v142
	v_pk_fma_f16 v141, v45, s0, v141
	v_pk_fma_f16 v149, v46, s0, v149
	v_pk_fma_f16 v148, v47, s0, v148
	s_waitcnt vmcnt(6)
	v_readlane_b32 s4, v51, 14
	v_readlane_b32 s0, v52, 13
	v_cvt_scalef32_pk_f16_fp4 v32, v16, 1.0
	v_cvt_scalef32_pk_f16_fp4 v33, v16, 1.0 op_sel:[1,0,0]
	v_cvt_scalef32_pk_f16_fp4 v34, v16, 1.0 op_sel:[0,1,0]
	v_cvt_scalef32_pk_f16_fp4 v35, v16, 1.0 op_sel:[1,1,0]
	v_cvt_scalef32_pk_f16_fp4 v36, v17, 1.0
	v_cvt_scalef32_pk_f16_fp4 v37, v17, 1.0 op_sel:[1,0,0]
	v_cvt_scalef32_pk_f16_fp4 v38, v17, 1.0 op_sel:[0,1,0]
	v_cvt_scalef32_pk_f16_fp4 v39, v17, 1.0 op_sel:[1,1,0]
	v_cvt_scalef32_pk_f16_fp4 v40, v18, 1.0
	v_cvt_scalef32_pk_f16_fp4 v41, v18, 1.0 op_sel:[1,0,0]
	v_cvt_scalef32_pk_f16_fp4 v42, v18, 1.0 op_sel:[0,1,0]
	v_cvt_scalef32_pk_f16_fp4 v43, v18, 1.0 op_sel:[1,1,0]
	v_cvt_scalef32_pk_f16_fp4 v44, v19, 1.0
	v_cvt_scalef32_pk_f16_fp4 v45, v19, 1.0 op_sel:[1,0,0]
	v_cvt_scalef32_pk_f16_fp4 v46, v19, 1.0 op_sel:[0,1,0]
	v_cvt_scalef32_pk_f16_fp4 v47, v19, 1.0 op_sel:[1,1,0]
	buffer_load_dwordx4 v[12:15], v115, s[12:15], s4 offen
	v_pk_fma_f16 v139, v32, s0, v139
	v_pk_fma_f16 v138, v33, s0, v138
	v_pk_fma_f16 v136, v34, s0, v136
	v_pk_fma_f16 v135, v35, s0, v135
	v_pk_fma_f16 v134, v36, s0, v134
	v_pk_fma_f16 v133, v37, s0, v133
	v_pk_fma_f16 v132, v38, s0, v132
	v_pk_fma_f16 v131, v39, s0, v131
	v_pk_fma_f16 v130, v40, s0, v130
	v_pk_fma_f16 v129, v41, s0, v129
	v_pk_fma_f16 v128, v42, s0, v128
	v_pk_fma_f16 v127, v43, s0, v127
	v_pk_fma_f16 v126, v44, s0, v126
	v_pk_fma_f16 v114, v45, s0, v114
	v_pk_fma_f16 v140, v46, s0, v140
	v_pk_fma_f16 v137, v47, s0, v137
	s_waitcnt vmcnt(6)
	v_readlane_b32 s4, v48, 15
	v_readlane_b32 s0, v53, 13
	v_cvt_scalef32_pk_f16_fp4 v32, v20, 1.0
	v_cvt_scalef32_pk_f16_fp4 v33, v20, 1.0 op_sel:[1,0,0]
	v_cvt_scalef32_pk_f16_fp4 v34, v20, 1.0 op_sel:[0,1,0]
	v_cvt_scalef32_pk_f16_fp4 v35, v20, 1.0 op_sel:[1,1,0]
	v_cvt_scalef32_pk_f16_fp4 v36, v21, 1.0
	v_cvt_scalef32_pk_f16_fp4 v37, v21, 1.0 op_sel:[1,0,0]
	v_cvt_scalef32_pk_f16_fp4 v38, v21, 1.0 op_sel:[0,1,0]
	v_cvt_scalef32_pk_f16_fp4 v39, v21, 1.0 op_sel:[1,1,0]
	v_cvt_scalef32_pk_f16_fp4 v40, v22, 1.0
	v_cvt_scalef32_pk_f16_fp4 v41, v22, 1.0 op_sel:[1,0,0]
	v_cvt_scalef32_pk_f16_fp4 v42, v22, 1.0 op_sel:[0,1,0]
	v_cvt_scalef32_pk_f16_fp4 v43, v22, 1.0 op_sel:[1,1,0]
	v_cvt_scalef32_pk_f16_fp4 v44, v23, 1.0
	v_cvt_scalef32_pk_f16_fp4 v45, v23, 1.0 op_sel:[1,0,0]
	v_cvt_scalef32_pk_f16_fp4 v46, v23, 1.0 op_sel:[0,1,0]
	v_cvt_scalef32_pk_f16_fp4 v47, v23, 1.0 op_sel:[1,1,0]
	buffer_load_dwordx4 v[16:19], v115, s[12:15], s4 offen
	v_pk_fma_f16 v124, v32, s0, v124
	v_pk_fma_f16 v123, v33, s0, v123
	v_pk_fma_f16 v121, v34, s0, v121
	v_pk_fma_f16 v120, v35, s0, v120
	v_pk_fma_f16 v119, v36, s0, v119
	v_pk_fma_f16 v118, v37, s0, v118
	v_pk_fma_f16 v117, v38, s0, v117
	v_pk_fma_f16 v116, v39, s0, v116
	v_pk_fma_f16 v113, v40, s0, v113
	v_pk_fma_f16 v112, v41, s0, v112
	v_pk_fma_f16 v67, v42, s0, v67
	v_pk_fma_f16 v66, v43, s0, v66
	v_pk_fma_f16 v65, v44, s0, v65
	v_pk_fma_f16 v64, v45, s0, v64
	v_pk_fma_f16 v125, v46, s0, v125
	v_pk_fma_f16 v122, v47, s0, v122
	s_waitcnt vmcnt(6)
	v_readlane_b32 s4, v49, 15
	v_readlane_b32 s0, v54, 13
	v_cvt_scalef32_pk_f16_fp4 v32, v24, 1.0
	v_cvt_scalef32_pk_f16_fp4 v33, v24, 1.0 op_sel:[1,0,0]
	v_cvt_scalef32_pk_f16_fp4 v34, v24, 1.0 op_sel:[0,1,0]
	v_cvt_scalef32_pk_f16_fp4 v35, v24, 1.0 op_sel:[1,1,0]
	v_cvt_scalef32_pk_f16_fp4 v36, v25, 1.0
	v_cvt_scalef32_pk_f16_fp4 v37, v25, 1.0 op_sel:[1,0,0]
	v_cvt_scalef32_pk_f16_fp4 v38, v25, 1.0 op_sel:[0,1,0]
	v_cvt_scalef32_pk_f16_fp4 v39, v25, 1.0 op_sel:[1,1,0]
	v_cvt_scalef32_pk_f16_fp4 v40, v26, 1.0
	v_cvt_scalef32_pk_f16_fp4 v41, v26, 1.0 op_sel:[1,0,0]
	v_cvt_scalef32_pk_f16_fp4 v42, v26, 1.0 op_sel:[0,1,0]
	v_cvt_scalef32_pk_f16_fp4 v43, v26, 1.0 op_sel:[1,1,0]
	v_cvt_scalef32_pk_f16_fp4 v44, v27, 1.0
	v_cvt_scalef32_pk_f16_fp4 v45, v27, 1.0 op_sel:[1,0,0]
	v_cvt_scalef32_pk_f16_fp4 v46, v27, 1.0 op_sel:[0,1,0]
	v_cvt_scalef32_pk_f16_fp4 v47, v27, 1.0 op_sel:[1,1,0]
	buffer_load_dwordx4 v[20:23], v115, s[12:15], s4 offen
	v_pk_fma_f16 v74, v32, s0, v74
	v_pk_fma_f16 v73, v33, s0, v73
	v_pk_fma_f16 v71, v34, s0, v71
	v_pk_fma_f16 v70, v35, s0, v70
	v_pk_fma_f16 v69, v36, s0, v69
	v_pk_fma_f16 v68, v37, s0, v68
	v_pk_fma_f16 v63, v38, s0, v63
	v_pk_fma_f16 v62, v39, s0, v62
	v_pk_fma_f16 v61, v40, s0, v61
	v_pk_fma_f16 v60, v41, s0, v60
	v_pk_fma_f16 v59, v42, s0, v59
	v_pk_fma_f16 v58, v43, s0, v58
	v_pk_fma_f16 v57, v44, s0, v57
	v_pk_fma_f16 v56, v45, s0, v56
	v_pk_fma_f16 v75, v46, s0, v75
	v_pk_fma_f16 v72, v47, s0, v72
	s_waitcnt vmcnt(6)
	v_readlane_b32 s4, v50, 15
	v_readlane_b32 s0, v55, 13
	v_cvt_scalef32_pk_f16_fp4 v32, v28, 1.0
	v_cvt_scalef32_pk_f16_fp4 v33, v28, 1.0 op_sel:[1,0,0]
	v_cvt_scalef32_pk_f16_fp4 v34, v28, 1.0 op_sel:[0,1,0]
	v_cvt_scalef32_pk_f16_fp4 v35, v28, 1.0 op_sel:[1,1,0]
	v_cvt_scalef32_pk_f16_fp4 v36, v29, 1.0
	v_cvt_scalef32_pk_f16_fp4 v37, v29, 1.0 op_sel:[1,0,0]
	v_cvt_scalef32_pk_f16_fp4 v38, v29, 1.0 op_sel:[0,1,0]
	v_cvt_scalef32_pk_f16_fp4 v39, v29, 1.0 op_sel:[1,1,0]
	v_cvt_scalef32_pk_f16_fp4 v40, v30, 1.0
	v_cvt_scalef32_pk_f16_fp4 v41, v30, 1.0 op_sel:[1,0,0]
	v_cvt_scalef32_pk_f16_fp4 v42, v30, 1.0 op_sel:[0,1,0]
	v_cvt_scalef32_pk_f16_fp4 v43, v30, 1.0 op_sel:[1,1,0]
	v_cvt_scalef32_pk_f16_fp4 v44, v31, 1.0
	v_cvt_scalef32_pk_f16_fp4 v45, v31, 1.0 op_sel:[1,0,0]
	v_cvt_scalef32_pk_f16_fp4 v46, v31, 1.0 op_sel:[0,1,0]
	v_cvt_scalef32_pk_f16_fp4 v47, v31, 1.0 op_sel:[1,1,0]
	buffer_load_dwordx4 v[24:27], v115, s[12:15], s4 offen
	v_pk_fma_f16 v162, v32, s0, v162
	v_pk_fma_f16 v161, v33, s0, v161
	v_pk_fma_f16 v160, v34, s0, v160
	v_pk_fma_f16 v159, v35, s0, v159
	v_pk_fma_f16 v158, v36, s0, v158
	v_pk_fma_f16 v157, v37, s0, v157
	v_pk_fma_f16 v156, v38, s0, v156
	v_pk_fma_f16 v147, v39, s0, v147
	v_pk_fma_f16 v146, v40, s0, v146
	v_pk_fma_f16 v145, v41, s0, v145
	v_pk_fma_f16 v144, v42, s0, v144
	v_pk_fma_f16 v143, v43, s0, v143
	v_pk_fma_f16 v142, v44, s0, v142
	v_pk_fma_f16 v141, v45, s0, v141
	v_pk_fma_f16 v149, v46, s0, v149
	v_pk_fma_f16 v148, v47, s0, v148
	s_waitcnt vmcnt(6)
	v_readlane_b32 s4, v51, 15
	v_readlane_b32 s0, v52, 14
	v_cvt_scalef32_pk_f16_fp4 v32, v0, 1.0
	v_cvt_scalef32_pk_f16_fp4 v33, v0, 1.0 op_sel:[1,0,0]
	v_cvt_scalef32_pk_f16_fp4 v34, v0, 1.0 op_sel:[0,1,0]
	v_cvt_scalef32_pk_f16_fp4 v35, v0, 1.0 op_sel:[1,1,0]
	v_cvt_scalef32_pk_f16_fp4 v36, v1, 1.0
	v_cvt_scalef32_pk_f16_fp4 v37, v1, 1.0 op_sel:[1,0,0]
	v_cvt_scalef32_pk_f16_fp4 v38, v1, 1.0 op_sel:[0,1,0]
	v_cvt_scalef32_pk_f16_fp4 v39, v1, 1.0 op_sel:[1,1,0]
	v_cvt_scalef32_pk_f16_fp4 v40, v2, 1.0
	v_cvt_scalef32_pk_f16_fp4 v41, v2, 1.0 op_sel:[1,0,0]
	v_cvt_scalef32_pk_f16_fp4 v42, v2, 1.0 op_sel:[0,1,0]
	v_cvt_scalef32_pk_f16_fp4 v43, v2, 1.0 op_sel:[1,1,0]
	v_cvt_scalef32_pk_f16_fp4 v44, v3, 1.0
	v_cvt_scalef32_pk_f16_fp4 v45, v3, 1.0 op_sel:[1,0,0]
	v_cvt_scalef32_pk_f16_fp4 v46, v3, 1.0 op_sel:[0,1,0]
	v_cvt_scalef32_pk_f16_fp4 v47, v3, 1.0 op_sel:[1,1,0]
	buffer_load_dwordx4 v[28:31], v115, s[12:15], s4 offen
	v_pk_fma_f16 v139, v32, s0, v139
	v_pk_fma_f16 v138, v33, s0, v138
	v_pk_fma_f16 v136, v34, s0, v136
	v_pk_fma_f16 v135, v35, s0, v135
	v_pk_fma_f16 v134, v36, s0, v134
	v_pk_fma_f16 v133, v37, s0, v133
	v_pk_fma_f16 v132, v38, s0, v132
	v_pk_fma_f16 v131, v39, s0, v131
	v_pk_fma_f16 v130, v40, s0, v130
	v_pk_fma_f16 v129, v41, s0, v129
	v_pk_fma_f16 v128, v42, s0, v128
	v_pk_fma_f16 v127, v43, s0, v127
	v_pk_fma_f16 v126, v44, s0, v126
	v_pk_fma_f16 v114, v45, s0, v114
	v_pk_fma_f16 v140, v46, s0, v140
	v_pk_fma_f16 v137, v47, s0, v137
	s_waitcnt vmcnt(6)
	v_readlane_b32 s4, v48, 16
	v_readlane_b32 s0, v53, 14
	v_cvt_scalef32_pk_f16_fp4 v32, v4, 1.0
	v_cvt_scalef32_pk_f16_fp4 v33, v4, 1.0 op_sel:[1,0,0]
	v_cvt_scalef32_pk_f16_fp4 v34, v4, 1.0 op_sel:[0,1,0]
	v_cvt_scalef32_pk_f16_fp4 v35, v4, 1.0 op_sel:[1,1,0]
	v_cvt_scalef32_pk_f16_fp4 v36, v5, 1.0
	v_cvt_scalef32_pk_f16_fp4 v37, v5, 1.0 op_sel:[1,0,0]
	v_cvt_scalef32_pk_f16_fp4 v38, v5, 1.0 op_sel:[0,1,0]
	v_cvt_scalef32_pk_f16_fp4 v39, v5, 1.0 op_sel:[1,1,0]
	v_cvt_scalef32_pk_f16_fp4 v40, v6, 1.0
	v_cvt_scalef32_pk_f16_fp4 v41, v6, 1.0 op_sel:[1,0,0]
	v_cvt_scalef32_pk_f16_fp4 v42, v6, 1.0 op_sel:[0,1,0]
	v_cvt_scalef32_pk_f16_fp4 v43, v6, 1.0 op_sel:[1,1,0]
	v_cvt_scalef32_pk_f16_fp4 v44, v7, 1.0
	v_cvt_scalef32_pk_f16_fp4 v45, v7, 1.0 op_sel:[1,0,0]
	v_cvt_scalef32_pk_f16_fp4 v46, v7, 1.0 op_sel:[0,1,0]
	v_cvt_scalef32_pk_f16_fp4 v47, v7, 1.0 op_sel:[1,1,0]
	buffer_load_dwordx4 v[0:3], v115, s[12:15], s4 offen
	v_pk_fma_f16 v124, v32, s0, v124
	v_pk_fma_f16 v123, v33, s0, v123
	v_pk_fma_f16 v121, v34, s0, v121
	v_pk_fma_f16 v120, v35, s0, v120
	v_pk_fma_f16 v119, v36, s0, v119
	v_pk_fma_f16 v118, v37, s0, v118
	v_pk_fma_f16 v117, v38, s0, v117
	v_pk_fma_f16 v116, v39, s0, v116
	v_pk_fma_f16 v113, v40, s0, v113
	v_pk_fma_f16 v112, v41, s0, v112
	v_pk_fma_f16 v67, v42, s0, v67
	v_pk_fma_f16 v66, v43, s0, v66
	v_pk_fma_f16 v65, v44, s0, v65
	v_pk_fma_f16 v64, v45, s0, v64
	v_pk_fma_f16 v125, v46, s0, v125
	v_pk_fma_f16 v122, v47, s0, v122
	s_waitcnt vmcnt(6)
	v_readlane_b32 s4, v49, 16
	v_readlane_b32 s0, v54, 14
	v_cvt_scalef32_pk_f16_fp4 v32, v8, 1.0
	v_cvt_scalef32_pk_f16_fp4 v33, v8, 1.0 op_sel:[1,0,0]
	v_cvt_scalef32_pk_f16_fp4 v34, v8, 1.0 op_sel:[0,1,0]
	v_cvt_scalef32_pk_f16_fp4 v35, v8, 1.0 op_sel:[1,1,0]
	v_cvt_scalef32_pk_f16_fp4 v36, v9, 1.0
	v_cvt_scalef32_pk_f16_fp4 v37, v9, 1.0 op_sel:[1,0,0]
	v_cvt_scalef32_pk_f16_fp4 v38, v9, 1.0 op_sel:[0,1,0]
	v_cvt_scalef32_pk_f16_fp4 v39, v9, 1.0 op_sel:[1,1,0]
	v_cvt_scalef32_pk_f16_fp4 v40, v10, 1.0
	v_cvt_scalef32_pk_f16_fp4 v41, v10, 1.0 op_sel:[1,0,0]
	v_cvt_scalef32_pk_f16_fp4 v42, v10, 1.0 op_sel:[0,1,0]
	v_cvt_scalef32_pk_f16_fp4 v43, v10, 1.0 op_sel:[1,1,0]
	v_cvt_scalef32_pk_f16_fp4 v44, v11, 1.0
	v_cvt_scalef32_pk_f16_fp4 v45, v11, 1.0 op_sel:[1,0,0]
	v_cvt_scalef32_pk_f16_fp4 v46, v11, 1.0 op_sel:[0,1,0]
	v_cvt_scalef32_pk_f16_fp4 v47, v11, 1.0 op_sel:[1,1,0]
	buffer_load_dwordx4 v[4:7], v115, s[12:15], s4 offen
	v_pk_fma_f16 v74, v32, s0, v74
	v_pk_fma_f16 v73, v33, s0, v73
	v_pk_fma_f16 v71, v34, s0, v71
	v_pk_fma_f16 v70, v35, s0, v70
	v_pk_fma_f16 v69, v36, s0, v69
	v_pk_fma_f16 v68, v37, s0, v68
	v_pk_fma_f16 v63, v38, s0, v63
	v_pk_fma_f16 v62, v39, s0, v62
	v_pk_fma_f16 v61, v40, s0, v61
	v_pk_fma_f16 v60, v41, s0, v60
	v_pk_fma_f16 v59, v42, s0, v59
	v_pk_fma_f16 v58, v43, s0, v58
	v_pk_fma_f16 v57, v44, s0, v57
	v_pk_fma_f16 v56, v45, s0, v56
	v_pk_fma_f16 v75, v46, s0, v75
	v_pk_fma_f16 v72, v47, s0, v72
	s_waitcnt vmcnt(6)
	v_readlane_b32 s4, v50, 16
	v_readlane_b32 s0, v55, 14
	v_cvt_scalef32_pk_f16_fp4 v32, v12, 1.0
	v_cvt_scalef32_pk_f16_fp4 v33, v12, 1.0 op_sel:[1,0,0]
	v_cvt_scalef32_pk_f16_fp4 v34, v12, 1.0 op_sel:[0,1,0]
	v_cvt_scalef32_pk_f16_fp4 v35, v12, 1.0 op_sel:[1,1,0]
	v_cvt_scalef32_pk_f16_fp4 v36, v13, 1.0
	v_cvt_scalef32_pk_f16_fp4 v37, v13, 1.0 op_sel:[1,0,0]
	v_cvt_scalef32_pk_f16_fp4 v38, v13, 1.0 op_sel:[0,1,0]
	v_cvt_scalef32_pk_f16_fp4 v39, v13, 1.0 op_sel:[1,1,0]
	v_cvt_scalef32_pk_f16_fp4 v40, v14, 1.0
	v_cvt_scalef32_pk_f16_fp4 v41, v14, 1.0 op_sel:[1,0,0]
	v_cvt_scalef32_pk_f16_fp4 v42, v14, 1.0 op_sel:[0,1,0]
	v_cvt_scalef32_pk_f16_fp4 v43, v14, 1.0 op_sel:[1,1,0]
	v_cvt_scalef32_pk_f16_fp4 v44, v15, 1.0
	v_cvt_scalef32_pk_f16_fp4 v45, v15, 1.0 op_sel:[1,0,0]
	v_cvt_scalef32_pk_f16_fp4 v46, v15, 1.0 op_sel:[0,1,0]
	v_cvt_scalef32_pk_f16_fp4 v47, v15, 1.0 op_sel:[1,1,0]
	buffer_load_dwordx4 v[8:11], v115, s[12:15], s4 offen
	v_pk_fma_f16 v162, v32, s0, v162
	v_pk_fma_f16 v161, v33, s0, v161
	v_pk_fma_f16 v160, v34, s0, v160
	v_pk_fma_f16 v159, v35, s0, v159
	v_pk_fma_f16 v158, v36, s0, v158
	v_pk_fma_f16 v157, v37, s0, v157
	v_pk_fma_f16 v156, v38, s0, v156
	v_pk_fma_f16 v147, v39, s0, v147
	v_pk_fma_f16 v146, v40, s0, v146
	v_pk_fma_f16 v145, v41, s0, v145
	v_pk_fma_f16 v144, v42, s0, v144
	v_pk_fma_f16 v143, v43, s0, v143
	v_pk_fma_f16 v142, v44, s0, v142
	v_pk_fma_f16 v141, v45, s0, v141
	v_pk_fma_f16 v149, v46, s0, v149
	v_pk_fma_f16 v148, v47, s0, v148
	s_waitcnt vmcnt(6)
	v_readlane_b32 s4, v51, 16
	v_readlane_b32 s0, v52, 15
	v_cvt_scalef32_pk_f16_fp4 v32, v16, 1.0
	v_cvt_scalef32_pk_f16_fp4 v33, v16, 1.0 op_sel:[1,0,0]
	v_cvt_scalef32_pk_f16_fp4 v34, v16, 1.0 op_sel:[0,1,0]
	v_cvt_scalef32_pk_f16_fp4 v35, v16, 1.0 op_sel:[1,1,0]
	v_cvt_scalef32_pk_f16_fp4 v36, v17, 1.0
	v_cvt_scalef32_pk_f16_fp4 v37, v17, 1.0 op_sel:[1,0,0]
	v_cvt_scalef32_pk_f16_fp4 v38, v17, 1.0 op_sel:[0,1,0]
	v_cvt_scalef32_pk_f16_fp4 v39, v17, 1.0 op_sel:[1,1,0]
	v_cvt_scalef32_pk_f16_fp4 v40, v18, 1.0
	v_cvt_scalef32_pk_f16_fp4 v41, v18, 1.0 op_sel:[1,0,0]
	v_cvt_scalef32_pk_f16_fp4 v42, v18, 1.0 op_sel:[0,1,0]
	v_cvt_scalef32_pk_f16_fp4 v43, v18, 1.0 op_sel:[1,1,0]
	v_cvt_scalef32_pk_f16_fp4 v44, v19, 1.0
	v_cvt_scalef32_pk_f16_fp4 v45, v19, 1.0 op_sel:[1,0,0]
	v_cvt_scalef32_pk_f16_fp4 v46, v19, 1.0 op_sel:[0,1,0]
	v_cvt_scalef32_pk_f16_fp4 v47, v19, 1.0 op_sel:[1,1,0]
	buffer_load_dwordx4 v[12:15], v115, s[12:15], s4 offen
	v_pk_fma_f16 v139, v32, s0, v139
	v_pk_fma_f16 v138, v33, s0, v138
	v_pk_fma_f16 v136, v34, s0, v136
	v_pk_fma_f16 v135, v35, s0, v135
	v_pk_fma_f16 v134, v36, s0, v134
	v_pk_fma_f16 v133, v37, s0, v133
	v_pk_fma_f16 v132, v38, s0, v132
	v_pk_fma_f16 v131, v39, s0, v131
	v_pk_fma_f16 v130, v40, s0, v130
	v_pk_fma_f16 v129, v41, s0, v129
	v_pk_fma_f16 v128, v42, s0, v128
	v_pk_fma_f16 v127, v43, s0, v127
	v_pk_fma_f16 v126, v44, s0, v126
	v_pk_fma_f16 v114, v45, s0, v114
	v_pk_fma_f16 v140, v46, s0, v140
	v_pk_fma_f16 v137, v47, s0, v137
	s_waitcnt vmcnt(6)
	v_readlane_b32 s4, v48, 17
	v_readlane_b32 s0, v53, 15
	v_cvt_scalef32_pk_f16_fp4 v32, v20, 1.0
	v_cvt_scalef32_pk_f16_fp4 v33, v20, 1.0 op_sel:[1,0,0]
	v_cvt_scalef32_pk_f16_fp4 v34, v20, 1.0 op_sel:[0,1,0]
	v_cvt_scalef32_pk_f16_fp4 v35, v20, 1.0 op_sel:[1,1,0]
	v_cvt_scalef32_pk_f16_fp4 v36, v21, 1.0
	v_cvt_scalef32_pk_f16_fp4 v37, v21, 1.0 op_sel:[1,0,0]
	v_cvt_scalef32_pk_f16_fp4 v38, v21, 1.0 op_sel:[0,1,0]
	v_cvt_scalef32_pk_f16_fp4 v39, v21, 1.0 op_sel:[1,1,0]
	v_cvt_scalef32_pk_f16_fp4 v40, v22, 1.0
	v_cvt_scalef32_pk_f16_fp4 v41, v22, 1.0 op_sel:[1,0,0]
	v_cvt_scalef32_pk_f16_fp4 v42, v22, 1.0 op_sel:[0,1,0]
	v_cvt_scalef32_pk_f16_fp4 v43, v22, 1.0 op_sel:[1,1,0]
	v_cvt_scalef32_pk_f16_fp4 v44, v23, 1.0
	v_cvt_scalef32_pk_f16_fp4 v45, v23, 1.0 op_sel:[1,0,0]
	v_cvt_scalef32_pk_f16_fp4 v46, v23, 1.0 op_sel:[0,1,0]
	v_cvt_scalef32_pk_f16_fp4 v47, v23, 1.0 op_sel:[1,1,0]
	buffer_load_dwordx4 v[16:19], v115, s[12:15], s4 offen
	v_pk_fma_f16 v124, v32, s0, v124
	v_pk_fma_f16 v123, v33, s0, v123
	v_pk_fma_f16 v121, v34, s0, v121
	v_pk_fma_f16 v120, v35, s0, v120
	v_pk_fma_f16 v119, v36, s0, v119
	v_pk_fma_f16 v118, v37, s0, v118
	v_pk_fma_f16 v117, v38, s0, v117
	v_pk_fma_f16 v116, v39, s0, v116
	v_pk_fma_f16 v113, v40, s0, v113
	v_pk_fma_f16 v112, v41, s0, v112
	v_pk_fma_f16 v67, v42, s0, v67
	v_pk_fma_f16 v66, v43, s0, v66
	v_pk_fma_f16 v65, v44, s0, v65
	v_pk_fma_f16 v64, v45, s0, v64
	v_pk_fma_f16 v125, v46, s0, v125
	v_pk_fma_f16 v122, v47, s0, v122
	s_waitcnt vmcnt(6)
	v_readlane_b32 s4, v49, 17
	v_readlane_b32 s0, v54, 15
	v_cvt_scalef32_pk_f16_fp4 v32, v24, 1.0
	v_cvt_scalef32_pk_f16_fp4 v33, v24, 1.0 op_sel:[1,0,0]
	v_cvt_scalef32_pk_f16_fp4 v34, v24, 1.0 op_sel:[0,1,0]
	v_cvt_scalef32_pk_f16_fp4 v35, v24, 1.0 op_sel:[1,1,0]
	v_cvt_scalef32_pk_f16_fp4 v36, v25, 1.0
	v_cvt_scalef32_pk_f16_fp4 v37, v25, 1.0 op_sel:[1,0,0]
	v_cvt_scalef32_pk_f16_fp4 v38, v25, 1.0 op_sel:[0,1,0]
	v_cvt_scalef32_pk_f16_fp4 v39, v25, 1.0 op_sel:[1,1,0]
	v_cvt_scalef32_pk_f16_fp4 v40, v26, 1.0
	v_cvt_scalef32_pk_f16_fp4 v41, v26, 1.0 op_sel:[1,0,0]
	v_cvt_scalef32_pk_f16_fp4 v42, v26, 1.0 op_sel:[0,1,0]
	v_cvt_scalef32_pk_f16_fp4 v43, v26, 1.0 op_sel:[1,1,0]
	v_cvt_scalef32_pk_f16_fp4 v44, v27, 1.0
	v_cvt_scalef32_pk_f16_fp4 v45, v27, 1.0 op_sel:[1,0,0]
	v_cvt_scalef32_pk_f16_fp4 v46, v27, 1.0 op_sel:[0,1,0]
	v_cvt_scalef32_pk_f16_fp4 v47, v27, 1.0 op_sel:[1,1,0]
	buffer_load_dwordx4 v[20:23], v115, s[12:15], s4 offen
	v_pk_fma_f16 v74, v32, s0, v74
	v_pk_fma_f16 v73, v33, s0, v73
	v_pk_fma_f16 v71, v34, s0, v71
	v_pk_fma_f16 v70, v35, s0, v70
	v_pk_fma_f16 v69, v36, s0, v69
	v_pk_fma_f16 v68, v37, s0, v68
	v_pk_fma_f16 v63, v38, s0, v63
	v_pk_fma_f16 v62, v39, s0, v62
	v_pk_fma_f16 v61, v40, s0, v61
	v_pk_fma_f16 v60, v41, s0, v60
	v_pk_fma_f16 v59, v42, s0, v59
	v_pk_fma_f16 v58, v43, s0, v58
	v_pk_fma_f16 v57, v44, s0, v57
	v_pk_fma_f16 v56, v45, s0, v56
	v_pk_fma_f16 v75, v46, s0, v75
	v_pk_fma_f16 v72, v47, s0, v72
	s_waitcnt vmcnt(6)
	v_readlane_b32 s4, v50, 17
	v_readlane_b32 s0, v55, 15
	v_cvt_scalef32_pk_f16_fp4 v32, v28, 1.0
	v_cvt_scalef32_pk_f16_fp4 v33, v28, 1.0 op_sel:[1,0,0]
	v_cvt_scalef32_pk_f16_fp4 v34, v28, 1.0 op_sel:[0,1,0]
	v_cvt_scalef32_pk_f16_fp4 v35, v28, 1.0 op_sel:[1,1,0]
	v_cvt_scalef32_pk_f16_fp4 v36, v29, 1.0
	v_cvt_scalef32_pk_f16_fp4 v37, v29, 1.0 op_sel:[1,0,0]
	v_cvt_scalef32_pk_f16_fp4 v38, v29, 1.0 op_sel:[0,1,0]
	v_cvt_scalef32_pk_f16_fp4 v39, v29, 1.0 op_sel:[1,1,0]
	v_cvt_scalef32_pk_f16_fp4 v40, v30, 1.0
	v_cvt_scalef32_pk_f16_fp4 v41, v30, 1.0 op_sel:[1,0,0]
	v_cvt_scalef32_pk_f16_fp4 v42, v30, 1.0 op_sel:[0,1,0]
	v_cvt_scalef32_pk_f16_fp4 v43, v30, 1.0 op_sel:[1,1,0]
	v_cvt_scalef32_pk_f16_fp4 v44, v31, 1.0
	v_cvt_scalef32_pk_f16_fp4 v45, v31, 1.0 op_sel:[1,0,0]
	v_cvt_scalef32_pk_f16_fp4 v46, v31, 1.0 op_sel:[0,1,0]
	v_cvt_scalef32_pk_f16_fp4 v47, v31, 1.0 op_sel:[1,1,0]
	buffer_load_dwordx4 v[24:27], v115, s[12:15], s4 offen
	v_pk_fma_f16 v162, v32, s0, v162
	v_pk_fma_f16 v161, v33, s0, v161
	v_pk_fma_f16 v160, v34, s0, v160
	v_pk_fma_f16 v159, v35, s0, v159
	v_pk_fma_f16 v158, v36, s0, v158
	v_pk_fma_f16 v157, v37, s0, v157
	v_pk_fma_f16 v156, v38, s0, v156
	v_pk_fma_f16 v147, v39, s0, v147
	v_pk_fma_f16 v146, v40, s0, v146
	v_pk_fma_f16 v145, v41, s0, v145
	v_pk_fma_f16 v144, v42, s0, v144
	v_pk_fma_f16 v143, v43, s0, v143
	v_pk_fma_f16 v142, v44, s0, v142
	v_pk_fma_f16 v141, v45, s0, v141
	v_pk_fma_f16 v149, v46, s0, v149
	v_pk_fma_f16 v148, v47, s0, v148
	v_add_u32_e32 v111, 64, v111
	s_add_i32 s11, s11, 1
	s_cmp_eq_u32 s11, 8
	s_cbranch_scc0 .Lmy_lblk
	s_waitcnt vmcnt(0) lgkmcnt(0)
	s_movk_i32 s12, 0x1000
	v_lshlrev_b32_e32 v236, 6, v78
	v_add_u32_e32 v237, 0x1000, v236
	global_load_dwordx4 v[172:175], v236, s[16:17] offset:0
	global_load_dwordx4 v[204:207], v236, s[18:19] offset:0
	global_load_dwordx4 v[176:179], v236, s[16:17] offset:16
	global_load_dwordx4 v[208:211], v236, s[18:19] offset:16
	global_load_dwordx4 v[180:183], v236, s[16:17] offset:32
	global_load_dwordx4 v[212:215], v236, s[18:19] offset:32
	global_load_dwordx4 v[184:187], v236, s[16:17] offset:48
	global_load_dwordx4 v[216:219], v236, s[18:19] offset:48
	global_load_dwordx4 v[188:191], v237, s[16:17] offset:0
	global_load_dwordx4 v[220:223], v237, s[18:19] offset:0
	global_load_dwordx4 v[192:195], v237, s[16:17] offset:16
	global_load_dwordx4 v[224:227], v237, s[18:19] offset:16
	global_load_dwordx4 v[196:199], v237, s[16:17] offset:32
	global_load_dwordx4 v[228:231], v237, s[18:19] offset:32
	global_load_dwordx4 v[200:203], v237, s[16:17] offset:48
	global_load_dwordx4 v[232:235], v237, s[18:19] offset:48
	s_lshl_b32 s0, s10, 2
	s_waitcnt vmcnt(11)
	v_mov_b32_e32 v0, v78
	s_or_b32 s10, s0, s22
	s_waitcnt vmcnt(0) lgkmcnt(0)
	s_ashr_i32 s11, s10, 31
	s_waitcnt vmcnt(2)
	v_lshlrev_b32_e32 v42, 4, v0
	v_ashrrev_i32_e32 v43, 31, v42
	s_lshl_b64 s[0:1], s[10:11], 11
	v_lshl_add_u64 v[0:1], s[0:1], 0, v[42:43]
	v_lshlrev_b64 v[0:1], 1, v[0:1]
	v_lshl_add_u64 v[28:29], s[70:71], 0, v[0:1]
	global_load_dwordx4 v[4:7], v[28:29], off offset:2064
	v_lshl_add_u64 v[24:25], s[2:3], 0, v[0:1]
	global_load_dwordx4 v[0:3], v[24:25], off offset:2064
	global_load_dwordx4 v[8:11], v[28:29], off
	global_load_dwordx4 v[12:15], v[24:25], off
	global_load_dwordx4 v[16:19], v[28:29], off offset:16
	global_load_dwordx4 v[20:23], v[24:25], off offset:16
	s_nop 0
	global_load_dwordx4 v[24:27], v[24:25], off offset:2048
	s_nop 0
	global_load_dwordx4 v[28:31], v[28:29], off offset:2048
	v_cvt_f32_f16_sdwa v35, v139 dst_sel:DWORD dst_unused:UNUSED_PAD src0_sel:WORD_1
	v_cvt_f32_f16_e32 v34, v139
	v_cvt_f32_f16_sdwa v41, v136 dst_sel:DWORD dst_unused:UNUSED_PAD src0_sel:WORD_1
	v_cvt_f32_f16_e32 v40, v136
	v_cvt_f32_f16_sdwa v37, v138 dst_sel:DWORD dst_unused:UNUSED_PAD src0_sel:WORD_1
	v_cvt_f32_f16_e32 v36, v138
	s_waitcnt vmcnt(9)
	v_cvt_f32_f16_sdwa v45, v135 dst_sel:DWORD dst_unused:UNUSED_PAD src0_sel:WORD_1
	v_cvt_f32_f16_e32 v44, v135
	v_cvt_f32_f16_sdwa v47, v134 dst_sel:DWORD dst_unused:UNUSED_PAD src0_sel:WORD_1
	v_cvt_f32_f16_e32 v46, v134
	v_cvt_f32_f16_sdwa v49, v133 dst_sel:DWORD dst_unused:UNUSED_PAD src0_sel:WORD_1
	v_cvt_f32_f16_e32 v48, v133
	v_cvt_f32_f16_sdwa v51, v132 dst_sel:DWORD dst_unused:UNUSED_PAD src0_sel:WORD_1
	v_cvt_f32_f16_e32 v50, v132
	v_cvt_f32_f16_sdwa v39, v137 dst_sel:DWORD dst_unused:UNUSED_PAD src0_sel:WORD_1
	v_cvt_f32_f16_e32 v38, v137
	v_cvt_f32_f16_sdwa v33, v140 dst_sel:DWORD dst_unused:UNUSED_PAD src0_sel:WORD_1
	v_cvt_f32_f16_e32 v32, v140
	s_lshl_b64 s[14:15], s[10:11], 13
	s_waitcnt vmcnt(6)
	v_and_b32_e32 v55, 0xffff0000, v2
	v_lshlrev_b32_e32 v54, 16, v2
	v_and_b32_e32 v53, 0xffff0000, v6
	v_lshlrev_b32_e32 v52, 16, v6
	s_waitcnt vmcnt(5)
	v_lshlrev_b32_e32 v104, 16, v8
	v_and_b32_e32 v105, 0xffff0000, v8
	s_waitcnt vmcnt(4)
	v_lshlrev_b32_e32 v106, 16, v12
	v_and_b32_e32 v107, 0xffff0000, v12
	v_and_b32_e32 v109, 0xffff0000, v7
	v_lshlrev_b32_e32 v108, 16, v7
	v_and_b32_e32 v7, 0xffff0000, v3
	v_lshlrev_b32_e32 v6, 16, v3
	v_lshlrev_b32_e32 v2, 16, v10
	v_and_b32_e32 v3, 0xffff0000, v10
	v_lshlrev_b32_e32 v110, 16, v14
	v_and_b32_e32 v111, 0xffff0000, v14
	v_lshlrev_b32_e32 v10, 16, v11
	v_and_b32_e32 v11, 0xffff0000, v11
	v_lshlrev_b32_e32 v14, 16, v15
	v_and_b32_e32 v15, 0xffff0000, v15
	s_waitcnt vmcnt(3)
	v_lshlrev_b32_e32 v132, 16, v16
	v_and_b32_e32 v133, 0xffff0000, v16
	s_waitcnt vmcnt(2)
	v_lshlrev_b32_e32 v134, 16, v20
	v_and_b32_e32 v135, 0xffff0000, v20
	v_lshlrev_b32_e32 v16, 16, v17
	v_and_b32_e32 v17, 0xffff0000, v17
	v_lshlrev_b32_e32 v20, 16, v21
	v_and_b32_e32 v21, 0xffff0000, v21
	v_pk_fma_f32 v[52:53], v[52:53], s[6:7], v[54:55] op_sel_hi:[1,0,1]
	v_pk_fma_f32 v[54:55], v[104:105], s[6:7], v[106:107] op_sel_hi:[1,0,1]
	v_lshlrev_b32_e32 v8, 16, v9
	v_and_b32_e32 v9, 0xffff0000, v9
	v_lshlrev_b32_e32 v12, 16, v13
	v_and_b32_e32 v13, 0xffff0000, v13
	v_pk_fma_f32 v[2:3], v[2:3], s[6:7], v[110:111] op_sel_hi:[1,0,1]
	v_pk_fma_f32 v[10:11], v[10:11], s[6:7], v[14:15] op_sel_hi:[1,0,1]
	v_pk_fma_f32 v[14:15], v[16:17], s[6:7], v[20:21] op_sel_hi:[1,0,1]
	v_pk_add_f32 v[20:21], v[54:55], v[34:35]
	v_pk_fma_f32 v[8:9], v[8:9], s[6:7], v[12:13] op_sel_hi:[1,0,1]
	v_pk_add_f32 v[40:41], v[2:3], v[40:41]
	v_add_f32_e32 v2, 0, v20
	v_pk_add_f32 v[8:9], v[8:9], v[36:37]
	v_add_f32_e32 v2, v21, v2
	v_add_f32_e32 v2, v8, v2
	v_add_f32_e32 v2, v9, v2
	v_add_f32_e32 v2, v40, v2
	v_pk_add_f32 v[10:11], v[10:11], v[44:45]
	v_add_f32_e32 v2, v41, v2
	v_pk_fma_f32 v[12:13], v[132:133], s[6:7], v[134:135] op_sel_hi:[1,0,1]
	v_add_f32_e32 v2, v10, v2
	v_pk_add_f32 v[12:13], v[12:13], v[46:47]
	v_add_f32_e32 v2, v11, v2
	v_add_f32_e32 v2, v12, v2
	v_pk_add_f32 v[14:15], v[14:15], v[48:49]
	v_add_f32_e32 v2, v13, v2
	v_lshlrev_b32_e32 v136, 16, v18
	v_and_b32_e32 v137, 0xffff0000, v18
	v_lshlrev_b32_e32 v138, 16, v22
	v_pk_fma_f32 v[6:7], v[108:109], s[6:7], v[6:7] op_sel_hi:[1,0,1]
	v_add_f32_e32 v2, v14, v2
	v_and_b32_e32 v139, 0xffff0000, v22
	v_pk_add_f32 v[38:39], v[6:7], v[38:39]
	v_add_f32_e32 v6, v15, v2
	v_pk_fma_f32 v[2:3], v[136:137], s[6:7], v[138:139] op_sel_hi:[1,0,1]
	v_and_b32_e32 v7, 0xffff0000, v19
	v_pk_add_f32 v[44:45], v[2:3], v[50:51]
	v_cvt_f32_f16_sdwa v3, v131 dst_sel:DWORD dst_unused:UNUSED_PAD src0_sel:WORD_1
	v_add_f32_e32 v2, v44, v6
	v_add_f32_e32 v22, v45, v2
	v_cvt_f32_f16_e32 v2, v131
	v_lshlrev_b32_e32 v6, 16, v19
	v_lshlrev_b32_e32 v18, 16, v23
	v_and_b32_e32 v19, 0xffff0000, v23
	v_pk_fma_f32 v[6:7], v[6:7], s[6:7], v[18:19] op_sel_hi:[1,0,1]
	v_pk_add_f32 v[16:17], v[52:53], v[32:33]
	v_pk_add_f32 v[18:19], v[6:7], v[2:3]
	v_cvt_f32_f16_sdwa v3, v130 dst_sel:DWORD dst_unused:UNUSED_PAD src0_sel:WORD_1
	v_add_f32_e32 v2, v18, v22
	v_add_f32_e32 v32, v19, v2
	v_cvt_f32_f16_e32 v2, v130
	s_waitcnt vmcnt(0)
	v_lshlrev_b32_e32 v6, 16, v28
	v_and_b32_e32 v7, 0xffff0000, v28
	v_lshlrev_b32_e32 v22, 16, v24
	v_and_b32_e32 v23, 0xffff0000, v24
	v_pk_fma_f32 v[6:7], v[6:7], s[6:7], v[22:23] op_sel_hi:[1,0,1]
	v_lshlrev_b32_e32 v24, 16, v25
	v_pk_add_f32 v[22:23], v[6:7], v[2:3]
	v_cvt_f32_f16_sdwa v3, v129 dst_sel:DWORD dst_unused:UNUSED_PAD src0_sel:WORD_1
	v_add_f32_e32 v2, v22, v32
	v_add_f32_e32 v28, v23, v2
	v_cvt_f32_f16_e32 v2, v129
	v_lshlrev_b32_e32 v6, 16, v29
	v_and_b32_e32 v7, 0xffff0000, v29
	v_and_b32_e32 v25, 0xffff0000, v25
	v_pk_fma_f32 v[6:7], v[6:7], s[6:7], v[24:25] op_sel_hi:[1,0,1]
	v_and_b32_e32 v29, 0xffff0000, v26
	v_pk_add_f32 v[24:25], v[6:7], v[2:3]
	v_cvt_f32_f16_sdwa v3, v128 dst_sel:DWORD dst_unused:UNUSED_PAD src0_sel:WORD_1
	v_add_f32_e32 v2, v24, v28
	v_add_f32_e32 v32, v25, v2
	v_cvt_f32_f16_e32 v2, v128
	v_lshlrev_b32_e32 v6, 16, v30
	v_and_b32_e32 v7, 0xffff0000, v30
	v_lshlrev_b32_e32 v28, 16, v26
	v_pk_fma_f32 v[6:7], v[6:7], s[6:7], v[28:29] op_sel_hi:[1,0,1]
	v_lshlrev_b32_e32 v26, 16, v27
	v_pk_add_f32 v[28:29], v[6:7], v[2:3]
	v_cvt_f32_f16_sdwa v3, v127 dst_sel:DWORD dst_unused:UNUSED_PAD src0_sel:WORD_1
	v_add_f32_e32 v2, v28, v32
	v_add_f32_e32 v30, v29, v2
	v_cvt_f32_f16_e32 v2, v127
	v_lshlrev_b32_e32 v6, 16, v31
	v_and_b32_e32 v7, 0xffff0000, v31
	v_and_b32_e32 v27, 0xffff0000, v27
	v_pk_fma_f32 v[6:7], v[6:7], s[6:7], v[26:27] op_sel_hi:[1,0,1]
	v_and_b32_e32 v31, 0xffff0000, v0
	v_pk_add_f32 v[26:27], v[6:7], v[2:3]
	v_cvt_f32_f16_sdwa v3, v126 dst_sel:DWORD dst_unused:UNUSED_PAD src0_sel:WORD_1
	v_add_f32_e32 v2, v26, v30
	v_add_f32_e32 v32, v27, v2
	v_cvt_f32_f16_e32 v2, v126
	v_lshlrev_b32_e32 v6, 16, v4
	v_and_b32_e32 v7, 0xffff0000, v4
	v_lshlrev_b32_e32 v30, 16, v0
	v_pk_fma_f32 v[6:7], v[6:7], s[6:7], v[30:31] op_sel_hi:[1,0,1]
	v_lshlrev_b32_e32 v4, 16, v5
	v_pk_add_f32 v[30:31], v[6:7], v[2:3]
	v_cvt_f32_f16_sdwa v3, v114 dst_sel:DWORD dst_unused:UNUSED_PAD src0_sel:WORD_1
	v_cvt_f32_f16_e32 v2, v114
	v_add_f32_e32 v0, v30, v32
	v_add_f32_e32 v6, v31, v0
	v_and_b32_e32 v5, 0xffff0000, v5
	v_lshlrev_b32_e32 v0, 16, v1
	v_and_b32_e32 v1, 0xffff0000, v1
	v_pk_fma_f32 v[0:1], v[4:5], s[6:7], v[0:1] op_sel_hi:[1,0,1]
	v_lshlrev_b64 v[36:37], 2, v[42:43]
	v_pk_add_f32 v[46:47], v[0:1], v[2:3]
	v_lshl_add_u64 v[32:33], s[16:17], 0, v[36:37]
	v_add_f32_e32 v0, v46, v6
	v_add_f32_e32 v0, v47, v0
	v_add_f32_e32 v0, v16, v0
	v_add_f32_e32 v0, v17, v0
	v_add_f32_e32 v0, v38, v0
	v_add_f32_e32 v0, v39, v0
	ds_bpermute_b32 v1, v79, v0
	v_lshl_add_u64 v[34:35], s[18:19], 0, v[36:37]
	s_waitcnt lgkmcnt(0)
	v_add_f32_e32 v0, v0, v1
	ds_bpermute_b32 v1, v80, v0
	s_waitcnt lgkmcnt(0)
	v_add_f32_e32 v0, v0, v1
	ds_bpermute_b32 v1, v81, v0
	s_waitcnt lgkmcnt(0)
	v_add_f32_e32 v0, v0, v1
	ds_bpermute_b32 v1, v82, v0
	s_waitcnt lgkmcnt(0)
	v_add_f32_e32 v0, v0, v1
	ds_bpermute_b32 v1, v83, v0
	s_waitcnt lgkmcnt(0)
	v_add_f32_e32 v48, v0, v1
	ds_bpermute_b32 v49, v84, v48
	s_waitcnt lgkmcnt(0)
	v_add_f32_e32 v48, v48, v49
	v_mul_f32_e32 v48, 0x3a000000, v48
	v_pk_add_f32 v[20:21], v[20:21], v[48:49] op_sel_hi:[1,0] neg_lo:[0,1] neg_hi:[0,1]
	v_pk_add_f32 v[8:9], v[8:9], v[48:49] op_sel_hi:[1,0] neg_lo:[0,1] neg_hi:[0,1]
	v_pk_mul_f32 v[50:51], v[20:21], v[20:21]
	v_pk_mul_f32 v[52:53], v[8:9], v[8:9]
	v_add_f32_e32 v50, v50, v51
	v_pk_add_f32 v[40:41], v[40:41], v[48:49] op_sel_hi:[1,0] neg_lo:[0,1] neg_hi:[0,1]
	v_add_f32_e32 v50, v52, v50
	v_pk_mul_f32 v[54:55], v[40:41], v[40:41]
	v_add_f32_e32 v50, v53, v50
	v_pk_add_f32 v[10:11], v[10:11], v[48:49] op_sel_hi:[1,0] neg_lo:[0,1] neg_hi:[0,1]
	v_add_f32_e32 v50, v54, v50
	v_pk_mul_f32 v[104:105], v[10:11], v[10:11]
	v_add_f32_e32 v50, v55, v50
	v_pk_add_f32 v[12:13], v[12:13], v[48:49] op_sel_hi:[1,0] neg_lo:[0,1] neg_hi:[0,1]
	v_add_f32_e32 v50, v104, v50
	v_pk_mul_f32 v[106:107], v[12:13], v[12:13]
	v_add_f32_e32 v50, v105, v50
	v_pk_add_f32 v[14:15], v[14:15], v[48:49] op_sel_hi:[1,0] neg_lo:[0,1] neg_hi:[0,1]
	v_add_f32_e32 v50, v106, v50
	v_pk_mul_f32 v[108:109], v[14:15], v[14:15]
	v_add_f32_e32 v50, v107, v50
	v_pk_add_f32 v[44:45], v[44:45], v[48:49] op_sel_hi:[1,0] neg_lo:[0,1] neg_hi:[0,1]
	v_add_f32_e32 v50, v108, v50
	v_pk_mul_f32 v[110:111], v[44:45], v[44:45]
	v_add_f32_e32 v50, v109, v50
	v_pk_add_f32 v[18:19], v[18:19], v[48:49] op_sel_hi:[1,0] neg_lo:[0,1] neg_hi:[0,1]
	v_add_f32_e32 v50, v110, v50
	v_pk_mul_f32 v[114:115], v[18:19], v[18:19]
	v_add_f32_e32 v50, v111, v50
	v_pk_add_f32 v[22:23], v[22:23], v[48:49] op_sel_hi:[1,0] neg_lo:[0,1] neg_hi:[0,1]
	v_add_f32_e32 v50, v114, v50
	v_pk_mul_f32 v[126:127], v[22:23], v[22:23]
	v_add_f32_e32 v50, v115, v50
	v_pk_add_f32 v[24:25], v[24:25], v[48:49] op_sel_hi:[1,0] neg_lo:[0,1] neg_hi:[0,1]
	v_add_f32_e32 v50, v126, v50
	v_pk_mul_f32 v[128:129], v[24:25], v[24:25]
	v_add_f32_e32 v50, v127, v50
	v_pk_add_f32 v[28:29], v[28:29], v[48:49] op_sel_hi:[1,0] neg_lo:[0,1] neg_hi:[0,1]
	v_add_f32_e32 v50, v128, v50
	v_pk_mul_f32 v[130:131], v[28:29], v[28:29]
	v_add_f32_e32 v50, v129, v50
	v_pk_add_f32 v[26:27], v[26:27], v[48:49] op_sel_hi:[1,0] neg_lo:[0,1] neg_hi:[0,1]
	v_add_f32_e32 v50, v130, v50
	v_pk_mul_f32 v[132:133], v[26:27], v[26:27]
	v_add_f32_e32 v50, v131, v50
	v_pk_add_f32 v[30:31], v[30:31], v[48:49] op_sel_hi:[1,0] neg_lo:[0,1] neg_hi:[0,1]
	v_add_f32_e32 v50, v132, v50
	v_pk_mul_f32 v[134:135], v[30:31], v[30:31]
	v_add_f32_e32 v50, v133, v50
	v_pk_add_f32 v[46:47], v[46:47], v[48:49] op_sel_hi:[1,0] neg_lo:[0,1] neg_hi:[0,1]
	v_add_f32_e32 v50, v134, v50
	v_pk_mul_f32 v[136:137], v[46:47], v[46:47]
	v_add_f32_e32 v50, v135, v50
	v_pk_add_f32 v[16:17], v[16:17], v[48:49] op_sel_hi:[1,0] neg_lo:[0,1] neg_hi:[0,1]
	v_add_f32_e32 v50, v136, v50
	v_pk_add_f32 v[138:139], v[38:39], v[48:49] op_sel_hi:[1,0] neg_lo:[0,1] neg_hi:[0,1]
	v_pk_mul_f32 v[48:49], v[16:17], v[16:17]
	v_add_f32_e32 v50, v137, v50
	v_add_f32_e32 v48, v48, v50
	v_pk_mul_f32 v[38:39], v[138:139], v[138:139]
	v_add_f32_e32 v48, v49, v48
	v_add_f32_e32 v38, v38, v48
	v_add_f32_e32 v38, v39, v38
	ds_bpermute_b32 v39, v79, v38
	v_cvt_f32_f16_sdwa v105, v119 dst_sel:DWORD dst_unused:UNUSED_PAD src0_sel:WORD_1
	v_cvt_f32_f16_e32 v104, v119
	v_cvt_f32_f16_sdwa v107, v118 dst_sel:DWORD dst_unused:UNUSED_PAD src0_sel:WORD_1
	v_cvt_f32_f16_e32 v106, v118
	s_waitcnt lgkmcnt(0)
	v_add_f32_e32 v38, v38, v39
	ds_bpermute_b32 v39, v80, v38
	v_cvt_f32_f16_sdwa v119, v65 dst_sel:DWORD dst_unused:UNUSED_PAD src0_sel:WORD_1
	v_cvt_f32_f16_e32 v118, v65
	v_cvt_f32_f16_sdwa v65, v64 dst_sel:DWORD dst_unused:UNUSED_PAD src0_sel:WORD_1
	v_cvt_f32_f16_e32 v64, v64
	s_waitcnt lgkmcnt(0)
	v_add_f32_e32 v38, v38, v39
	ds_bpermute_b32 v39, v81, v38
	v_cvt_f32_f16_sdwa v55, v120 dst_sel:DWORD dst_unused:UNUSED_PAD src0_sel:WORD_1
	v_cvt_f32_f16_e32 v54, v120
	v_cvt_f32_f16_sdwa v109, v117 dst_sel:DWORD dst_unused:UNUSED_PAD src0_sel:WORD_1
	v_cvt_f32_f16_e32 v108, v117
	s_waitcnt lgkmcnt(0)
	v_add_f32_e32 v38, v38, v39
	ds_bpermute_b32 v39, v82, v38
	v_cvt_f32_f16_sdwa v111, v116 dst_sel:DWORD dst_unused:UNUSED_PAD src0_sel:WORD_1
	v_cvt_f32_f16_e32 v110, v116
	v_cvt_f32_f16_sdwa v115, v113 dst_sel:DWORD dst_unused:UNUSED_PAD src0_sel:WORD_1
	v_cvt_f32_f16_e32 v114, v113
	s_waitcnt lgkmcnt(0)
	v_add_f32_e32 v38, v38, v39
	ds_bpermute_b32 v39, v83, v38
	v_cvt_f32_f16_sdwa v113, v112 dst_sel:DWORD dst_unused:UNUSED_PAD src0_sel:WORD_1
	v_cvt_f32_f16_e32 v112, v112
	v_cvt_f32_f16_sdwa v117, v67 dst_sel:DWORD dst_unused:UNUSED_PAD src0_sel:WORD_1
	v_cvt_f32_f16_e32 v116, v67
	s_waitcnt lgkmcnt(0)
	v_add_f32_e32 v38, v38, v39
	ds_bpermute_b32 v39, v84, v38
	v_cvt_f32_f16_sdwa v67, v66 dst_sel:DWORD dst_unused:UNUSED_PAD src0_sel:WORD_1
	v_cvt_f32_f16_e32 v66, v66
	s_waitcnt lgkmcnt(0)
	v_add_f32_e32 v38, v38, v39
	v_fmamk_f32 v38, v38, 0x3a000000, v101
	v_mul_f32_e32 v39, 0x4f800000, v38
	v_cmp_gt_f32_e32 vcc, s7, v38
	s_nop 1
	v_cndmask_b32_e32 v38, v38, v39, vcc
	v_sqrt_f32_e32 v39, v38
	s_nop 0
	v_add_u32_e32 v48, -1, v39
	v_fma_f32 v49, -v48, v39, v38
	v_cmp_ge_f32_e64 s[0:1], 0, v49
	v_add_u32_e32 v49, 1, v39
	s_nop 0
	v_cndmask_b32_e64 v48, v39, v48, s[0:1]
	v_fma_f32 v39, -v49, v39, v38
	v_cmp_lt_f32_e64 s[0:1], 0, v39
	s_nop 1
	v_cndmask_b32_e64 v39, v48, v49, s[0:1]
	v_mul_f32_e32 v48, 0x37800000, v39
	v_cndmask_b32_e32 v39, v39, v48, vcc
	v_cmp_class_f32_e32 vcc, v38, v102
	s_nop 1
	v_cndmask_b32_e32 v38, v39, v38, vcc
	v_div_scale_f32 v39, s[0:1], v38, v38, 1.0
	v_rcp_f32_e32 v50, v39
	s_add_u32 s0, s20, s14
	s_addc_u32 s1, s21, s15
	v_lshl_add_u64 v[48:49], s[0:1], 0, v[36:37]
	v_fma_f32 v51, -v39, v50, 1.0
	v_fmac_f32_e32 v50, v51, v50
	v_div_scale_f32 v51, vcc, 1.0, v38, 1.0
	v_mul_f32_e32 v52, v51, v50
	v_fma_f32 v53, -v39, v52, v51
	v_fmac_f32_e32 v52, v53, v50
	v_fma_f32 v39, -v39, v52, v51
	v_div_fmas_f32 v39, v39, v50, v52
	v_div_fixup_f32 v50, v39, v38, 1.0
	v_pk_mul_f32 v[20:21], v[20:21], v[50:51] op_sel_hi:[1,0]
	v_pk_mul_f32 v[8:9], v[8:9], v[50:51] op_sel_hi:[1,0]
	v_pk_fma_f32 v[0:1], v[172:173], v[20:21], v[204:205]
	v_pk_fma_f32 v[2:3], v[174:175], v[8:9], v[206:207]
	global_store_dwordx4 v[48:49], v[0:3], off
	s_nop 1
	s_nop 0
	v_pk_mul_f32 v[8:9], v[10:11], v[50:51] op_sel_hi:[1,0]
	v_pk_mul_f32 v[10:11], v[40:41], v[50:51] op_sel_hi:[1,0]
	v_add_co_u32_e32 v38, vcc, s12, v32
	s_or_b32 s0, s10, 1
	s_nop 0
	v_addc_co_u32_e32 v39, vcc, 0, v33, vcc
	v_add_co_u32_e32 v40, vcc, s12, v34
	s_ashr_i32 s1, s0, 31
	s_nop 0
	v_addc_co_u32_e32 v41, vcc, 0, v35, vcc
	s_lshl_b64 s[14:15], s[0:1], 11
	v_cvt_f32_f16_sdwa v53, v121 dst_sel:DWORD dst_unused:UNUSED_PAD src0_sel:WORD_1
	v_cvt_f32_f16_e32 v52, v121
	s_lshl_b64 s[0:1], s[0:1], 13
	v_pk_fma_f32 v[0:1], v[176:177], v[10:11], v[208:209]
	v_pk_fma_f32 v[2:3], v[178:179], v[8:9], v[210:211]
	global_store_dwordx4 v[48:49], v[0:3], off offset:16
	s_nop 1
	s_nop 0
	v_pk_mul_f32 v[8:9], v[14:15], v[50:51] op_sel_hi:[1,0]
	v_pk_mul_f32 v[10:11], v[12:13], v[50:51] op_sel_hi:[1,0]
	v_pk_mul_f32 v[12:13], v[22:23], v[50:51] op_sel_hi:[1,0]
	v_pk_mul_f32 v[14:15], v[16:17], v[50:51] op_sel_hi:[1,0]
	v_pk_fma_f32 v[0:1], v[180:181], v[10:11], v[212:213]
	v_pk_fma_f32 v[2:3], v[182:183], v[8:9], v[214:215]
	global_store_dwordx4 v[48:49], v[0:3], off offset:32
	s_nop 1
	s_nop 0
	v_pk_mul_f32 v[8:9], v[18:19], v[50:51] op_sel_hi:[1,0]
	v_pk_mul_f32 v[10:11], v[44:45], v[50:51] op_sel_hi:[1,0]
	v_pk_fma_f32 v[2:3], v[186:187], v[8:9], v[218:219]
	v_pk_fma_f32 v[0:1], v[184:185], v[10:11], v[216:217]
	global_store_dwordx4 v[48:49], v[0:3], off offset:48
	s_nop 1
	s_nop 0
	v_add_co_u32_e32 v8, vcc, s12, v48
	v_pk_mul_f32 v[10:11], v[24:25], v[50:51] op_sel_hi:[1,0]
	s_nop 0
	v_addc_co_u32_e32 v9, vcc, 0, v49, vcc
	v_cvt_f32_f16_sdwa v49, v123 dst_sel:DWORD dst_unused:UNUSED_PAD src0_sel:WORD_1
	v_cvt_f32_f16_e32 v48, v123
	v_pk_fma_f32 v[0:1], v[188:189], v[12:13], v[220:221]
	v_pk_fma_f32 v[2:3], v[190:191], v[10:11], v[222:223]
	global_store_dwordx4 v[8:9], v[0:3], off
	s_nop 1
	s_nop 0
	v_pk_mul_f32 v[10:11], v[26:27], v[50:51] op_sel_hi:[1,0]
	v_pk_mul_f32 v[12:13], v[28:29], v[50:51] op_sel_hi:[1,0]
	v_pk_fma_f32 v[2:3], v[194:195], v[10:11], v[226:227]
	v_pk_fma_f32 v[0:1], v[192:193], v[12:13], v[224:225]
	global_store_dwordx4 v[8:9], v[0:3], off offset:16
	s_nop 1
	s_nop 0
	v_pk_mul_f32 v[10:11], v[46:47], v[50:51] op_sel_hi:[1,0]
	v_pk_mul_f32 v[12:13], v[30:31], v[50:51] op_sel_hi:[1,0]
	v_pk_fma_f32 v[2:3], v[198:199], v[10:11], v[230:231]
	v_pk_fma_f32 v[0:1], v[196:197], v[12:13], v[228:229]
	global_store_dwordx4 v[8:9], v[0:3], off offset:32
	s_nop 1
	s_nop 0
	v_lshl_add_u64 v[10:11], s[14:15], 0, v[42:43]
	v_pk_mul_f32 v[12:13], v[138:139], v[50:51] op_sel_hi:[1,0]
	v_lshlrev_b64 v[10:11], 1, v[10:11]
	v_lshl_add_u64 v[44:45], s[70:71], 0, v[10:11]
	v_lshl_add_u64 v[46:47], s[2:3], 0, v[10:11]
	v_cvt_f32_f16_sdwa v51, v122 dst_sel:DWORD dst_unused:UNUSED_PAD src0_sel:WORD_1
	v_cvt_f32_f16_e32 v50, v122
	s_add_u32 s14, s20, s0
	s_addc_u32 s15, s21, s1
	v_pk_fma_f32 v[0:1], v[200:201], v[14:15], v[232:233]
	v_pk_fma_f32 v[2:3], v[202:203], v[12:13], v[234:235]
	global_store_dwordx4 v[8:9], v[0:3], off offset:48
	s_nop 1
	global_load_dwordx4 v[4:7], v[44:45], off offset:2064
	s_nop 0
	global_load_dwordx4 v[0:3], v[46:47], off offset:2064
	global_load_dwordx4 v[28:31], v[44:45], off
	global_load_dwordx4 v[24:27], v[46:47], off
	global_load_dwordx4 v[20:23], v[44:45], off offset:16
	global_load_dwordx4 v[16:19], v[46:47], off offset:16
	global_load_dwordx4 v[12:15], v[44:45], off offset:2048
	global_load_dwordx4 v[8:11], v[46:47], off offset:2048
	v_cvt_f32_f16_sdwa v45, v125 dst_sel:DWORD dst_unused:UNUSED_PAD src0_sel:WORD_1
	v_cvt_f32_f16_e32 v44, v125
	v_cvt_f32_f16_sdwa v47, v124 dst_sel:DWORD dst_unused:UNUSED_PAD src0_sel:WORD_1
	v_cvt_f32_f16_e32 v46, v124
	s_waitcnt vmcnt(6)
	v_and_b32_e32 v123, 0xffff0000, v2
	v_lshlrev_b32_e32 v122, 16, v2
	s_waitcnt vmcnt(5)
	v_lshlrev_b32_e32 v124, 16, v28
	v_and_b32_e32 v125, 0xffff0000, v28
	s_waitcnt vmcnt(4)
	v_lshlrev_b32_e32 v126, 16, v24
	v_and_b32_e32 v121, 0xffff0000, v6
	v_lshlrev_b32_e32 v120, 16, v6
	v_and_b32_e32 v127, 0xffff0000, v24
	v_and_b32_e32 v129, 0xffff0000, v7
	v_lshlrev_b32_e32 v128, 16, v7
	v_and_b32_e32 v7, 0xffff0000, v3
	v_lshlrev_b32_e32 v6, 16, v3
	v_lshlrev_b32_e32 v2, 16, v30
	v_and_b32_e32 v3, 0xffff0000, v30
	v_lshlrev_b32_e32 v130, 16, v26
	v_and_b32_e32 v131, 0xffff0000, v26
	v_lshlrev_b32_e32 v30, 16, v31
	v_and_b32_e32 v31, 0xffff0000, v31
	v_lshlrev_b32_e32 v26, 16, v27
	v_and_b32_e32 v27, 0xffff0000, v27
	v_lshlrev_b32_e32 v166, 16, v4
	v_and_b32_e32 v167, 0xffff0000, v4
	v_lshlrev_b32_e32 v168, 16, v0
	v_and_b32_e32 v169, 0xffff0000, v0
	v_lshlrev_b32_e32 v4, 16, v5
	v_and_b32_e32 v5, 0xffff0000, v5
	v_lshlrev_b32_e32 v0, 16, v1
	v_and_b32_e32 v1, 0xffff0000, v1
	v_pk_fma_f32 v[120:121], v[120:121], s[6:7], v[122:123] op_sel_hi:[1,0,1]
	v_pk_fma_f32 v[122:123], v[124:125], s[6:7], v[126:127] op_sel_hi:[1,0,1]
	v_lshlrev_b32_e32 v28, 16, v29
	v_and_b32_e32 v29, 0xffff0000, v29
	v_lshlrev_b32_e32 v24, 16, v25
	v_and_b32_e32 v25, 0xffff0000, v25
	v_pk_fma_f32 v[6:7], v[128:129], s[6:7], v[6:7] op_sel_hi:[1,0,1]
	v_pk_fma_f32 v[26:27], v[30:31], s[6:7], v[26:27] op_sel_hi:[1,0,1]
	v_pk_fma_f32 v[0:1], v[4:5], s[6:7], v[0:1] op_sel_hi:[1,0,1]
	v_pk_add_f32 v[30:31], v[120:121], v[44:45]
	v_pk_add_f32 v[44:45], v[122:123], v[46:47]
	v_pk_fma_f32 v[24:25], v[28:29], s[6:7], v[24:25] op_sel_hi:[1,0,1]
	v_pk_add_f32 v[46:47], v[6:7], v[50:51]
	v_pk_add_f32 v[50:51], v[0:1], v[64:65]
	v_add_f32_e32 v0, 0, v44
	v_pk_add_f32 v[24:25], v[24:25], v[48:49]
	v_add_f32_e32 v0, v45, v0
	v_pk_fma_f32 v[2:3], v[2:3], s[6:7], v[130:131] op_sel_hi:[1,0,1]
	v_add_f32_e32 v0, v24, v0
	v_pk_add_f32 v[48:49], v[2:3], v[52:53]
	v_add_f32_e32 v0, v25, v0
	v_add_f32_e32 v0, v48, v0
	s_waitcnt vmcnt(3)
	v_lshlrev_b32_e32 v132, 16, v20
	v_and_b32_e32 v133, 0xffff0000, v20
	s_waitcnt vmcnt(2)
	v_lshlrev_b32_e32 v134, 16, v16
	v_and_b32_e32 v135, 0xffff0000, v16
	v_pk_add_f32 v[26:27], v[26:27], v[54:55]
	v_add_f32_e32 v0, v49, v0
	v_pk_fma_f32 v[28:29], v[132:133], s[6:7], v[134:135] op_sel_hi:[1,0,1]
	v_add_f32_e32 v0, v26, v0
	v_lshlrev_b32_e32 v20, 16, v21
	v_and_b32_e32 v21, 0xffff0000, v21
	v_lshlrev_b32_e32 v16, 16, v17
	v_and_b32_e32 v17, 0xffff0000, v17
	v_pk_add_f32 v[28:29], v[28:29], v[104:105]
	v_add_f32_e32 v0, v27, v0
	v_pk_fma_f32 v[16:17], v[20:21], s[6:7], v[16:17] op_sel_hi:[1,0,1]
	v_add_f32_e32 v0, v28, v0
	v_lshlrev_b32_e32 v136, 16, v22
	v_and_b32_e32 v137, 0xffff0000, v22
	v_lshlrev_b32_e32 v138, 16, v18
	v_and_b32_e32 v139, 0xffff0000, v18
	v_pk_add_f32 v[16:17], v[16:17], v[106:107]
	v_add_f32_e32 v0, v29, v0
	v_pk_fma_f32 v[20:21], v[136:137], s[6:7], v[138:139] op_sel_hi:[1,0,1]
	v_add_f32_e32 v0, v16, v0
	v_lshlrev_b32_e32 v22, 16, v23
	v_and_b32_e32 v23, 0xffff0000, v23
	v_lshlrev_b32_e32 v18, 16, v19
	v_and_b32_e32 v19, 0xffff0000, v19
	v_pk_add_f32 v[20:21], v[20:21], v[108:109]
	v_add_f32_e32 v0, v17, v0
	v_pk_fma_f32 v[18:19], v[22:23], s[6:7], v[18:19] op_sel_hi:[1,0,1]
	v_add_f32_e32 v0, v20, v0
	s_waitcnt vmcnt(1)
	v_lshlrev_b32_e32 v150, 16, v12
	v_and_b32_e32 v151, 0xffff0000, v12
	s_waitcnt vmcnt(0)
	v_lshlrev_b32_e32 v152, 16, v8
	v_and_b32_e32 v153, 0xffff0000, v8
	v_pk_add_f32 v[18:19], v[18:19], v[110:111]
	v_add_f32_e32 v0, v21, v0
	v_pk_fma_f32 v[22:23], v[150:151], s[6:7], v[152:153] op_sel_hi:[1,0,1]
	v_add_f32_e32 v0, v18, v0
	v_lshlrev_b32_e32 v12, 16, v13
	v_and_b32_e32 v13, 0xffff0000, v13
	v_lshlrev_b32_e32 v8, 16, v9
	v_and_b32_e32 v9, 0xffff0000, v9
	v_pk_add_f32 v[22:23], v[22:23], v[114:115]
	v_add_f32_e32 v0, v19, v0
	v_pk_fma_f32 v[8:9], v[12:13], s[6:7], v[8:9] op_sel_hi:[1,0,1]
	v_add_f32_e32 v0, v22, v0
	v_lshlrev_b32_e32 v154, 16, v14
	v_and_b32_e32 v155, 0xffff0000, v14
	v_lshlrev_b32_e32 v164, 16, v10
	v_and_b32_e32 v165, 0xffff0000, v10
	v_pk_add_f32 v[8:9], v[8:9], v[112:113]
	v_add_f32_e32 v0, v23, v0
	v_pk_fma_f32 v[12:13], v[154:155], s[6:7], v[164:165] op_sel_hi:[1,0,1]
	v_add_f32_e32 v0, v8, v0
	v_lshlrev_b32_e32 v14, 16, v15
	v_and_b32_e32 v15, 0xffff0000, v15
	v_lshlrev_b32_e32 v10, 16, v11
	v_and_b32_e32 v11, 0xffff0000, v11
	v_pk_add_f32 v[12:13], v[12:13], v[116:117]
	v_add_f32_e32 v0, v9, v0
	v_pk_fma_f32 v[10:11], v[14:15], s[6:7], v[10:11] op_sel_hi:[1,0,1]
	v_add_f32_e32 v0, v12, v0
	v_pk_add_f32 v[10:11], v[10:11], v[66:67]
	v_add_f32_e32 v0, v13, v0
	v_pk_fma_f32 v[14:15], v[166:167], s[6:7], v[168:169] op_sel_hi:[1,0,1]
	v_add_f32_e32 v0, v10, v0
	v_pk_add_f32 v[14:15], v[14:15], v[118:119]
	v_add_f32_e32 v0, v11, v0
	v_add_f32_e32 v0, v14, v0
	v_add_f32_e32 v0, v15, v0
	v_add_f32_e32 v0, v50, v0
	v_add_f32_e32 v0, v51, v0
	v_add_f32_e32 v0, v30, v0
	v_add_f32_e32 v0, v31, v0
	v_add_f32_e32 v0, v46, v0
	v_add_f32_e32 v0, v47, v0
	ds_bpermute_b32 v1, v79, v0
	s_waitcnt lgkmcnt(0)
	v_add_f32_e32 v0, v0, v1
	ds_bpermute_b32 v1, v80, v0
	s_waitcnt lgkmcnt(0)
	v_add_f32_e32 v0, v0, v1
	ds_bpermute_b32 v1, v81, v0
	s_waitcnt lgkmcnt(0)
	v_add_f32_e32 v0, v0, v1
	ds_bpermute_b32 v1, v82, v0
	s_waitcnt lgkmcnt(0)
	v_add_f32_e32 v0, v0, v1
	ds_bpermute_b32 v1, v83, v0
	s_waitcnt lgkmcnt(0)
	v_add_f32_e32 v52, v0, v1
	ds_bpermute_b32 v53, v84, v52
	s_waitcnt lgkmcnt(0)
	v_add_f32_e32 v52, v52, v53
	v_mul_f32_e32 v52, 0x3a000000, v52
	v_pk_add_f32 v[44:45], v[44:45], v[52:53] op_sel_hi:[1,0] neg_lo:[0,1] neg_hi:[0,1]
	v_pk_add_f32 v[24:25], v[24:25], v[52:53] op_sel_hi:[1,0] neg_lo:[0,1] neg_hi:[0,1]
	v_pk_add_f32 v[48:49], v[48:49], v[52:53] op_sel_hi:[1,0] neg_lo:[0,1] neg_hi:[0,1]
	v_pk_add_f32 v[26:27], v[26:27], v[52:53] op_sel_hi:[1,0] neg_lo:[0,1] neg_hi:[0,1]
	v_pk_add_f32 v[28:29], v[28:29], v[52:53] op_sel_hi:[1,0] neg_lo:[0,1] neg_hi:[0,1]
	v_pk_add_f32 v[16:17], v[16:17], v[52:53] op_sel_hi:[1,0] neg_lo:[0,1] neg_hi:[0,1]
	v_pk_add_f32 v[20:21], v[20:21], v[52:53] op_sel_hi:[1,0] neg_lo:[0,1] neg_hi:[0,1]
	v_pk_add_f32 v[18:19], v[18:19], v[52:53] op_sel_hi:[1,0] neg_lo:[0,1] neg_hi:[0,1]
	v_pk_add_f32 v[22:23], v[22:23], v[52:53] op_sel_hi:[1,0] neg_lo:[0,1] neg_hi:[0,1]
	v_pk_add_f32 v[8:9], v[8:9], v[52:53] op_sel_hi:[1,0] neg_lo:[0,1] neg_hi:[0,1]
	v_pk_add_f32 v[12:13], v[12:13], v[52:53] op_sel_hi:[1,0] neg_lo:[0,1] neg_hi:[0,1]
	v_pk_add_f32 v[10:11], v[10:11], v[52:53] op_sel_hi:[1,0] neg_lo:[0,1] neg_hi:[0,1]
	v_pk_add_f32 v[14:15], v[14:15], v[52:53] op_sel_hi:[1,0] neg_lo:[0,1] neg_hi:[0,1]
	v_pk_add_f32 v[50:51], v[50:51], v[52:53] op_sel_hi:[1,0] neg_lo:[0,1] neg_hi:[0,1]
	v_pk_add_f32 v[46:47], v[46:47], v[52:53] op_sel_hi:[1,0] neg_lo:[0,1] neg_hi:[0,1]
	v_pk_add_f32 v[30:31], v[30:31], v[52:53] op_sel_hi:[1,0] neg_lo:[0,1] neg_hi:[0,1]
	v_pk_mul_f32 v[52:53], v[44:45], v[44:45]
	v_pk_mul_f32 v[54:55], v[24:25], v[24:25]
	v_add_f32_e32 v52, v52, v53
	v_add_f32_e32 v52, v54, v52
	v_pk_mul_f32 v[64:65], v[48:49], v[48:49]
	v_add_f32_e32 v52, v55, v52
	v_add_f32_e32 v52, v64, v52
	v_pk_mul_f32 v[66:67], v[26:27], v[26:27]
	v_add_f32_e32 v52, v65, v52
	v_add_f32_e32 v52, v66, v52
	v_pk_mul_f32 v[104:105], v[28:29], v[28:29]
	v_add_f32_e32 v52, v67, v52
	v_add_f32_e32 v52, v104, v52
	v_pk_mul_f32 v[106:107], v[16:17], v[16:17]
	v_add_f32_e32 v52, v105, v52
	v_add_f32_e32 v52, v106, v52
	v_pk_mul_f32 v[108:109], v[20:21], v[20:21]
	v_add_f32_e32 v52, v107, v52
	v_add_f32_e32 v52, v108, v52
	v_pk_mul_f32 v[110:111], v[18:19], v[18:19]
	v_add_f32_e32 v52, v109, v52
	v_add_f32_e32 v52, v110, v52
	v_pk_mul_f32 v[112:113], v[22:23], v[22:23]
	v_add_f32_e32 v52, v111, v52
	v_add_f32_e32 v52, v112, v52
	v_pk_mul_f32 v[114:115], v[8:9], v[8:9]
	v_add_f32_e32 v52, v113, v52
	v_add_f32_e32 v52, v114, v52
	v_pk_mul_f32 v[116:117], v[12:13], v[12:13]
	v_add_f32_e32 v52, v115, v52
	v_add_f32_e32 v52, v116, v52
	v_pk_mul_f32 v[118:119], v[10:11], v[10:11]
	v_add_f32_e32 v52, v117, v52
	v_add_f32_e32 v52, v118, v52
	v_pk_mul_f32 v[120:121], v[14:15], v[14:15]
	v_add_f32_e32 v52, v119, v52
	v_add_f32_e32 v52, v120, v52
	v_pk_mul_f32 v[122:123], v[50:51], v[50:51]
	v_add_f32_e32 v52, v121, v52
	v_add_f32_e32 v52, v122, v52
	v_pk_mul_f32 v[126:127], v[30:31], v[30:31]
	v_add_f32_e32 v52, v123, v52
	v_add_f32_e32 v52, v126, v52
	v_pk_mul_f32 v[124:125], v[46:47], v[46:47]
	v_add_f32_e32 v52, v127, v52
	v_add_f32_e32 v52, v124, v52
	v_add_f32_e32 v52, v125, v52
	ds_bpermute_b32 v53, v79, v52
	s_waitcnt lgkmcnt(0)
	v_add_f32_e32 v52, v52, v53
	ds_bpermute_b32 v53, v80, v52
	s_waitcnt lgkmcnt(0)
	v_add_f32_e32 v52, v52, v53
	ds_bpermute_b32 v53, v81, v52
	s_waitcnt lgkmcnt(0)
	v_add_f32_e32 v52, v52, v53
	ds_bpermute_b32 v53, v82, v52
	s_waitcnt lgkmcnt(0)
	v_add_f32_e32 v52, v52, v53
	ds_bpermute_b32 v53, v83, v52
	s_waitcnt lgkmcnt(0)
	v_add_f32_e32 v52, v52, v53
	ds_bpermute_b32 v53, v84, v52
	s_waitcnt lgkmcnt(0)
	v_add_f32_e32 v52, v52, v53
	v_fmamk_f32 v52, v52, 0x3a000000, v101
	v_mul_f32_e32 v53, 0x4f800000, v52
	v_cmp_gt_f32_e32 vcc, s7, v52
	s_nop 1
	v_cndmask_b32_e32 v52, v52, v53, vcc
	v_sqrt_f32_e32 v53, v52
	s_nop 0
	v_add_u32_e32 v54, -1, v53
	v_add_u32_e32 v55, 1, v53
	v_fma_f32 v64, -v54, v53, v52
	v_fma_f32 v65, -v55, v53, v52
	v_cmp_ge_f32_e64 s[0:1], 0, v64
	s_nop 1
	v_cndmask_b32_e64 v53, v53, v54, s[0:1]
	v_cmp_lt_f32_e64 s[0:1], 0, v65
	s_nop 1
	v_cndmask_b32_e64 v53, v53, v55, s[0:1]
	v_mul_f32_e32 v54, 0x37800000, v53
	v_cndmask_b32_e32 v53, v53, v54, vcc
	v_cmp_class_f32_e32 vcc, v52, v102
	s_nop 1
	v_cndmask_b32_e32 v54, v53, v52, vcc
	v_div_scale_f32 v55, s[0:1], v54, v54, 1.0
	v_rcp_f32_e32 v64, v55
	v_div_scale_f32 v65, vcc, 1.0, v54, 1.0
	v_lshl_add_u64 v[52:53], s[14:15], 0, v[36:37]
	v_fma_f32 v66, -v55, v64, 1.0
	v_fmac_f32_e32 v64, v66, v64
	v_mul_f32_e32 v66, v65, v64
	v_fma_f32 v67, -v55, v66, v65
	v_fmac_f32_e32 v66, v67, v64
	v_fma_f32 v55, -v55, v66, v65
	v_div_fmas_f32 v55, v55, v64, v66
	v_div_fixup_f32 v54, v55, v54, 1.0
	v_pk_mul_f32 v[44:45], v[44:45], v[54:55] op_sel_hi:[1,0]
	v_pk_mul_f32 v[24:25], v[24:25], v[54:55] op_sel_hi:[1,0]
	v_pk_fma_f32 v[0:1], v[172:173], v[44:45], v[204:205]
	v_pk_fma_f32 v[2:3], v[174:175], v[24:25], v[206:207]
	global_store_dwordx4 v[52:53], v[0:3], off
	s_nop 1
	s_nop 0
	v_pk_mul_f32 v[24:25], v[26:27], v[54:55] op_sel_hi:[1,0]
	v_pk_mul_f32 v[26:27], v[48:49], v[54:55] op_sel_hi:[1,0]
	v_pk_mul_f32 v[16:17], v[16:17], v[54:55] op_sel_hi:[1,0]
	v_pk_mul_f32 v[8:9], v[8:9], v[54:55] op_sel_hi:[1,0]
	s_or_b32 s0, s10, 2
	s_ashr_i32 s1, s0, 31
	s_lshl_b64 s[14:15], s[0:1], 11
	v_cvt_f32_f16_sdwa v49, v73 dst_sel:DWORD dst_unused:UNUSED_PAD src0_sel:WORD_1
	v_cvt_f32_f16_e32 v48, v73
	v_cvt_f32_f16_sdwa v65, v69 dst_sel:DWORD dst_unused:UNUSED_PAD src0_sel:WORD_1
	v_cvt_f32_f16_e32 v64, v69
	v_cvt_f32_f16_sdwa v67, v68 dst_sel:DWORD dst_unused:UNUSED_PAD src0_sel:WORD_1
	v_cvt_f32_f16_e32 v66, v68
	v_cvt_f32_f16_sdwa v69, v63 dst_sel:DWORD dst_unused:UNUSED_PAD src0_sel:WORD_1
	v_cvt_f32_f16_e32 v68, v63
	v_cvt_f32_f16_sdwa v63, v62 dst_sel:DWORD dst_unused:UNUSED_PAD src0_sel:WORD_1
	v_cvt_f32_f16_e32 v62, v62
	v_cvt_f32_f16_sdwa v73, v59 dst_sel:DWORD dst_unused:UNUSED_PAD src0_sel:WORD_1
	s_lshl_b64 s[0:1], s[0:1], 13
	v_pk_fma_f32 v[0:1], v[176:177], v[26:27], v[208:209]
	v_pk_fma_f32 v[2:3], v[178:179], v[24:25], v[210:211]
	global_store_dwordx4 v[52:53], v[0:3], off offset:16
	s_nop 1
	s_nop 0
	v_pk_mul_f32 v[24:25], v[28:29], v[54:55] op_sel_hi:[1,0]
	v_pk_fma_f32 v[2:3], v[182:183], v[16:17], v[214:215]
	v_pk_fma_f32 v[0:1], v[180:181], v[24:25], v[212:213]
	global_store_dwordx4 v[52:53], v[0:3], off offset:32
	s_nop 1
	s_nop 0
	v_pk_mul_f32 v[16:17], v[18:19], v[54:55] op_sel_hi:[1,0]
	v_pk_mul_f32 v[18:19], v[20:21], v[54:55] op_sel_hi:[1,0]
	v_pk_fma_f32 v[2:3], v[186:187], v[16:17], v[218:219]
	v_pk_fma_f32 v[0:1], v[184:185], v[18:19], v[216:217]
	global_store_dwordx4 v[52:53], v[0:3], off offset:48
	s_nop 1
	s_nop 0
	v_add_co_u32_e32 v16, vcc, s12, v52
	v_pk_mul_f32 v[18:19], v[22:23], v[54:55] op_sel_hi:[1,0]
	s_nop 0
	v_addc_co_u32_e32 v17, vcc, 0, v53, vcc
	v_cvt_f32_f16_sdwa v53, v71 dst_sel:DWORD dst_unused:UNUSED_PAD src0_sel:WORD_1
	v_cvt_f32_f16_e32 v52, v71
	v_cvt_f32_f16_sdwa v71, v61 dst_sel:DWORD dst_unused:UNUSED_PAD src0_sel:WORD_1
	v_pk_fma_f32 v[0:1], v[188:189], v[18:19], v[220:221]
	v_pk_fma_f32 v[2:3], v[190:191], v[8:9], v[222:223]
	global_store_dwordx4 v[16:17], v[0:3], off
	s_nop 1
	s_nop 0
	v_pk_mul_f32 v[8:9], v[10:11], v[54:55] op_sel_hi:[1,0]
	v_pk_mul_f32 v[10:11], v[12:13], v[54:55] op_sel_hi:[1,0]
	v_pk_mul_f32 v[12:13], v[30:31], v[54:55] op_sel_hi:[1,0]
	v_pk_fma_f32 v[0:1], v[192:193], v[10:11], v[224:225]
	v_pk_fma_f32 v[2:3], v[194:195], v[8:9], v[226:227]
	global_store_dwordx4 v[16:17], v[0:3], off offset:16
	s_nop 1
	s_nop 0
	v_pk_mul_f32 v[8:9], v[50:51], v[54:55] op_sel_hi:[1,0]
	v_pk_mul_f32 v[10:11], v[14:15], v[54:55] op_sel_hi:[1,0]
	v_cvt_f32_f16_sdwa v51, v72 dst_sel:DWORD dst_unused:UNUSED_PAD src0_sel:WORD_1
	v_cvt_f32_f16_e32 v50, v72
	v_cvt_f32_f16_e32 v72, v59
	v_cvt_f32_f16_sdwa v59, v58 dst_sel:DWORD dst_unused:UNUSED_PAD src0_sel:WORD_1
	v_cvt_f32_f16_e32 v58, v58
	v_pk_fma_f32 v[0:1], v[196:197], v[10:11], v[228:229]
	v_pk_fma_f32 v[2:3], v[198:199], v[8:9], v[230:231]
	global_store_dwordx4 v[16:17], v[0:3], off offset:32
	s_nop 1
	s_nop 0
	v_lshl_add_u64 v[8:9], s[14:15], 0, v[42:43]
	v_pk_mul_f32 v[10:11], v[46:47], v[54:55] op_sel_hi:[1,0]
	v_lshlrev_b64 v[8:9], 1, v[8:9]
	v_lshl_add_u64 v[44:45], s[70:71], 0, v[8:9]
	v_lshl_add_u64 v[46:47], s[2:3], 0, v[8:9]
	v_cvt_f32_f16_sdwa v55, v70 dst_sel:DWORD dst_unused:UNUSED_PAD src0_sel:WORD_1
	v_cvt_f32_f16_e32 v54, v70
	v_cvt_f32_f16_e32 v70, v61
	v_cvt_f32_f16_sdwa v61, v60 dst_sel:DWORD dst_unused:UNUSED_PAD src0_sel:WORD_1
	v_cvt_f32_f16_e32 v60, v60
	s_add_u32 s14, s20, s0
	s_addc_u32 s15, s21, s1
	v_pk_fma_f32 v[0:1], v[200:201], v[12:13], v[232:233]
	v_pk_fma_f32 v[2:3], v[202:203], v[10:11], v[234:235]
	global_store_dwordx4 v[16:17], v[0:3], off offset:48
	s_nop 1
	global_load_dwordx4 v[4:7], v[44:45], off offset:2064
	s_nop 0
	global_load_dwordx4 v[0:3], v[46:47], off offset:2064
	global_load_dwordx4 v[28:31], v[44:45], off
	global_load_dwordx4 v[24:27], v[46:47], off
	global_load_dwordx4 v[20:23], v[44:45], off offset:16
	global_load_dwordx4 v[16:19], v[46:47], off offset:16
	global_load_dwordx4 v[12:15], v[44:45], off offset:2048
	global_load_dwordx4 v[8:11], v[46:47], off offset:2048
	v_cvt_f32_f16_sdwa v45, v75 dst_sel:DWORD dst_unused:UNUSED_PAD src0_sel:WORD_1
	v_cvt_f32_f16_e32 v44, v75
	v_cvt_f32_f16_sdwa v47, v74 dst_sel:DWORD dst_unused:UNUSED_PAD src0_sel:WORD_1
	v_cvt_f32_f16_e32 v46, v74
	v_cvt_f32_f16_sdwa v75, v57 dst_sel:DWORD dst_unused:UNUSED_PAD src0_sel:WORD_1
	v_cvt_f32_f16_e32 v74, v57
	v_cvt_f32_f16_sdwa v57, v56 dst_sel:DWORD dst_unused:UNUSED_PAD src0_sel:WORD_1
	v_cvt_f32_f16_e32 v56, v56
	s_waitcnt vmcnt(6)
	v_and_b32_e32 v107, 0xffff0000, v2
	v_lshlrev_b32_e32 v106, 16, v2
	s_waitcnt vmcnt(5)
	v_lshlrev_b32_e32 v108, 16, v28
	v_and_b32_e32 v109, 0xffff0000, v28
	s_waitcnt vmcnt(4)
	v_lshlrev_b32_e32 v110, 16, v24
	v_and_b32_e32 v105, 0xffff0000, v6
	v_lshlrev_b32_e32 v104, 16, v6
	v_and_b32_e32 v111, 0xffff0000, v24
	v_and_b32_e32 v113, 0xffff0000, v7
	v_lshlrev_b32_e32 v112, 16, v7
	v_and_b32_e32 v7, 0xffff0000, v3
	v_lshlrev_b32_e32 v6, 16, v3
	v_lshlrev_b32_e32 v2, 16, v30
	v_and_b32_e32 v3, 0xffff0000, v30
	v_lshlrev_b32_e32 v114, 16, v26
	v_and_b32_e32 v115, 0xffff0000, v26
	v_lshlrev_b32_e32 v30, 16, v31
	v_and_b32_e32 v31, 0xffff0000, v31
	v_lshlrev_b32_e32 v26, 16, v27
	v_and_b32_e32 v27, 0xffff0000, v27
	v_lshlrev_b32_e32 v132, 16, v4
	v_and_b32_e32 v133, 0xffff0000, v4
	v_lshlrev_b32_e32 v134, 16, v0
	v_and_b32_e32 v135, 0xffff0000, v0
	v_lshlrev_b32_e32 v4, 16, v5
	v_and_b32_e32 v5, 0xffff0000, v5
	v_lshlrev_b32_e32 v0, 16, v1
	v_and_b32_e32 v1, 0xffff0000, v1
	v_pk_fma_f32 v[104:105], v[104:105], s[6:7], v[106:107] op_sel_hi:[1,0,1]
	v_pk_fma_f32 v[106:107], v[108:109], s[6:7], v[110:111] op_sel_hi:[1,0,1]
	v_lshlrev_b32_e32 v28, 16, v29
	v_and_b32_e32 v29, 0xffff0000, v29
	v_lshlrev_b32_e32 v24, 16, v25
	v_and_b32_e32 v25, 0xffff0000, v25
	v_pk_fma_f32 v[6:7], v[112:113], s[6:7], v[6:7] op_sel_hi:[1,0,1]
	v_pk_fma_f32 v[26:27], v[30:31], s[6:7], v[26:27] op_sel_hi:[1,0,1]
	v_pk_fma_f32 v[0:1], v[4:5], s[6:7], v[0:1] op_sel_hi:[1,0,1]
	v_pk_add_f32 v[30:31], v[104:105], v[44:45]
	v_pk_add_f32 v[44:45], v[106:107], v[46:47]
	v_pk_fma_f32 v[24:25], v[28:29], s[6:7], v[24:25] op_sel_hi:[1,0,1]
	v_pk_add_f32 v[46:47], v[6:7], v[50:51]
	v_pk_add_f32 v[50:51], v[0:1], v[56:57]
	v_add_f32_e32 v0, 0, v44
	v_pk_add_f32 v[24:25], v[24:25], v[48:49]
	v_add_f32_e32 v0, v45, v0
	v_pk_fma_f32 v[2:3], v[2:3], s[6:7], v[114:115] op_sel_hi:[1,0,1]
	v_add_f32_e32 v0, v24, v0
	v_pk_add_f32 v[48:49], v[2:3], v[52:53]
	v_add_f32_e32 v0, v25, v0
	v_add_f32_e32 v0, v48, v0
	s_waitcnt vmcnt(3)
	v_lshlrev_b32_e32 v116, 16, v20
	v_and_b32_e32 v117, 0xffff0000, v20
	s_waitcnt vmcnt(2)
	v_lshlrev_b32_e32 v118, 16, v16
	v_and_b32_e32 v119, 0xffff0000, v16
	v_pk_add_f32 v[26:27], v[26:27], v[54:55]
	v_add_f32_e32 v0, v49, v0
	v_pk_fma_f32 v[28:29], v[116:117], s[6:7], v[118:119] op_sel_hi:[1,0,1]
	v_add_f32_e32 v0, v26, v0
	v_lshlrev_b32_e32 v20, 16, v21
	v_and_b32_e32 v21, 0xffff0000, v21
	v_lshlrev_b32_e32 v16, 16, v17
	v_and_b32_e32 v17, 0xffff0000, v17
	v_pk_add_f32 v[28:29], v[28:29], v[64:65]
	v_add_f32_e32 v0, v27, v0
	v_pk_fma_f32 v[16:17], v[20:21], s[6:7], v[16:17] op_sel_hi:[1,0,1]
	v_add_f32_e32 v0, v28, v0
	v_lshlrev_b32_e32 v120, 16, v22
	v_and_b32_e32 v121, 0xffff0000, v22
	v_lshlrev_b32_e32 v122, 16, v18
	v_and_b32_e32 v123, 0xffff0000, v18
	v_pk_add_f32 v[16:17], v[16:17], v[66:67]
	v_add_f32_e32 v0, v29, v0
	v_pk_fma_f32 v[20:21], v[120:121], s[6:7], v[122:123] op_sel_hi:[1,0,1]
	v_add_f32_e32 v0, v16, v0
	v_lshlrev_b32_e32 v22, 16, v23
	v_and_b32_e32 v23, 0xffff0000, v23
	v_lshlrev_b32_e32 v18, 16, v19
	v_and_b32_e32 v19, 0xffff0000, v19
	v_pk_add_f32 v[20:21], v[20:21], v[68:69]
	v_add_f32_e32 v0, v17, v0
	v_pk_fma_f32 v[18:19], v[22:23], s[6:7], v[18:19] op_sel_hi:[1,0,1]
	v_add_f32_e32 v0, v20, v0
	s_waitcnt vmcnt(1)
	v_lshlrev_b32_e32 v124, 16, v12
	v_and_b32_e32 v125, 0xffff0000, v12
	s_waitcnt vmcnt(0)
	v_lshlrev_b32_e32 v126, 16, v8
	v_and_b32_e32 v127, 0xffff0000, v8
	v_pk_add_f32 v[18:19], v[18:19], v[62:63]
	v_add_f32_e32 v0, v21, v0
	v_pk_fma_f32 v[22:23], v[124:125], s[6:7], v[126:127] op_sel_hi:[1,0,1]
	v_add_f32_e32 v0, v18, v0
	v_lshlrev_b32_e32 v12, 16, v13
	v_and_b32_e32 v13, 0xffff0000, v13
	v_lshlrev_b32_e32 v8, 16, v9
	v_and_b32_e32 v9, 0xffff0000, v9
	v_pk_add_f32 v[22:23], v[22:23], v[70:71]
	v_add_f32_e32 v0, v19, v0
	v_pk_fma_f32 v[8:9], v[12:13], s[6:7], v[8:9] op_sel_hi:[1,0,1]
	v_add_f32_e32 v0, v22, v0
	v_lshlrev_b32_e32 v128, 16, v14
	v_and_b32_e32 v129, 0xffff0000, v14
	v_lshlrev_b32_e32 v130, 16, v10
	v_and_b32_e32 v131, 0xffff0000, v10
	v_pk_add_f32 v[8:9], v[8:9], v[60:61]
	v_add_f32_e32 v0, v23, v0
	v_pk_fma_f32 v[12:13], v[128:129], s[6:7], v[130:131] op_sel_hi:[1,0,1]
	v_add_f32_e32 v0, v8, v0
	v_lshlrev_b32_e32 v14, 16, v15
	v_and_b32_e32 v15, 0xffff0000, v15
	v_lshlrev_b32_e32 v10, 16, v11
	v_and_b32_e32 v11, 0xffff0000, v11
	v_pk_add_f32 v[12:13], v[12:13], v[72:73]
	v_add_f32_e32 v0, v9, v0
	v_pk_fma_f32 v[10:11], v[14:15], s[6:7], v[10:11] op_sel_hi:[1,0,1]
	v_add_f32_e32 v0, v12, v0
	v_pk_add_f32 v[10:11], v[10:11], v[58:59]
	v_add_f32_e32 v0, v13, v0
	v_pk_fma_f32 v[14:15], v[132:133], s[6:7], v[134:135] op_sel_hi:[1,0,1]
	v_add_f32_e32 v0, v10, v0
	v_pk_add_f32 v[14:15], v[14:15], v[74:75]
	v_add_f32_e32 v0, v11, v0
	v_add_f32_e32 v0, v14, v0
	v_add_f32_e32 v0, v15, v0
	v_add_f32_e32 v0, v50, v0
	v_add_f32_e32 v0, v51, v0
	v_add_f32_e32 v0, v30, v0
	v_add_f32_e32 v0, v31, v0
	v_add_f32_e32 v0, v46, v0
	v_add_f32_e32 v0, v47, v0
	ds_bpermute_b32 v1, v79, v0
	s_waitcnt lgkmcnt(0)
	v_add_f32_e32 v0, v0, v1
	ds_bpermute_b32 v1, v80, v0
	s_waitcnt lgkmcnt(0)
	v_add_f32_e32 v0, v0, v1
	ds_bpermute_b32 v1, v81, v0
	s_waitcnt lgkmcnt(0)
	v_add_f32_e32 v0, v0, v1
	ds_bpermute_b32 v1, v82, v0
	s_waitcnt lgkmcnt(0)
	v_add_f32_e32 v0, v0, v1
	ds_bpermute_b32 v1, v83, v0
	s_waitcnt lgkmcnt(0)
	v_add_f32_e32 v52, v0, v1
	ds_bpermute_b32 v53, v84, v52
	s_waitcnt lgkmcnt(0)
	v_add_f32_e32 v52, v52, v53
	v_mul_f32_e32 v52, 0x3a000000, v52
	v_pk_add_f32 v[44:45], v[44:45], v[52:53] op_sel_hi:[1,0] neg_lo:[0,1] neg_hi:[0,1]
	v_pk_add_f32 v[24:25], v[24:25], v[52:53] op_sel_hi:[1,0] neg_lo:[0,1] neg_hi:[0,1]
	v_pk_add_f32 v[48:49], v[48:49], v[52:53] op_sel_hi:[1,0] neg_lo:[0,1] neg_hi:[0,1]
	v_pk_add_f32 v[26:27], v[26:27], v[52:53] op_sel_hi:[1,0] neg_lo:[0,1] neg_hi:[0,1]
	v_pk_add_f32 v[28:29], v[28:29], v[52:53] op_sel_hi:[1,0] neg_lo:[0,1] neg_hi:[0,1]
	v_pk_add_f32 v[16:17], v[16:17], v[52:53] op_sel_hi:[1,0] neg_lo:[0,1] neg_hi:[0,1]
	v_pk_add_f32 v[20:21], v[20:21], v[52:53] op_sel_hi:[1,0] neg_lo:[0,1] neg_hi:[0,1]
	v_pk_add_f32 v[18:19], v[18:19], v[52:53] op_sel_hi:[1,0] neg_lo:[0,1] neg_hi:[0,1]
	v_pk_add_f32 v[22:23], v[22:23], v[52:53] op_sel_hi:[1,0] neg_lo:[0,1] neg_hi:[0,1]
	v_pk_add_f32 v[8:9], v[8:9], v[52:53] op_sel_hi:[1,0] neg_lo:[0,1] neg_hi:[0,1]
	v_pk_add_f32 v[12:13], v[12:13], v[52:53] op_sel_hi:[1,0] neg_lo:[0,1] neg_hi:[0,1]
	v_pk_add_f32 v[10:11], v[10:11], v[52:53] op_sel_hi:[1,0] neg_lo:[0,1] neg_hi:[0,1]
	v_pk_add_f32 v[14:15], v[14:15], v[52:53] op_sel_hi:[1,0] neg_lo:[0,1] neg_hi:[0,1]
	v_pk_add_f32 v[50:51], v[50:51], v[52:53] op_sel_hi:[1,0] neg_lo:[0,1] neg_hi:[0,1]
	v_pk_add_f32 v[46:47], v[46:47], v[52:53] op_sel_hi:[1,0] neg_lo:[0,1] neg_hi:[0,1]
	v_pk_add_f32 v[30:31], v[30:31], v[52:53] op_sel_hi:[1,0] neg_lo:[0,1] neg_hi:[0,1]
	v_pk_mul_f32 v[52:53], v[44:45], v[44:45]
	v_pk_mul_f32 v[54:55], v[24:25], v[24:25]
	v_add_f32_e32 v52, v52, v53
	v_add_f32_e32 v52, v54, v52
	v_pk_mul_f32 v[56:57], v[48:49], v[48:49]
	v_add_f32_e32 v52, v55, v52
	v_add_f32_e32 v52, v56, v52
	v_pk_mul_f32 v[58:59], v[26:27], v[26:27]
	v_add_f32_e32 v52, v57, v52
	v_add_f32_e32 v52, v58, v52
	v_pk_mul_f32 v[60:61], v[28:29], v[28:29]
	v_add_f32_e32 v52, v59, v52
	v_add_f32_e32 v52, v60, v52
	v_pk_mul_f32 v[62:63], v[16:17], v[16:17]
	v_add_f32_e32 v52, v61, v52
	v_add_f32_e32 v52, v62, v52
	v_pk_mul_f32 v[64:65], v[20:21], v[20:21]
	v_add_f32_e32 v52, v63, v52
	v_add_f32_e32 v52, v64, v52
	v_pk_mul_f32 v[66:67], v[18:19], v[18:19]
	v_add_f32_e32 v52, v65, v52
	v_add_f32_e32 v52, v66, v52
	v_pk_mul_f32 v[68:69], v[22:23], v[22:23]
	v_add_f32_e32 v52, v67, v52
	v_add_f32_e32 v52, v68, v52
	v_pk_mul_f32 v[70:71], v[8:9], v[8:9]
	v_add_f32_e32 v52, v69, v52
	v_add_f32_e32 v52, v70, v52
	v_pk_mul_f32 v[72:73], v[12:13], v[12:13]
	v_add_f32_e32 v52, v71, v52
	v_add_f32_e32 v52, v72, v52
	v_pk_mul_f32 v[74:75], v[10:11], v[10:11]
	v_add_f32_e32 v52, v73, v52
	v_add_f32_e32 v52, v74, v52
	v_pk_mul_f32 v[104:105], v[14:15], v[14:15]
	v_add_f32_e32 v52, v75, v52
	v_add_f32_e32 v52, v104, v52
	v_pk_mul_f32 v[106:107], v[50:51], v[50:51]
	v_add_f32_e32 v52, v105, v52
	v_add_f32_e32 v52, v106, v52
	v_pk_mul_f32 v[110:111], v[30:31], v[30:31]
	v_add_f32_e32 v52, v107, v52
	v_add_f32_e32 v52, v110, v52
	v_pk_mul_f32 v[108:109], v[46:47], v[46:47]
	v_add_f32_e32 v52, v111, v52
	v_add_f32_e32 v52, v108, v52
	v_add_f32_e32 v52, v109, v52
	ds_bpermute_b32 v53, v79, v52
	v_cvt_f32_f16_sdwa v73, v141 dst_sel:DWORD dst_unused:UNUSED_PAD src0_sel:WORD_1
	v_cvt_f32_f16_e32 v72, v141
	v_cvt_f32_f16_sdwa v61, v147 dst_sel:DWORD dst_unused:UNUSED_PAD src0_sel:WORD_1
	v_cvt_f32_f16_e32 v60, v147
	s_waitcnt lgkmcnt(0)
	v_add_f32_e32 v52, v52, v53
	ds_bpermute_b32 v53, v80, v52
	v_cvt_f32_f16_sdwa v63, v146 dst_sel:DWORD dst_unused:UNUSED_PAD src0_sel:WORD_1
	v_cvt_f32_f16_e32 v62, v146
	v_cvt_f32_f16_sdwa v65, v145 dst_sel:DWORD dst_unused:UNUSED_PAD src0_sel:WORD_1
	v_cvt_f32_f16_e32 v64, v145
	s_waitcnt lgkmcnt(0)
	v_add_f32_e32 v52, v52, v53
	ds_bpermute_b32 v53, v81, v52
	v_cvt_f32_f16_sdwa v67, v144 dst_sel:DWORD dst_unused:UNUSED_PAD src0_sel:WORD_1
	v_cvt_f32_f16_e32 v66, v144
	v_cvt_f32_f16_sdwa v69, v143 dst_sel:DWORD dst_unused:UNUSED_PAD src0_sel:WORD_1
	v_cvt_f32_f16_e32 v68, v143
	s_waitcnt lgkmcnt(0)
	v_add_f32_e32 v52, v52, v53
	ds_bpermute_b32 v53, v82, v52
	v_cvt_f32_f16_sdwa v71, v142 dst_sel:DWORD dst_unused:UNUSED_PAD src0_sel:WORD_1
	v_cvt_f32_f16_e32 v70, v142
	s_waitcnt lgkmcnt(0)
	v_add_f32_e32 v52, v52, v53
	ds_bpermute_b32 v53, v83, v52
	s_waitcnt lgkmcnt(0)
	v_add_f32_e32 v52, v52, v53
	ds_bpermute_b32 v53, v84, v52
	s_waitcnt lgkmcnt(0)
	v_add_f32_e32 v52, v52, v53
	v_fmamk_f32 v52, v52, 0x3a000000, v101
	v_mul_f32_e32 v53, 0x4f800000, v52
	v_cmp_gt_f32_e32 vcc, s7, v52
	s_nop 1
	v_cndmask_b32_e32 v52, v52, v53, vcc
	v_sqrt_f32_e32 v53, v52
	s_nop 0
	v_add_u32_e32 v54, -1, v53
	v_add_u32_e32 v55, 1, v53
	v_fma_f32 v56, -v54, v53, v52
	v_fma_f32 v57, -v55, v53, v52
	v_cmp_ge_f32_e64 s[0:1], 0, v56
	s_nop 1
	v_cndmask_b32_e64 v53, v53, v54, s[0:1]
	v_cmp_lt_f32_e64 s[0:1], 0, v57
	s_nop 1
	v_cndmask_b32_e64 v53, v53, v55, s[0:1]
	v_mul_f32_e32 v54, 0x37800000, v53
	v_cndmask_b32_e32 v53, v53, v54, vcc
	v_cmp_class_f32_e32 vcc, v52, v102
	s_nop 1
	v_cndmask_b32_e32 v54, v53, v52, vcc
	v_div_scale_f32 v55, s[0:1], v54, v54, 1.0
	v_rcp_f32_e32 v56, v55
	v_div_scale_f32 v57, vcc, 1.0, v54, 1.0
	v_lshl_add_u64 v[52:53], s[14:15], 0, v[36:37]
	v_fma_f32 v58, -v55, v56, 1.0
	v_fmac_f32_e32 v56, v58, v56
	v_mul_f32_e32 v58, v57, v56
	v_fma_f32 v59, -v55, v58, v57
	v_fmac_f32_e32 v58, v59, v56
	v_fma_f32 v55, -v55, v58, v57
	v_div_fmas_f32 v55, v55, v56, v58
	v_div_fixup_f32 v54, v55, v54, 1.0
	v_pk_mul_f32 v[44:45], v[44:45], v[54:55] op_sel_hi:[1,0]
	v_pk_mul_f32 v[24:25], v[24:25], v[54:55] op_sel_hi:[1,0]
	v_pk_fma_f32 v[0:1], v[172:173], v[44:45], v[204:205]
	v_pk_fma_f32 v[2:3], v[174:175], v[24:25], v[206:207]
	global_store_dwordx4 v[52:53], v[0:3], off
	s_nop 1
	s_nop 0
	v_pk_mul_f32 v[24:25], v[26:27], v[54:55] op_sel_hi:[1,0]
	v_pk_mul_f32 v[26:27], v[48:49], v[54:55] op_sel_hi:[1,0]
	v_pk_mul_f32 v[16:17], v[16:17], v[54:55] op_sel_hi:[1,0]
	v_pk_mul_f32 v[8:9], v[8:9], v[54:55] op_sel_hi:[1,0]
	s_or_b32 s0, s10, 3
	s_ashr_i32 s1, s0, 31
	s_lshl_b64 s[10:11], s[0:1], 11
	v_cvt_f32_f16_sdwa v49, v148 dst_sel:DWORD dst_unused:UNUSED_PAD src0_sel:WORD_1
	v_cvt_f32_f16_e32 v48, v148
	v_cvt_f32_f16_sdwa v57, v157 dst_sel:DWORD dst_unused:UNUSED_PAD src0_sel:WORD_1
	v_cvt_f32_f16_e32 v56, v157
	v_cvt_f32_f16_sdwa v59, v156 dst_sel:DWORD dst_unused:UNUSED_PAD src0_sel:WORD_1
	v_cvt_f32_f16_e32 v58, v156
	s_lshl_b64 s[0:1], s[0:1], 13
	v_pk_fma_f32 v[0:1], v[176:177], v[26:27], v[208:209]
	v_pk_fma_f32 v[2:3], v[178:179], v[24:25], v[210:211]
	global_store_dwordx4 v[52:53], v[0:3], off offset:16
	s_nop 1
	s_nop 0
	v_pk_mul_f32 v[24:25], v[28:29], v[54:55] op_sel_hi:[1,0]
	v_pk_fma_f32 v[2:3], v[182:183], v[16:17], v[214:215]
	v_pk_fma_f32 v[0:1], v[180:181], v[24:25], v[212:213]
	global_store_dwordx4 v[52:53], v[0:3], off offset:32
	s_nop 1
	s_nop 0
	v_pk_mul_f32 v[16:17], v[18:19], v[54:55] op_sel_hi:[1,0]
	v_pk_mul_f32 v[18:19], v[20:21], v[54:55] op_sel_hi:[1,0]
	v_pk_fma_f32 v[2:3], v[186:187], v[16:17], v[218:219]
	v_pk_fma_f32 v[0:1], v[184:185], v[18:19], v[216:217]
	global_store_dwordx4 v[52:53], v[0:3], off offset:48
	s_nop 1
	s_nop 0
	v_add_co_u32_e32 v16, vcc, s12, v52
	v_pk_mul_f32 v[18:19], v[22:23], v[54:55] op_sel_hi:[1,0]
	s_nop 0
	v_addc_co_u32_e32 v17, vcc, 0, v53, vcc
	v_cvt_f32_f16_sdwa v53, v159 dst_sel:DWORD dst_unused:UNUSED_PAD src0_sel:WORD_1
	v_cvt_f32_f16_e32 v52, v159
	v_pk_fma_f32 v[0:1], v[188:189], v[18:19], v[220:221]
	v_pk_fma_f32 v[2:3], v[190:191], v[8:9], v[222:223]
	global_store_dwordx4 v[16:17], v[0:3], off
	s_nop 1
	s_nop 0
	v_pk_mul_f32 v[8:9], v[10:11], v[54:55] op_sel_hi:[1,0]
	v_pk_mul_f32 v[10:11], v[12:13], v[54:55] op_sel_hi:[1,0]
	v_pk_mul_f32 v[12:13], v[30:31], v[54:55] op_sel_hi:[1,0]
	v_pk_fma_f32 v[0:1], v[192:193], v[10:11], v[224:225]
	v_pk_fma_f32 v[2:3], v[194:195], v[8:9], v[226:227]
	global_store_dwordx4 v[16:17], v[0:3], off offset:16
	s_nop 1
	s_nop 0
	v_pk_mul_f32 v[8:9], v[50:51], v[54:55] op_sel_hi:[1,0]
	v_pk_mul_f32 v[10:11], v[14:15], v[54:55] op_sel_hi:[1,0]
	v_cvt_f32_f16_sdwa v51, v160 dst_sel:DWORD dst_unused:UNUSED_PAD src0_sel:WORD_1
	v_cvt_f32_f16_e32 v50, v160
	v_pk_fma_f32 v[0:1], v[196:197], v[10:11], v[228:229]
	v_pk_fma_f32 v[2:3], v[198:199], v[8:9], v[230:231]
	global_store_dwordx4 v[16:17], v[0:3], off offset:32
	s_nop 1
	s_nop 0
	v_lshl_add_u64 v[8:9], s[10:11], 0, v[42:43]
	v_pk_mul_f32 v[10:11], v[46:47], v[54:55] op_sel_hi:[1,0]
	v_lshlrev_b64 v[8:9], 1, v[8:9]
	v_lshl_add_u64 v[42:43], s[70:71], 0, v[8:9]
	v_lshl_add_u64 v[44:45], s[2:3], 0, v[8:9]
	v_cvt_f32_f16_sdwa v47, v161 dst_sel:DWORD dst_unused:UNUSED_PAD src0_sel:WORD_1
	v_cvt_f32_f16_e32 v46, v161
	v_cvt_f32_f16_sdwa v55, v158 dst_sel:DWORD dst_unused:UNUSED_PAD src0_sel:WORD_1
	v_cvt_f32_f16_e32 v54, v158
	s_add_u32 s10, s20, s0
	s_addc_u32 s11, s21, s1
	v_lshl_add_u64 v[36:37], s[10:11], 0, v[36:37]
	s_mov_b32 s10, 1
	v_pk_fma_f32 v[0:1], v[200:201], v[12:13], v[232:233]
	v_pk_fma_f32 v[2:3], v[202:203], v[10:11], v[234:235]
	global_store_dwordx4 v[16:17], v[0:3], off offset:48
	s_nop 1
	global_load_dwordx4 v[4:7], v[42:43], off offset:2064
	s_nop 0
	global_load_dwordx4 v[0:3], v[44:45], off offset:2064
	global_load_dwordx4 v[28:31], v[42:43], off
	global_load_dwordx4 v[24:27], v[44:45], off
	global_load_dwordx4 v[20:23], v[42:43], off offset:16
	global_load_dwordx4 v[16:19], v[44:45], off offset:16
	global_load_dwordx4 v[12:15], v[42:43], off offset:2048
	global_load_dwordx4 v[8:11], v[44:45], off offset:2048
	v_cvt_f32_f16_sdwa v43, v149 dst_sel:DWORD dst_unused:UNUSED_PAD src0_sel:WORD_1
	v_cvt_f32_f16_e32 v42, v149
	v_cvt_f32_f16_sdwa v45, v162 dst_sel:DWORD dst_unused:UNUSED_PAD src0_sel:WORD_1
	v_cvt_f32_f16_e32 v44, v162
	s_waitcnt vmcnt(6)
	v_and_b32_e32 v105, 0xffff0000, v2
	v_lshlrev_b32_e32 v104, 16, v2
	s_waitcnt vmcnt(5)
	v_lshlrev_b32_e32 v106, 16, v28
	v_and_b32_e32 v107, 0xffff0000, v28
	s_waitcnt vmcnt(4)
	v_lshlrev_b32_e32 v108, 16, v24
	v_and_b32_e32 v75, 0xffff0000, v6
	v_lshlrev_b32_e32 v74, 16, v6
	v_and_b32_e32 v109, 0xffff0000, v24
	v_and_b32_e32 v111, 0xffff0000, v7
	v_lshlrev_b32_e32 v110, 16, v7
	v_and_b32_e32 v7, 0xffff0000, v3
	v_lshlrev_b32_e32 v6, 16, v3
	v_lshlrev_b32_e32 v2, 16, v30
	v_and_b32_e32 v3, 0xffff0000, v30
	v_lshlrev_b32_e32 v112, 16, v26
	v_and_b32_e32 v113, 0xffff0000, v26
	v_lshlrev_b32_e32 v30, 16, v31
	v_and_b32_e32 v31, 0xffff0000, v31
	v_lshlrev_b32_e32 v26, 16, v27
	v_and_b32_e32 v27, 0xffff0000, v27
	v_lshlrev_b32_e32 v130, 16, v4
	v_and_b32_e32 v131, 0xffff0000, v4
	v_lshlrev_b32_e32 v132, 16, v0
	v_and_b32_e32 v133, 0xffff0000, v0
	v_lshlrev_b32_e32 v4, 16, v5
	v_and_b32_e32 v5, 0xffff0000, v5
	v_lshlrev_b32_e32 v0, 16, v1
	v_and_b32_e32 v1, 0xffff0000, v1
	v_pk_fma_f32 v[74:75], v[74:75], s[6:7], v[104:105] op_sel_hi:[1,0,1]
	v_pk_fma_f32 v[104:105], v[106:107], s[6:7], v[108:109] op_sel_hi:[1,0,1]
	v_lshlrev_b32_e32 v28, 16, v29
	v_and_b32_e32 v29, 0xffff0000, v29
	v_lshlrev_b32_e32 v24, 16, v25
	v_and_b32_e32 v25, 0xffff0000, v25
	v_pk_fma_f32 v[6:7], v[110:111], s[6:7], v[6:7] op_sel_hi:[1,0,1]
	v_pk_fma_f32 v[26:27], v[30:31], s[6:7], v[26:27] op_sel_hi:[1,0,1]
	v_pk_fma_f32 v[0:1], v[4:5], s[6:7], v[0:1] op_sel_hi:[1,0,1]
	v_pk_add_f32 v[30:31], v[74:75], v[42:43]
	v_pk_add_f32 v[42:43], v[104:105], v[44:45]
	v_pk_fma_f32 v[24:25], v[28:29], s[6:7], v[24:25] op_sel_hi:[1,0,1]
	v_pk_add_f32 v[44:45], v[6:7], v[48:49]
	v_pk_add_f32 v[48:49], v[0:1], v[72:73]
	v_add_f32_e32 v0, 0, v42
	v_pk_add_f32 v[24:25], v[24:25], v[46:47]
	v_add_f32_e32 v0, v43, v0
	v_pk_fma_f32 v[2:3], v[2:3], s[6:7], v[112:113] op_sel_hi:[1,0,1]
	v_add_f32_e32 v0, v24, v0
	v_pk_add_f32 v[46:47], v[2:3], v[50:51]
	v_add_f32_e32 v0, v25, v0
	v_add_f32_e32 v0, v46, v0
	s_waitcnt vmcnt(3)
	v_lshlrev_b32_e32 v114, 16, v20
	v_and_b32_e32 v115, 0xffff0000, v20
	s_waitcnt vmcnt(2)
	v_lshlrev_b32_e32 v116, 16, v16
	v_and_b32_e32 v117, 0xffff0000, v16
	v_pk_add_f32 v[26:27], v[26:27], v[52:53]
	v_add_f32_e32 v0, v47, v0
	v_pk_fma_f32 v[28:29], v[114:115], s[6:7], v[116:117] op_sel_hi:[1,0,1]
	v_add_f32_e32 v0, v26, v0
	v_lshlrev_b32_e32 v20, 16, v21
	v_and_b32_e32 v21, 0xffff0000, v21
	v_lshlrev_b32_e32 v16, 16, v17
	v_and_b32_e32 v17, 0xffff0000, v17
	v_pk_add_f32 v[28:29], v[28:29], v[54:55]
	v_add_f32_e32 v0, v27, v0
	v_pk_fma_f32 v[16:17], v[20:21], s[6:7], v[16:17] op_sel_hi:[1,0,1]
	v_add_f32_e32 v0, v28, v0
	v_lshlrev_b32_e32 v118, 16, v22
	v_and_b32_e32 v119, 0xffff0000, v22
	v_lshlrev_b32_e32 v120, 16, v18
	v_and_b32_e32 v121, 0xffff0000, v18
	v_pk_add_f32 v[16:17], v[16:17], v[56:57]
	v_add_f32_e32 v0, v29, v0
	v_pk_fma_f32 v[20:21], v[118:119], s[6:7], v[120:121] op_sel_hi:[1,0,1]
	v_add_f32_e32 v0, v16, v0
	v_lshlrev_b32_e32 v22, 16, v23
	v_and_b32_e32 v23, 0xffff0000, v23
	v_lshlrev_b32_e32 v18, 16, v19
	v_and_b32_e32 v19, 0xffff0000, v19
	v_pk_add_f32 v[20:21], v[20:21], v[58:59]
	v_add_f32_e32 v0, v17, v0
	v_pk_fma_f32 v[18:19], v[22:23], s[6:7], v[18:19] op_sel_hi:[1,0,1]
	v_add_f32_e32 v0, v20, v0
	s_waitcnt vmcnt(1)
	v_lshlrev_b32_e32 v122, 16, v12
	v_and_b32_e32 v123, 0xffff0000, v12
	s_waitcnt vmcnt(0)
	v_lshlrev_b32_e32 v124, 16, v8
	v_and_b32_e32 v125, 0xffff0000, v8
	v_pk_add_f32 v[18:19], v[18:19], v[60:61]
	v_add_f32_e32 v0, v21, v0
	v_pk_fma_f32 v[22:23], v[122:123], s[6:7], v[124:125] op_sel_hi:[1,0,1]
	v_add_f32_e32 v0, v18, v0
	v_lshlrev_b32_e32 v12, 16, v13
	v_and_b32_e32 v13, 0xffff0000, v13
	v_lshlrev_b32_e32 v8, 16, v9
	v_and_b32_e32 v9, 0xffff0000, v9
	v_pk_add_f32 v[22:23], v[22:23], v[62:63]
	v_add_f32_e32 v0, v19, v0
	v_pk_fma_f32 v[8:9], v[12:13], s[6:7], v[8:9] op_sel_hi:[1,0,1]
	v_add_f32_e32 v0, v22, v0
	v_lshlrev_b32_e32 v126, 16, v14
	v_and_b32_e32 v127, 0xffff0000, v14
	v_lshlrev_b32_e32 v128, 16, v10
	v_and_b32_e32 v129, 0xffff0000, v10
	v_pk_add_f32 v[8:9], v[8:9], v[64:65]
	v_add_f32_e32 v0, v23, v0
	v_pk_fma_f32 v[12:13], v[126:127], s[6:7], v[128:129] op_sel_hi:[1,0,1]
	v_add_f32_e32 v0, v8, v0
	v_lshlrev_b32_e32 v14, 16, v15
	v_and_b32_e32 v15, 0xffff0000, v15
	v_lshlrev_b32_e32 v10, 16, v11
	v_and_b32_e32 v11, 0xffff0000, v11
	v_pk_add_f32 v[12:13], v[12:13], v[66:67]
	v_add_f32_e32 v0, v9, v0
	v_pk_fma_f32 v[10:11], v[14:15], s[6:7], v[10:11] op_sel_hi:[1,0,1]
	v_add_f32_e32 v0, v12, v0
	v_pk_add_f32 v[10:11], v[10:11], v[68:69]
	v_add_f32_e32 v0, v13, v0
	v_pk_fma_f32 v[14:15], v[130:131], s[6:7], v[132:133] op_sel_hi:[1,0,1]
	v_add_f32_e32 v0, v10, v0
	v_pk_add_f32 v[14:15], v[14:15], v[70:71]
	v_add_f32_e32 v0, v11, v0
	v_add_f32_e32 v0, v14, v0
	v_add_f32_e32 v0, v15, v0
	v_add_f32_e32 v0, v48, v0
	v_add_f32_e32 v0, v49, v0
	v_add_f32_e32 v0, v30, v0
	v_add_f32_e32 v0, v31, v0
	v_add_f32_e32 v0, v44, v0
	v_add_f32_e32 v0, v45, v0
	ds_bpermute_b32 v1, v79, v0
	s_waitcnt lgkmcnt(0)
	v_add_f32_e32 v0, v0, v1
	ds_bpermute_b32 v1, v80, v0
	s_waitcnt lgkmcnt(0)
	v_add_f32_e32 v0, v0, v1
	ds_bpermute_b32 v1, v81, v0
	s_waitcnt lgkmcnt(0)
	v_add_f32_e32 v0, v0, v1
	ds_bpermute_b32 v1, v82, v0
	s_waitcnt lgkmcnt(0)
	v_add_f32_e32 v0, v0, v1
	ds_bpermute_b32 v1, v83, v0
	s_waitcnt lgkmcnt(0)
	v_add_f32_e32 v50, v0, v1
	ds_bpermute_b32 v51, v84, v50
	s_waitcnt lgkmcnt(0)
	v_add_f32_e32 v50, v50, v51
	v_mul_f32_e32 v50, 0x3a000000, v50
	v_pk_add_f32 v[42:43], v[42:43], v[50:51] op_sel_hi:[1,0] neg_lo:[0,1] neg_hi:[0,1]
	v_pk_add_f32 v[24:25], v[24:25], v[50:51] op_sel_hi:[1,0] neg_lo:[0,1] neg_hi:[0,1]
	v_pk_add_f32 v[46:47], v[46:47], v[50:51] op_sel_hi:[1,0] neg_lo:[0,1] neg_hi:[0,1]
	v_pk_add_f32 v[26:27], v[26:27], v[50:51] op_sel_hi:[1,0] neg_lo:[0,1] neg_hi:[0,1]
	v_pk_add_f32 v[28:29], v[28:29], v[50:51] op_sel_hi:[1,0] neg_lo:[0,1] neg_hi:[0,1]
	v_pk_add_f32 v[16:17], v[16:17], v[50:51] op_sel_hi:[1,0] neg_lo:[0,1] neg_hi:[0,1]
	v_pk_add_f32 v[20:21], v[20:21], v[50:51] op_sel_hi:[1,0] neg_lo:[0,1] neg_hi:[0,1]
	v_pk_add_f32 v[18:19], v[18:19], v[50:51] op_sel_hi:[1,0] neg_lo:[0,1] neg_hi:[0,1]
	v_pk_add_f32 v[22:23], v[22:23], v[50:51] op_sel_hi:[1,0] neg_lo:[0,1] neg_hi:[0,1]
	v_pk_add_f32 v[8:9], v[8:9], v[50:51] op_sel_hi:[1,0] neg_lo:[0,1] neg_hi:[0,1]
	v_pk_add_f32 v[12:13], v[12:13], v[50:51] op_sel_hi:[1,0] neg_lo:[0,1] neg_hi:[0,1]
	v_pk_add_f32 v[10:11], v[10:11], v[50:51] op_sel_hi:[1,0] neg_lo:[0,1] neg_hi:[0,1]
	v_pk_add_f32 v[14:15], v[14:15], v[50:51] op_sel_hi:[1,0] neg_lo:[0,1] neg_hi:[0,1]
	v_pk_add_f32 v[48:49], v[48:49], v[50:51] op_sel_hi:[1,0] neg_lo:[0,1] neg_hi:[0,1]
	v_pk_add_f32 v[44:45], v[44:45], v[50:51] op_sel_hi:[1,0] neg_lo:[0,1] neg_hi:[0,1]
	v_pk_add_f32 v[30:31], v[30:31], v[50:51] op_sel_hi:[1,0] neg_lo:[0,1] neg_hi:[0,1]
	v_pk_mul_f32 v[50:51], v[42:43], v[42:43]
	v_pk_mul_f32 v[52:53], v[24:25], v[24:25]
	v_add_f32_e32 v50, v50, v51
	v_add_f32_e32 v50, v52, v50
	v_pk_mul_f32 v[54:55], v[46:47], v[46:47]
	v_add_f32_e32 v50, v53, v50
	v_add_f32_e32 v50, v54, v50
	v_pk_mul_f32 v[56:57], v[26:27], v[26:27]
	v_add_f32_e32 v50, v55, v50
	v_add_f32_e32 v50, v56, v50
	v_pk_mul_f32 v[58:59], v[28:29], v[28:29]
	v_add_f32_e32 v50, v57, v50
	v_add_f32_e32 v50, v58, v50
	v_pk_mul_f32 v[60:61], v[16:17], v[16:17]
	v_add_f32_e32 v50, v59, v50
	v_add_f32_e32 v50, v60, v50
	v_pk_mul_f32 v[62:63], v[20:21], v[20:21]
	v_add_f32_e32 v50, v61, v50
	v_add_f32_e32 v50, v62, v50
	v_pk_mul_f32 v[64:65], v[18:19], v[18:19]
	v_add_f32_e32 v50, v63, v50
	v_add_f32_e32 v50, v64, v50
	v_pk_mul_f32 v[66:67], v[22:23], v[22:23]
	v_add_f32_e32 v50, v65, v50
	v_add_f32_e32 v50, v66, v50
	v_pk_mul_f32 v[68:69], v[8:9], v[8:9]
	v_add_f32_e32 v50, v67, v50
	v_add_f32_e32 v50, v68, v50
	v_pk_mul_f32 v[70:71], v[12:13], v[12:13]
	v_add_f32_e32 v50, v69, v50
	v_add_f32_e32 v50, v70, v50
	v_pk_mul_f32 v[72:73], v[10:11], v[10:11]
	v_add_f32_e32 v50, v71, v50
	v_add_f32_e32 v50, v72, v50
	v_pk_mul_f32 v[74:75], v[14:15], v[14:15]
	v_add_f32_e32 v50, v73, v50
	v_add_f32_e32 v50, v74, v50
	v_pk_mul_f32 v[104:105], v[48:49], v[48:49]
	v_add_f32_e32 v50, v75, v50
	v_add_f32_e32 v50, v104, v50
	v_pk_mul_f32 v[108:109], v[30:31], v[30:31]
	v_add_f32_e32 v50, v105, v50
	v_add_f32_e32 v50, v108, v50
	v_pk_mul_f32 v[106:107], v[44:45], v[44:45]
	v_add_f32_e32 v50, v109, v50
	v_add_f32_e32 v50, v106, v50
	v_add_f32_e32 v50, v107, v50
	ds_bpermute_b32 v51, v79, v50
	s_waitcnt lgkmcnt(0)
	v_add_f32_e32 v50, v50, v51
	ds_bpermute_b32 v51, v80, v50
	s_waitcnt lgkmcnt(0)
	v_add_f32_e32 v50, v50, v51
	ds_bpermute_b32 v51, v81, v50
	s_waitcnt lgkmcnt(0)
	v_add_f32_e32 v50, v50, v51
	ds_bpermute_b32 v51, v82, v50
	s_waitcnt lgkmcnt(0)
	v_add_f32_e32 v50, v50, v51
	ds_bpermute_b32 v51, v83, v50
	s_waitcnt lgkmcnt(0)
	v_add_f32_e32 v50, v50, v51
	ds_bpermute_b32 v51, v84, v50
	s_waitcnt lgkmcnt(0)
	v_add_f32_e32 v50, v50, v51
	v_fmamk_f32 v50, v50, 0x3a000000, v101
	v_mul_f32_e32 v51, 0x4f800000, v50
	v_cmp_gt_f32_e32 vcc, s7, v50
	s_nop 1
	v_cndmask_b32_e32 v50, v50, v51, vcc
	v_sqrt_f32_e32 v51, v50
	s_nop 0
	v_add_u32_e32 v52, -1, v51
	v_add_u32_e32 v53, 1, v51
	v_fma_f32 v54, -v52, v51, v50
	v_fma_f32 v55, -v53, v51, v50
	v_cmp_ge_f32_e64 s[0:1], 0, v54
	s_nop 1
	v_cndmask_b32_e64 v51, v51, v52, s[0:1]
	v_cmp_lt_f32_e64 s[0:1], 0, v55
	s_nop 1
	v_cndmask_b32_e64 v51, v51, v53, s[0:1]
	v_mul_f32_e32 v52, 0x37800000, v51
	v_cndmask_b32_e32 v51, v51, v52, vcc
	v_cmp_class_f32_e32 vcc, v50, v102
	s_nop 1
	v_cndmask_b32_e32 v50, v51, v50, vcc
	v_div_scale_f32 v51, s[0:1], v50, v50, 1.0
	v_rcp_f32_e32 v52, v51
	v_div_scale_f32 v53, vcc, 1.0, v50, 1.0
	s_mov_b64 s[0:1], 0
	v_fma_f32 v54, -v51, v52, 1.0
	v_fmac_f32_e32 v52, v54, v52
	v_mul_f32_e32 v54, v53, v52
	v_fma_f32 v55, -v51, v54, v53
	v_fmac_f32_e32 v54, v55, v52
	v_fma_f32 v51, -v51, v54, v53
	v_div_fmas_f32 v51, v51, v52, v54
	v_div_fixup_f32 v50, v51, v50, 1.0
	v_pk_mul_f32 v[42:43], v[42:43], v[50:51] op_sel_hi:[1,0]
	v_pk_mul_f32 v[24:25], v[24:25], v[50:51] op_sel_hi:[1,0]
	v_pk_fma_f32 v[0:1], v[172:173], v[42:43], v[204:205]
	v_pk_fma_f32 v[2:3], v[174:175], v[24:25], v[206:207]
	global_store_dwordx4 v[36:37], v[0:3], off
	s_nop 1
	s_nop 0
	v_pk_mul_f32 v[24:25], v[26:27], v[50:51] op_sel_hi:[1,0]
	v_pk_mul_f32 v[26:27], v[46:47], v[50:51] op_sel_hi:[1,0]
	v_pk_mul_f32 v[16:17], v[16:17], v[50:51] op_sel_hi:[1,0]
	v_pk_mul_f32 v[8:9], v[8:9], v[50:51] op_sel_hi:[1,0]
	v_pk_fma_f32 v[0:1], v[176:177], v[26:27], v[208:209]
	v_pk_fma_f32 v[2:3], v[178:179], v[24:25], v[210:211]
	global_store_dwordx4 v[36:37], v[0:3], off offset:16
	s_nop 1
	s_nop 0
	v_pk_mul_f32 v[24:25], v[28:29], v[50:51] op_sel_hi:[1,0]
	v_pk_fma_f32 v[2:3], v[182:183], v[16:17], v[214:215]
	v_pk_fma_f32 v[0:1], v[180:181], v[24:25], v[212:213]
	global_store_dwordx4 v[36:37], v[0:3], off offset:32
	s_nop 1
	s_nop 0
	v_pk_mul_f32 v[16:17], v[18:19], v[50:51] op_sel_hi:[1,0]
	v_pk_mul_f32 v[18:19], v[20:21], v[50:51] op_sel_hi:[1,0]
	v_pk_fma_f32 v[2:3], v[186:187], v[16:17], v[218:219]
	v_pk_fma_f32 v[0:1], v[184:185], v[18:19], v[216:217]
	global_store_dwordx4 v[36:37], v[0:3], off offset:48
	s_nop 1
	s_nop 0
	v_add_co_u32_e32 v16, vcc, s12, v36
	v_pk_mul_f32 v[18:19], v[22:23], v[50:51] op_sel_hi:[1,0]
	s_nop 0
	v_addc_co_u32_e32 v17, vcc, 0, v37, vcc
	s_and_b64 vcc, exec, s[8:9]
	v_pk_fma_f32 v[0:1], v[188:189], v[18:19], v[220:221]
	v_pk_fma_f32 v[2:3], v[190:191], v[8:9], v[222:223]
	global_store_dwordx4 v[16:17], v[0:3], off
	s_nop 1
	s_nop 0
	v_pk_mul_f32 v[8:9], v[10:11], v[50:51] op_sel_hi:[1,0]
	v_pk_mul_f32 v[10:11], v[12:13], v[50:51] op_sel_hi:[1,0]
	v_pk_fma_f32 v[2:3], v[194:195], v[8:9], v[226:227]
	v_pk_fma_f32 v[0:1], v[192:193], v[10:11], v[224:225]
	global_store_dwordx4 v[16:17], v[0:3], off offset:16
	s_nop 1
	s_nop 0
	v_pk_mul_f32 v[8:9], v[48:49], v[50:51] op_sel_hi:[1,0]
	v_pk_mul_f32 v[10:11], v[14:15], v[50:51] op_sel_hi:[1,0]
	v_pk_fma_f32 v[2:3], v[198:199], v[8:9], v[230:231]
	v_pk_fma_f32 v[0:1], v[196:197], v[10:11], v[228:229]
	global_store_dwordx4 v[16:17], v[0:3], off offset:32
	s_nop 1
	s_nop 0
	v_pk_mul_f32 v[8:9], v[44:45], v[50:51] op_sel_hi:[1,0]
	v_pk_mul_f32 v[10:11], v[30:31], v[50:51] op_sel_hi:[1,0]
	v_pk_fma_f32 v[2:3], v[202:203], v[8:9], v[234:235]
	v_pk_fma_f32 v[0:1], v[200:201], v[10:11], v[232:233]
	global_store_dwordx4 v[16:17], v[0:3], off offset:48
	s_nop 1
	s_waitcnt vmcnt(0)
	s_cbranch_vccz .LBB0_1012
